# GEMM phases: LDS-DMA loads use scalar-base + 32-bit lane offset form, dropping 34 64-bit VALU address adds (fewer VALU per MFMA)
# speedup vs baseline: 1.0075x; 1.0017x over previous
; #define PG8_STAGE(bufoff, gbase, voff) do { _Pragma("unroll") for (int _i = 0; _i < 2; ++_i) \
;         __builtin_amdgcn_global_load_lds((const unsigned*)((const char*)(gbase) + (voff)[_i]), (PG8_LAS unsigned*)(lds + (bufoff) + ldsw + _i * 8192), 16, 0, 0); } while (0)
; #define PG8_WAIT_V(n) asm volatile("s_waitcnt vmcnt(" #n ")" ::: "memory")
; #define PG8_BAR __builtin_amdgcn_s_barrier()
; template <class Epi, class Sched, bool ALIGN_EPI = false, bool SP2 = false>
; __device__ __forceinline__ void gemm_phase(PG8_LAS unsigned char* lds, const Gemm g, const Sched& S, const Epi& E) {
;     ...
;     for (int i = 0; i < 2; ++i) { int R, C; stage_rc(tid * 16 + i * 8192, R, C); const int Rb = Epi::PERM ? ((R & ~31) + perm32(R & 31)) : R;
;         voffA[i] = (unsigned)(R * K + C) * 2u; voffB[i] = (unsigned)(Rb * K + C) * 2u; }
;     const size_t kstep = (size_t)(BK * 2);
;     const size_t hstep = (size_t)HALF * K * 2;
;     const size_t tstep = 2 * hstep;
;     const unsigned ldsw = (unsigned)wid * 1024u;
;     const int aoff = lds_byte(wr * 64 + fr, fq * 8), boff = lds_byte(wc * 32 + fr, fq * 8);
;     ...
;     Unit cur, nxt; int ui = 0;
;     if (!S.next(0, cur)) return;
;     f32x4 acc[2][2][4][2];
; #pragma unroll
;     for (int a = 0; a < 2; ++a)
; #pragma unroll
;         for (int b = 0; b < 2; ++b)
; #pragma unroll
;             for (int m = 0; m < 4; ++m)
; #pragma unroll
;                 for (int n = 0; n < 2; ++n) acc[a][b][m][n] = (f32x4){0.f, 0.f, 0.f, 0.f};
;     bf16x8 At[4][2], B0[2][2], B1[2][2];
;     const char* cA = (const char*)g.A + (size_t)cur.pm * tstep; const char* cB = (const char*)g.Bt + (size_t)cur.pn * tstep;
;     S.a_ready(cur);
;     if constexpr (SP2) {
;         PG8_STAGE(PG8_SB(0, 0), cB, voffB); PG8_STAGE(PG8_SB(0, 1), cB + hstep, voffB); PG8_STAGE(PG8_SA(0, 0), cA, voffA); PG8_STAGE(PG8_SA(0, 1), cA + hstep, voffA);
;         if (wr == 1) PG8_BAR;
;         PG8_WAIT_V(2); PG8_BAR;
;         PG8_STAGE(PG8_SB(1, 0), cB + kstep, voffB); PG8_STAGE(PG8_SA(1, 0), cA + kstep, voffA); PG8_STAGE(PG8_SB(1, 1), cB + hstep + kstep, voffB);
;         PG8_WAIT_V(6); PG8_BAR;
.LBB0_304:
	v_lshrrev_b32_e32 v20, 1, v18
	v_and_b32_e32 v20, 24, v20
	s_add_u32 s16, s16, 0x8800000
	v_and_b32_e32 v19, 15, v18
	v_lshlrev_b32_e32 v21, 1, v20
	v_lshlrev_b32_e32 v18, 2, v18
	s_sext_i32_i16 s51, s18
	s_addc_u32 s17, s17, 0
	v_lshl_or_b32 v1, s24, 6, v19
	v_lshl_or_b32 v19, v19, 6, v21
	s_lshl_b32 s18, s24, 13
	v_and_b32_e32 v18, 32, v18
	v_bitop3_b32 v21, v19, s18, v18 bitop3:0xde
	s_lshl_b32 s18, s23, 5
	s_and_b32 s26, s18, 0x60
	s_lshl_b32 s18, s26, 7
	s_add_i32 m0, s12, 0x18000
	v_lshl_add_u64 v[10:11], v[10:11], 0, s[28:29]
	v_bitop3_b32 v146, v19, s18, v18 bitop3:0xde
	s_waitcnt vmcnt(2)
	s_barrier
	global_load_lds_dwordx4 v[10:11], off
	v_lshl_add_u64 v[8:9], v[8:9], 0, s[28:29]
	s_add_i32 m0, s12, 0x1a000
	s_add_i32 s18, s12, 0x8000
	s_add_i32 s48, s12, 0xa000
	global_load_lds_dwordx4 v[8:9], off
	v_lshl_add_u64 v[4:5], v[4:5], 0, s[28:29]
	s_mov_b32 m0, s18
	s_add_u32 s24, s20, 0x80080
	global_load_lds_dwordx4 v[4:5], off
	v_lshl_add_u64 v[4:5], v[6:7], 0, s[28:29]
	s_mov_b32 m0, s48
	s_addc_u32 s25, s21, 0
	global_load_lds_dwordx4 v[4:5], off
	s_add_i32 m0, s12, 0x1c000
	s_nop 0
	global_load_lds_dwordx4 v2, s[24:25]
	v_lshl_add_u64 v[4:5], s[24:25], 0, v[132:133]
	s_add_i32 m0, s12, 0x1e000
	s_cmpk_lt_u32 s22, 0x100
	global_load_lds_dwordx4 v[4:5], off
	v_lshlrev_b32_e32 v4, 15, v12
	v_and_b32_e32 v4, 0xffff0000, v4
	v_lshl_add_u32 v4, v13, 12, v4
	v_and_b32_e32 v5, 1, v12
	v_lshl_or_b32 v4, v5, 6, v4
	v_lshl_add_u32 v138, v14, 1, v4
	v_lshlrev_b32_e32 v4, 15, v16
	v_and_b32_e32 v4, 0xffff0000, v4
	s_waitcnt vmcnt(6)
	v_lshl_add_u32 v4, v15, 12, v4
	v_and_b32_e32 v5, 1, v16
	v_lshl_or_b32 v4, v5, 6, v4
	s_cselect_b64 s[22:23], -1, 0
	s_ashr_i32 s49, s4, 31
	v_or_b32_e32 v147, s26, v20
	v_mov_b32_e32 v139, v3
	v_lshl_add_u32 v140, v17, 1, v4
	v_mov_b32_e32 v141, v3
	s_mov_b32 s50, 0
	v_add_u32_e32 v148, 0, v21
	s_barrier
	s_branch .LBB0_307

; #define PG8_STAGE(bufoff, gbase, voff) do { _Pragma("unroll") for (int _i = 0; _i < 2; ++_i) \
;         __builtin_amdgcn_global_load_lds((const unsigned*)((const char*)(gbase) + (voff)[_i]), (PG8_LAS unsigned*)(lds + (bufoff) + ldsw + _i * 8192), 16, 0, 0); } while (0)
; #define PG8_LDA(dst, b, h) do { _Pragma("unroll") for (int m = 0; m < 4; ++m) _Pragma("unroll") for (int k = 0; k < 2; ++k) dst[m][k] = *(const PG8_LAS bf16x8*)(lds + PG8_SA(b, h) + aoff + m * 2048 + k * 1024); } while (0)
; #define PG8_LDB(dst, b, h) do { _Pragma("unroll") for (int n = 0; n < 2; ++n) _Pragma("unroll") for (int k = 0; k < 2; ++k) dst[n][k] = *(const PG8_LAS bf16x8*)(lds + PG8_SB(b, h) + boff + n * 2048 + k * 1024); } while (0)
; #define PG8_WAIT_V(n) asm volatile("s_waitcnt vmcnt(" #n ")" ::: "memory")
; #define PG8_WAIT_L(n) asm volatile("s_waitcnt lgkmcnt(" #n ")" ::: "memory")
; #define PG8_BAR __builtin_amdgcn_s_barrier()
; #define PG8_SCHED __builtin_amdgcn_sched_barrier(0)
; template <class Epi, class Sched, bool ALIGN_EPI = false, bool SP2 = false>
; __device__ __forceinline__ void gemm_phase(PG8_LAS unsigned char* lds, const Gemm g, const Sched& S, const Epi& E) {
;     ...
;         const char* nA = has_next ? (const char*)g.A + (size_t)nxt.pm * tstep : cA; const char* nB = has_next ? (const char*)g.Bt + (size_t)nxt.pn * tstep : cB;
;         for (int t = 0; t < nt; t += 2) {
;             const bool last = (t == nt - 2);
;             const char* a1 = cA + (size_t)(t + 1) * kstep;
;             const char* a2 = last ? nA : cA + (size_t)(t + 2) * kstep; const char* b2 = last ? nB : cB + (size_t)(t + 2) * kstep;
;             const char* a3 = a2 + kstep; const char* b3 = b2 + kstep;
;             if (last && has_next) S.a_ready(nxt);
;             if constexpr (SP2) {
;             PG8_LDB(B0, 0, 0); PG8_LDB(B1, 0, 1); PG8_SCHED; PG8_LDA(At, 0, 0); PG8_STAGE(PG8_SA(1, 1), a1 + hstep, voffA);
;             PG8_WAIT_V(8); PG8_WAIT_L(0); PG8_BAR; PG8_MMA(0, 0, At, B0); PG8_MMA(0, 1, At, B1); PG8_BAR; PG8_SCHED;
;             PG8_LDA(At, 0, 1); PG8_STAGE(PG8_SB(0, 0), b2, voffB); PG8_STAGE(PG8_SB(0, 1), b2 + hstep, voffB); PG8_STAGE(PG8_SA(0, 0), a2, voffA);
;             PG8_WAIT_V(8); PG8_WAIT_L(0); PG8_BAR; PG8_MMA(1, 0, At, B0); PG8_MMA(1, 1, At, B1); PG8_BAR; PG8_SCHED;
.LBB0_310:
	s_add_u32 s20, s44, 0xfff80080
	s_addc_u32 s21, s45, -1
	s_add_i32 s30, 0, 0x10000
	s_cmp_eq_u32 s56, 28
	s_cselect_b32 s47, s27, s21
	s_cselect_b32 s46, s52, s20
	v_add_u32_e32 v149, s30, v146
	s_cselect_b32 s21, s25, s55
	s_cselect_b32 s20, s53, s54
	s_add_i32 s57, 0, 0x14000
	ds_read_b128 v[142:145], v149
	ds_read_b128 v[150:153], v149 offset:1024
	ds_read_b128 v[154:157], v149 offset:2048
	ds_read_b128 v[158:161], v149 offset:3072
	v_add_u32_e32 v149, s57, v146
	ds_read_b128 v[162:165], v149
	ds_read_b128 v[166:169], v149 offset:1024
	ds_read_b128 v[170:173], v149 offset:2048
	ds_read_b128 v[174:177], v149 offset:3072
	s_add_i32 m0, s12, 0xc000
	ds_read_b128 v[178:181], v148
	ds_read_b128 v[182:185], v148 offset:1024
	ds_read_b128 v[186:189], v148 offset:2048
	ds_read_b128 v[190:193], v148 offset:3072
	ds_read_b128 v[194:197], v148 offset:4096
	ds_read_b128 v[198:201], v148 offset:5120
	ds_read_b128 v[202:205], v148 offset:6144
	ds_read_b128 v[206:209], v148 offset:7168
	global_load_lds_dwordx4 v140, s[44:45]
	s_add_i32 m0, s12, 0xe000
	s_nop 0
	global_load_lds_dwordx4 v138, s[44:45]
	s_waitcnt vmcnt(8)
	s_waitcnt lgkmcnt(0)
	s_barrier
	s_setprio 1
	s_waitcnt lgkmcnt(0)
	v_mfma_f32_16x16x32_bf16 v[128:131], v[142:145], v[178:181], v[128:131]
	v_mfma_f32_16x16x32_bf16 v[124:127], v[154:157], v[178:181], v[124:127]
	v_mfma_f32_16x16x32_bf16 v[120:123], v[142:145], v[186:189], v[120:123]
	v_mfma_f32_16x16x32_bf16 v[112:115], v[154:157], v[186:189], v[112:115]
	v_mfma_f32_16x16x32_bf16 v[104:107], v[142:145], v[194:197], v[104:107]
	v_mfma_f32_16x16x32_bf16 v[96:99], v[154:157], v[194:197], v[96:99]
	v_mfma_f32_16x16x32_bf16 v[88:91], v[142:145], v[202:205], v[88:91]
	v_mfma_f32_16x16x32_bf16 v[80:83], v[154:157], v[202:205], v[80:83]
	v_mfma_f32_16x16x32_bf16 v[128:131], v[150:153], v[182:185], v[128:131]
	v_mfma_f32_16x16x32_bf16 v[124:127], v[158:161], v[182:185], v[124:127]
	v_mfma_f32_16x16x32_bf16 v[120:123], v[150:153], v[190:193], v[120:123]
	v_mfma_f32_16x16x32_bf16 v[112:115], v[158:161], v[190:193], v[112:115]
	v_mfma_f32_16x16x32_bf16 v[104:107], v[150:153], v[198:201], v[104:107]
	v_mfma_f32_16x16x32_bf16 v[96:99], v[158:161], v[198:201], v[96:99]
	v_mfma_f32_16x16x32_bf16 v[88:91], v[150:153], v[206:209], v[88:91]
	v_mfma_f32_16x16x32_bf16 v[80:83], v[158:161], v[206:209], v[80:83]
	s_setprio 0
	s_setprio 1
	v_mfma_f32_16x16x32_bf16 v[116:119], v[162:165], v[178:181], v[116:119]
	v_mfma_f32_16x16x32_bf16 v[108:111], v[170:173], v[178:181], v[108:111]
	v_mfma_f32_16x16x32_bf16 v[100:103], v[162:165], v[186:189], v[100:103]
	v_mfma_f32_16x16x32_bf16 v[92:95], v[170:173], v[186:189], v[92:95]
	v_mfma_f32_16x16x32_bf16 v[84:87], v[162:165], v[194:197], v[84:87]
	v_mfma_f32_16x16x32_bf16 v[76:79], v[170:173], v[194:197], v[76:79]
	v_mfma_f32_16x16x32_bf16 v[72:75], v[162:165], v[202:205], v[72:75]
	v_mfma_f32_16x16x32_bf16 v[68:71], v[170:173], v[202:205], v[68:71]
	v_mfma_f32_16x16x32_bf16 v[116:119], v[166:169], v[182:185], v[116:119]
	v_mfma_f32_16x16x32_bf16 v[108:111], v[174:177], v[182:185], v[108:111]
	v_mfma_f32_16x16x32_bf16 v[100:103], v[166:169], v[190:193], v[100:103]
	v_mfma_f32_16x16x32_bf16 v[92:95], v[174:177], v[190:193], v[92:95]
	v_mfma_f32_16x16x32_bf16 v[84:87], v[166:169], v[198:201], v[84:87]
	v_mfma_f32_16x16x32_bf16 v[76:79], v[174:177], v[198:201], v[76:79]
	v_mfma_f32_16x16x32_bf16 v[72:75], v[166:169], v[206:209], v[72:75]
	v_mfma_f32_16x16x32_bf16 v[68:71], v[174:177], v[206:209], v[68:71]
	s_setprio 0
	s_barrier
	s_add_i32 s30, s30, s10
	v_lshl_add_u64 v[210:211], s[20:21], 0, v[2:3]
	s_mov_b32 m0, s30
	ds_read_b128 v[178:181], v148 offset:16384
	ds_read_b128 v[182:185], v148 offset:17408
	ds_read_b128 v[186:189], v148 offset:18432
	ds_read_b128 v[190:193], v148 offset:19456
	ds_read_b128 v[194:197], v148 offset:20480
	ds_read_b128 v[198:201], v148 offset:21504
	ds_read_b128 v[202:205], v148 offset:22528
	ds_read_b128 v[206:209], v148 offset:23552
	global_load_lds_dwordx4 v[210:211], off
	s_add_i32 m0, s30, 0x2000
	s_add_u32 s30, s20, 0x80000
	v_lshl_add_u64 v[212:213], s[20:21], 0, v[132:133]
	s_addc_u32 s31, s21, 0
	s_add_i32 s57, s57, s10
	global_load_lds_dwordx4 v[212:213], off
	s_mov_b32 m0, s57
	v_lshl_add_u64 v[216:217], s[46:47], 0, v[134:135]
	global_load_lds_dwordx4 v2, s[30:31]
	s_add_i32 m0, s57, 0x2000
	s_nop 0
	global_load_lds_dwordx4 v132, s[30:31]
	v_lshl_add_u64 v[214:215], s[46:47], 0, v[136:137]
	s_mov_b32 m0, s12
	s_nop 0
	global_load_lds_dwordx4 v[214:215], off
	s_mov_b32 m0, s13
	s_nop 0
	global_load_lds_dwordx4 v[216:217], off
	s_waitcnt vmcnt(8)
	s_waitcnt lgkmcnt(0)
	s_barrier
; #define PG8_STAGE(bufoff, gbase, voff) do { _Pragma("unroll") for (int _i = 0; _i < 2; ++_i) \
;         __builtin_amdgcn_global_load_lds((const unsigned*)((const char*)(gbase) + (voff)[_i]), (PG8_LAS unsigned*)(lds + (bufoff) + ldsw + _i * 8192), 16, 0, 0); } while (0)
; #define PG8_LDA(dst, b, h) do { _Pragma("unroll") for (int m = 0; m < 4; ++m) _Pragma("unroll") for (int k = 0; k < 2; ++k) dst[m][k] = *(const PG8_LAS bf16x8*)(lds + PG8_SA(b, h) + aoff + m * 2048 + k * 1024); } while (0)
; #define PG8_LDB(dst, b, h) do { _Pragma("unroll") for (int n = 0; n < 2; ++n) _Pragma("unroll") for (int k = 0; k < 2; ++k) dst[n][k] = *(const PG8_LAS bf16x8*)(lds + PG8_SB(b, h) + boff + n * 2048 + k * 1024); } while (0)
; #define PG8_MMA(ai, bj, At, Bt) do { __builtin_amdgcn_s_setprio(1); _Pragma("unroll") for (int m = 0; m < 4; ++m) _Pragma("unroll") for (int n = 0; n < 2; ++n) _Pragma("unroll") for (int k = 0; k < 2; ++k) \
;         acc[ai][bj][m][n] = __builtin_amdgcn_mfma_f32_16x16x32_bf16(Bt[n][k], At[m][k], acc[ai][bj][m][n], 0, 0, 0); __builtin_amdgcn_s_setprio(0); } while (0)
; #define PG8_WAIT_V(n) asm volatile("s_waitcnt vmcnt(" #n ")" ::: "memory")
; #define PG8_WAIT_L(n) asm volatile("s_waitcnt lgkmcnt(" #n ")" ::: "memory")
; #define PG8_BAR __builtin_amdgcn_s_barrier()
; #define PG8_SCHED __builtin_amdgcn_sched_barrier(0)
; template <class Epi, class Sched, bool ALIGN_EPI = false, bool SP2 = false>
; __device__ __forceinline__ void gemm_phase(PG8_LAS unsigned char* lds, const Gemm g, const Sched& S, const Epi& E) {
;     ...
;             PG8_WAIT_V(8); PG8_WAIT_L(0); PG8_BAR; PG8_MMA(1, 0, At, B0); PG8_MMA(1, 1, At, B1); PG8_BAR; PG8_SCHED;
;             PG8_LDB(B0, 1, 0); PG8_LDB(B1, 1, 1); PG8_SCHED; PG8_LDA(At, 1, 0); PG8_STAGE(PG8_SA(0, 1), a2 + hstep, voffA);
;             PG8_WAIT_V(8); PG8_WAIT_L(0); PG8_BAR; PG8_MMA(0, 0, At, B0); PG8_MMA(0, 1, At, B1); PG8_BAR; PG8_SCHED;
	s_setprio 1
	s_waitcnt lgkmcnt(0)
	v_mfma_f32_16x16x32_bf16 v[64:67], v[142:145], v[178:181], v[64:67]
	v_mfma_f32_16x16x32_bf16 v[60:63], v[154:157], v[178:181], v[60:63]
	v_mfma_f32_16x16x32_bf16 v[56:59], v[142:145], v[186:189], v[56:59]
	v_mfma_f32_16x16x32_bf16 v[48:51], v[154:157], v[186:189], v[48:51]
	v_mfma_f32_16x16x32_bf16 v[40:43], v[142:145], v[194:197], v[40:43]
	v_mfma_f32_16x16x32_bf16 v[32:35], v[154:157], v[194:197], v[32:35]
	v_mfma_f32_16x16x32_bf16 v[24:27], v[142:145], v[202:205], v[24:27]
	v_mfma_f32_16x16x32_bf16 v[16:19], v[154:157], v[202:205], v[16:19]
	v_mfma_f32_16x16x32_bf16 v[64:67], v[150:153], v[182:185], v[64:67]
	v_mfma_f32_16x16x32_bf16 v[60:63], v[158:161], v[182:185], v[60:63]
	v_mfma_f32_16x16x32_bf16 v[56:59], v[150:153], v[190:193], v[56:59]
	v_mfma_f32_16x16x32_bf16 v[48:51], v[158:161], v[190:193], v[48:51]
	v_mfma_f32_16x16x32_bf16 v[40:43], v[150:153], v[198:201], v[40:43]
	v_mfma_f32_16x16x32_bf16 v[32:35], v[158:161], v[198:201], v[32:35]
	v_mfma_f32_16x16x32_bf16 v[24:27], v[150:153], v[206:209], v[24:27]
	v_mfma_f32_16x16x32_bf16 v[16:19], v[158:161], v[206:209], v[16:19]
	s_setprio 0
	s_setprio 1
	v_mfma_f32_16x16x32_bf16 v[52:55], v[162:165], v[178:181], v[52:55]
	v_mfma_f32_16x16x32_bf16 v[44:47], v[170:173], v[178:181], v[44:47]
	v_mfma_f32_16x16x32_bf16 v[36:39], v[162:165], v[186:189], v[36:39]
	v_mfma_f32_16x16x32_bf16 v[28:31], v[170:173], v[186:189], v[28:31]
	v_mfma_f32_16x16x32_bf16 v[20:23], v[162:165], v[194:197], v[20:23]
	v_mfma_f32_16x16x32_bf16 v[12:15], v[170:173], v[194:197], v[12:15]
	v_mfma_f32_16x16x32_bf16 v[8:11], v[162:165], v[202:205], v[8:11]
	v_mfma_f32_16x16x32_bf16 v[4:7], v[170:173], v[202:205], v[4:7]
	v_mfma_f32_16x16x32_bf16 v[52:55], v[166:169], v[182:185], v[52:55]
	v_mfma_f32_16x16x32_bf16 v[44:47], v[174:177], v[182:185], v[44:47]
	v_mfma_f32_16x16x32_bf16 v[36:39], v[166:169], v[190:193], v[36:39]
	v_mfma_f32_16x16x32_bf16 v[28:31], v[174:177], v[190:193], v[28:31]
	v_mfma_f32_16x16x32_bf16 v[20:23], v[166:169], v[198:201], v[20:23]
	v_mfma_f32_16x16x32_bf16 v[12:15], v[174:177], v[198:201], v[12:15]
	v_mfma_f32_16x16x32_bf16 v[8:11], v[166:169], v[206:209], v[8:11]
	v_mfma_f32_16x16x32_bf16 v[4:7], v[174:177], v[206:209], v[4:7]
	s_setprio 0
	s_barrier
	s_add_i32 s57, 0, 0x18000
	v_add_u32_e32 v149, s57, v146
	s_add_i32 s58, 0, 0x1c000
	ds_read_b128 v[142:145], v149
	ds_read_b128 v[150:153], v149 offset:1024
	ds_read_b128 v[154:157], v149 offset:2048
	ds_read_b128 v[158:161], v149 offset:3072
	v_add_u32_e32 v149, s58, v146
	ds_read_b128 v[162:165], v149
	ds_read_b128 v[166:169], v149 offset:1024
	ds_read_b128 v[170:173], v149 offset:2048
	ds_read_b128 v[174:177], v149 offset:3072
	s_add_u32 s30, s46, 0x80000
	s_addc_u32 s31, s47, 0
	s_mov_b32 m0, s33
	ds_read_b128 v[178:181], v148 offset:32768
	ds_read_b128 v[182:185], v148 offset:33792
	ds_read_b128 v[186:189], v148 offset:34816
	ds_read_b128 v[190:193], v148 offset:35840
	ds_read_b128 v[194:197], v148 offset:36864
	ds_read_b128 v[198:201], v148 offset:37888
	ds_read_b128 v[202:205], v148 offset:38912
	ds_read_b128 v[206:209], v148 offset:39936
	global_load_lds_dwordx4 v136, s[30:31]
	s_mov_b32 m0, s37
	s_nop 0
	global_load_lds_dwordx4 v134, s[30:31]
	s_waitcnt vmcnt(8)
	s_waitcnt lgkmcnt(0)
	s_barrier
	s_setprio 1
	s_waitcnt lgkmcnt(0)
	v_mfma_f32_16x16x32_bf16 v[128:131], v[142:145], v[178:181], v[128:131]
	v_mfma_f32_16x16x32_bf16 v[124:127], v[154:157], v[178:181], v[124:127]
	v_mfma_f32_16x16x32_bf16 v[120:123], v[142:145], v[186:189], v[120:123]
	v_mfma_f32_16x16x32_bf16 v[112:115], v[154:157], v[186:189], v[112:115]
	v_mfma_f32_16x16x32_bf16 v[104:107], v[142:145], v[194:197], v[104:107]
	v_mfma_f32_16x16x32_bf16 v[96:99], v[154:157], v[194:197], v[96:99]
	v_mfma_f32_16x16x32_bf16 v[88:91], v[142:145], v[202:205], v[88:91]
	v_mfma_f32_16x16x32_bf16 v[80:83], v[154:157], v[202:205], v[80:83]
	v_mfma_f32_16x16x32_bf16 v[128:131], v[150:153], v[182:185], v[128:131]
	v_mfma_f32_16x16x32_bf16 v[124:127], v[158:161], v[182:185], v[124:127]
	v_mfma_f32_16x16x32_bf16 v[120:123], v[150:153], v[190:193], v[120:123]
	v_mfma_f32_16x16x32_bf16 v[112:115], v[158:161], v[190:193], v[112:115]
	v_mfma_f32_16x16x32_bf16 v[104:107], v[150:153], v[198:201], v[104:107]
	v_mfma_f32_16x16x32_bf16 v[96:99], v[158:161], v[198:201], v[96:99]
	v_mfma_f32_16x16x32_bf16 v[88:91], v[150:153], v[206:209], v[88:91]
	v_mfma_f32_16x16x32_bf16 v[80:83], v[158:161], v[206:209], v[80:83]
	s_setprio 0
	s_setprio 1
	v_mfma_f32_16x16x32_bf16 v[116:119], v[162:165], v[178:181], v[116:119]
	v_mfma_f32_16x16x32_bf16 v[108:111], v[170:173], v[178:181], v[108:111]
	v_mfma_f32_16x16x32_bf16 v[100:103], v[162:165], v[186:189], v[100:103]
	v_mfma_f32_16x16x32_bf16 v[92:95], v[170:173], v[186:189], v[92:95]
	v_mfma_f32_16x16x32_bf16 v[84:87], v[162:165], v[194:197], v[84:87]
	v_mfma_f32_16x16x32_bf16 v[76:79], v[170:173], v[194:197], v[76:79]
	v_mfma_f32_16x16x32_bf16 v[72:75], v[162:165], v[202:205], v[72:75]
	v_mfma_f32_16x16x32_bf16 v[68:71], v[170:173], v[202:205], v[68:71]
	v_mfma_f32_16x16x32_bf16 v[116:119], v[166:169], v[182:185], v[116:119]
	v_mfma_f32_16x16x32_bf16 v[108:111], v[174:177], v[182:185], v[108:111]
	v_mfma_f32_16x16x32_bf16 v[100:103], v[166:169], v[190:193], v[100:103]
	v_mfma_f32_16x16x32_bf16 v[92:95], v[174:177], v[190:193], v[92:95]
	v_mfma_f32_16x16x32_bf16 v[84:87], v[166:169], v[198:201], v[84:87]
	v_mfma_f32_16x16x32_bf16 v[76:79], v[174:177], v[198:201], v[76:79]
	v_mfma_f32_16x16x32_bf16 v[72:75], v[166:169], v[206:209], v[72:75]
	v_mfma_f32_16x16x32_bf16 v[68:71], v[174:177], v[206:209], v[68:71]
	s_setprio 0
	s_barrier
; #define PG8_STAGE(bufoff, gbase, voff) do { _Pragma("unroll") for (int _i = 0; _i < 2; ++_i) \
;         __builtin_amdgcn_global_load_lds((const unsigned*)((const char*)(gbase) + (voff)[_i]), (PG8_LAS unsigned*)(lds + (bufoff) + ldsw + _i * 8192), 16, 0, 0); } while (0)
; #define PG8_LDA(dst, b, h) do { _Pragma("unroll") for (int m = 0; m < 4; ++m) _Pragma("unroll") for (int k = 0; k < 2; ++k) dst[m][k] = *(const PG8_LAS bf16x8*)(lds + PG8_SA(b, h) + aoff + m * 2048 + k * 1024); } while (0)
; #define PG8_MMA(ai, bj, At, Bt) do { __builtin_amdgcn_s_setprio(1); _Pragma("unroll") for (int m = 0; m < 4; ++m) _Pragma("unroll") for (int n = 0; n < 2; ++n) _Pragma("unroll") for (int k = 0; k < 2; ++k) \
;         acc[ai][bj][m][n] = __builtin_amdgcn_mfma_f32_16x16x32_bf16(Bt[n][k], At[m][k], acc[ai][bj][m][n], 0, 0, 0); __builtin_amdgcn_s_setprio(0); } while (0)
; #define PG8_WAIT_V(n) asm volatile("s_waitcnt vmcnt(" #n ")" ::: "memory")
; #define PG8_WAIT_L(n) asm volatile("s_waitcnt lgkmcnt(" #n ")" ::: "memory")
; #define PG8_BAR __builtin_amdgcn_s_barrier()
; #define PG8_SCHED __builtin_amdgcn_sched_barrier(0)
; template <class Epi, class Sched, bool ALIGN_EPI = false, bool SP2 = false>
; __device__ __forceinline__ void gemm_phase(PG8_LAS unsigned char* lds, const Gemm g, const Sched& S, const Epi& E) {
;     ...
;             PG8_LDA(At, 1, 1); PG8_STAGE(PG8_SB(1, 0), b3, voffB); PG8_STAGE(PG8_SB(1, 1), b3 + hstep, voffB); PG8_STAGE(PG8_SA(1, 0), a3, voffA);
;             PG8_WAIT_V(8); PG8_WAIT_L(0); PG8_BAR; PG8_MMA(1, 0, At, B0); PG8_MMA(1, 1, At, B1); PG8_BAR; PG8_SCHED;
	s_add_i32 s30, s57, s10
	v_lshl_add_u64 v[210:211], v[210:211], 0, s[28:29]
	s_mov_b32 m0, s30
	ds_read_b128 v[178:181], v148 offset:49152
	ds_read_b128 v[182:185], v148 offset:50176
	ds_read_b128 v[186:189], v148 offset:51200
	ds_read_b128 v[190:193], v148 offset:52224
	ds_read_b128 v[194:197], v148 offset:53248
	ds_read_b128 v[198:201], v148 offset:54272
	ds_read_b128 v[202:205], v148 offset:55296
	ds_read_b128 v[206:209], v148 offset:56320
	global_load_lds_dwordx4 v[210:211], off
	s_add_i32 m0, s30, 0x2000
	s_add_u32 s20, s20, 0x80080
	v_lshl_add_u64 v[210:211], v[212:213], 0, s[28:29]
	s_addc_u32 s21, s21, 0
	s_add_i32 s30, s58, s10
	global_load_lds_dwordx4 v[210:211], off
	s_mov_b32 m0, s30
	s_nop 0
	global_load_lds_dwordx4 v2, s[20:21]
	s_add_i32 m0, s30, 0x2000
	s_nop 0
	global_load_lds_dwordx4 v132, s[20:21]
	v_lshl_add_u64 v[210:211], v[214:215], 0, s[28:29]
	s_mov_b32 m0, s18
	s_nop 0
	global_load_lds_dwordx4 v[210:211], off
	v_lshl_add_u64 v[210:211], v[216:217], 0, s[28:29]
	s_mov_b32 m0, s48
	s_nop 0
	global_load_lds_dwordx4 v[210:211], off
	s_waitcnt vmcnt(8)
	s_waitcnt lgkmcnt(0)
	s_barrier
	s_setprio 1
	s_waitcnt lgkmcnt(0)
	v_mfma_f32_16x16x32_bf16 v[64:67], v[142:145], v[178:181], v[64:67]
	v_mfma_f32_16x16x32_bf16 v[60:63], v[154:157], v[178:181], v[60:63]
	v_mfma_f32_16x16x32_bf16 v[56:59], v[142:145], v[186:189], v[56:59]
	v_mfma_f32_16x16x32_bf16 v[48:51], v[154:157], v[186:189], v[48:51]
	v_mfma_f32_16x16x32_bf16 v[40:43], v[142:145], v[194:197], v[40:43]
	v_mfma_f32_16x16x32_bf16 v[32:35], v[154:157], v[194:197], v[32:35]
	v_mfma_f32_16x16x32_bf16 v[24:27], v[142:145], v[202:205], v[24:27]
	v_mfma_f32_16x16x32_bf16 v[16:19], v[154:157], v[202:205], v[16:19]
	v_mfma_f32_16x16x32_bf16 v[64:67], v[150:153], v[182:185], v[64:67]
	v_mfma_f32_16x16x32_bf16 v[60:63], v[158:161], v[182:185], v[60:63]
	v_mfma_f32_16x16x32_bf16 v[56:59], v[150:153], v[190:193], v[56:59]
	v_mfma_f32_16x16x32_bf16 v[48:51], v[158:161], v[190:193], v[48:51]
	v_mfma_f32_16x16x32_bf16 v[40:43], v[150:153], v[198:201], v[40:43]
	v_mfma_f32_16x16x32_bf16 v[32:35], v[158:161], v[198:201], v[32:35]
	v_mfma_f32_16x16x32_bf16 v[24:27], v[150:153], v[206:209], v[24:27]
	v_mfma_f32_16x16x32_bf16 v[16:19], v[158:161], v[206:209], v[16:19]
	s_setprio 0
	s_setprio 1
	v_mfma_f32_16x16x32_bf16 v[52:55], v[162:165], v[178:181], v[52:55]
	v_mfma_f32_16x16x32_bf16 v[44:47], v[170:173], v[178:181], v[44:47]
	v_mfma_f32_16x16x32_bf16 v[36:39], v[162:165], v[186:189], v[36:39]
	v_mfma_f32_16x16x32_bf16 v[28:31], v[170:173], v[186:189], v[28:31]
	v_mfma_f32_16x16x32_bf16 v[20:23], v[162:165], v[194:197], v[20:23]
	v_mfma_f32_16x16x32_bf16 v[12:15], v[170:173], v[194:197], v[12:15]
	v_mfma_f32_16x16x32_bf16 v[8:11], v[162:165], v[202:205], v[8:11]
	v_mfma_f32_16x16x32_bf16 v[4:7], v[170:173], v[202:205], v[4:7]
	v_mfma_f32_16x16x32_bf16 v[52:55], v[166:169], v[182:185], v[52:55]
	v_mfma_f32_16x16x32_bf16 v[44:47], v[174:177], v[182:185], v[44:47]
	v_mfma_f32_16x16x32_bf16 v[36:39], v[166:169], v[190:193], v[36:39]
	v_mfma_f32_16x16x32_bf16 v[28:31], v[174:177], v[190:193], v[28:31]
	v_mfma_f32_16x16x32_bf16 v[20:23], v[166:169], v[198:201], v[20:23]
	v_mfma_f32_16x16x32_bf16 v[12:15], v[174:177], v[198:201], v[12:15]
	v_mfma_f32_16x16x32_bf16 v[8:11], v[166:169], v[206:209], v[8:11]
	v_mfma_f32_16x16x32_bf16 v[4:7], v[174:177], v[206:209], v[4:7]
	s_setprio 0
	s_barrier
	s_add_i32 s56, s56, 2
	s_add_u32 s54, s54, 0x100
	s_addc_u32 s55, s55, 0
	s_add_u32 s44, s44, 0x100
	s_addc_u32 s45, s45, 0
	s_cmp_gt_u32 s56, 29
	s_cbranch_scc0 .LBB0_310
	s_and_b64 vcc, exec, s[22:23]
	s_cbranch_vccz .LBB0_313
	s_barrier

; #define PG8_STAGE(bufoff, gbase, voff) do { _Pragma("unroll") for (int _i = 0; _i < 2; ++_i) \
;         __builtin_amdgcn_global_load_lds((const unsigned*)((const char*)(gbase) + (voff)[_i]), (PG8_LAS unsigned*)(lds + (bufoff) + ldsw + _i * 8192), 16, 0, 0); } while (0)
; #define PG8_WAIT_V(n) asm volatile("s_waitcnt vmcnt(" #n ")" ::: "memory")
; #define PG8_BAR __builtin_amdgcn_s_barrier()
; template <class Epi, class Sched, bool ALIGN_EPI = false, bool SP2 = false>
; __device__ __forceinline__ void gemm_phase(PG8_LAS unsigned char* lds, const Gemm g, const Sched& S, const Epi& E) {
;     ...
;     for (int i = 0; i < 2; ++i) { int R, C; stage_rc(tid * 16 + i * 8192, R, C); const int Rb = Epi::PERM ? ((R & ~31) + perm32(R & 31)) : R;
;         voffA[i] = (unsigned)(R * K + C) * 2u; voffB[i] = (unsigned)(Rb * K + C) * 2u; }
;     const size_t kstep = (size_t)(BK * 2);
;     const size_t hstep = (size_t)HALF * K * 2;
;     const size_t tstep = 2 * hstep;
;     const unsigned ldsw = (unsigned)wid * 1024u;
;     const int aoff = lds_byte(wr * 64 + fr, fq * 8), boff = lds_byte(wc * 32 + fr, fq * 8);
;     ...
;     Unit cur, nxt; int ui = 0;
;     if (!S.next(0, cur)) return;
;     f32x4 acc[2][2][4][2];
; #pragma unroll
;     for (int a = 0; a < 2; ++a)
; #pragma unroll
;         for (int b = 0; b < 2; ++b)
; #pragma unroll
;             for (int m = 0; m < 4; ++m)
; #pragma unroll
;                 for (int n = 0; n < 2; ++n) acc[a][b][m][n] = (f32x4){0.f, 0.f, 0.f, 0.f};
;     bf16x8 At[4][2], B0[2][2], B1[2][2];
;     const char* cA = (const char*)g.A + (size_t)cur.pm * tstep; const char* cB = (const char*)g.Bt + (size_t)cur.pn * tstep;
;     S.a_ready(cur);
;     if constexpr (SP2) {
;         PG8_STAGE(PG8_SB(0, 0), cB, voffB); PG8_STAGE(PG8_SB(0, 1), cB + hstep, voffB); PG8_STAGE(PG8_SA(0, 0), cA, voffA); PG8_STAGE(PG8_SA(0, 1), cA + hstep, voffA);
;         if (wr == 1) PG8_BAR;
;         PG8_WAIT_V(2); PG8_BAR;
;         PG8_STAGE(PG8_SB(1, 0), cB + kstep, voffB); PG8_STAGE(PG8_SA(1, 0), cA + kstep, voffA); PG8_STAGE(PG8_SB(1, 1), cB + hstep + kstep, voffB);
;         PG8_WAIT_V(6); PG8_BAR;
.LBB0_2037:
	s_add_u32 s14, s14, 0x4800000
	s_addc_u32 s15, s15, 0
	s_sext_i32_i8 s4, s18
	s_add_u32 s18, s13, 0x104000
	v_lshrrev_b32_e32 v20, 1, v18
	s_addc_u32 s53, s22, 0
	v_and_b32_e32 v20, 24, v20
	s_lshl_b32 s12, s12, 5
	v_and_b32_e32 v19, 15, v18
	v_lshlrev_b32_e32 v21, 1, v20
	v_lshlrev_b32_e32 v18, 2, v18
	s_and_b32 s22, s12, 0x60
	s_add_i32 m0, s43, 0x18000
	v_lshl_add_u64 v[10:11], v[10:11], 0, s[28:29]
	v_lshl_or_b32 v1, s23, 6, v19
	v_lshl_or_b32 v19, v19, 6, v21
	s_lshl_b32 s13, s23, 13
	v_and_b32_e32 v18, 32, v18
	s_lshl_b32 s12, s22, 7
	s_waitcnt vmcnt(2)
	s_barrier
	global_load_lds_dwordx4 v[10:11], off
	v_lshl_add_u64 v[8:9], v[8:9], 0, s[28:29]
	s_add_i32 m0, s43, 0x1a000
	s_add_i32 s54, s43, 0x8000
	s_add_i32 s55, s43, 0xa000
	v_bitop3_b32 v212, v19, s12, v18 bitop3:0xde
	global_load_lds_dwordx4 v[8:9], off
	v_lshl_add_u64 v[6:7], v[6:7], 0, s[28:29]
	s_mov_b32 m0, s54
	s_add_u32 s12, s20, 0x80080
	v_bitop3_b32 v21, v19, s13, v18 bitop3:0xde
	global_load_lds_dwordx4 v[6:7], off
	v_lshl_add_u64 v[4:5], v[4:5], 0, s[28:29]
	s_mov_b32 m0, s55
	s_addc_u32 s13, s21, 0
	global_load_lds_dwordx4 v[4:5], off
	s_add_i32 m0, s43, 0x1c000
	s_nop 0
	global_load_lds_dwordx4 v2, s[12:13]
	v_lshl_add_u64 v[4:5], s[12:13], 0, v[184:185]
	s_add_i32 m0, s43, 0x1e000
	s_ashr_i32 s56, s5, 31
	global_load_lds_dwordx4 v[4:5], off
	v_lshlrev_b32_e32 v4, 15, v15
	v_and_b32_e32 v4, 0xffff0000, v4
	v_lshl_add_u32 v4, v16, 12, v4
	v_and_b32_e32 v5, 1, v15
	v_lshl_or_b32 v4, v5, 6, v4
	v_lshl_add_u32 v186, v17, 1, v4
	v_lshlrev_b32_e32 v4, 15, v12
	v_and_b32_e32 v4, 0xffff0000, v4
	s_waitcnt vmcnt(6)
	v_lshl_add_u32 v4, v13, 12, v4
	v_and_b32_e32 v5, 1, v12
	v_lshl_or_b32 v4, v5, 6, v4
	v_or_b32_e32 v213, s22, v20
	v_mov_b32_e32 v187, v3
	v_lshl_add_u32 v188, v14, 1, v4
	v_mov_b32_e32 v189, v3
	s_mov_b32 s57, 0
	v_add_u32_e32 v218, 0, v21
	s_barrier
	s_branch .LBB0_2039

; #define PG8_STAGE(bufoff, gbase, voff) do { _Pragma("unroll") for (int _i = 0; _i < 2; ++_i) \
;         __builtin_amdgcn_global_load_lds((const unsigned*)((const char*)(gbase) + (voff)[_i]), (PG8_LAS unsigned*)(lds + (bufoff) + ldsw + _i * 8192), 16, 0, 0); } while (0)
; #define PG8_LDA(dst, b, h) do { _Pragma("unroll") for (int m = 0; m < 4; ++m) _Pragma("unroll") for (int k = 0; k < 2; ++k) dst[m][k] = *(const PG8_LAS bf16x8*)(lds + PG8_SA(b, h) + aoff + m * 2048 + k * 1024); } while (0)
; #define PG8_LDB(dst, b, h) do { _Pragma("unroll") for (int n = 0; n < 2; ++n) _Pragma("unroll") for (int k = 0; k < 2; ++k) dst[n][k] = *(const PG8_LAS bf16x8*)(lds + PG8_SB(b, h) + boff + n * 2048 + k * 1024); } while (0)
; #define PG8_WAIT_V(n) asm volatile("s_waitcnt vmcnt(" #n ")" ::: "memory")
; #define PG8_WAIT_L(n) asm volatile("s_waitcnt lgkmcnt(" #n ")" ::: "memory")
; #define PG8_BAR __builtin_amdgcn_s_barrier()
; #define PG8_SCHED __builtin_amdgcn_sched_barrier(0)
; template <class Epi, class Sched, bool ALIGN_EPI = false, bool SP2 = false>
; __device__ __forceinline__ void gemm_phase(PG8_LAS unsigned char* lds, const Gemm g, const Sched& S, const Epi& E) {
;     ...
;         const char* nA = has_next ? (const char*)g.A + (size_t)nxt.pm * tstep : cA; const char* nB = has_next ? (const char*)g.Bt + (size_t)nxt.pn * tstep : cB;
;         for (int t = 0; t < nt; t += 2) {
;             const bool last = (t == nt - 2);
;             const char* a1 = cA + (size_t)(t + 1) * kstep;
;             const char* a2 = last ? nA : cA + (size_t)(t + 2) * kstep; const char* b2 = last ? nB : cB + (size_t)(t + 2) * kstep;
;             const char* a3 = a2 + kstep; const char* b3 = b2 + kstep;
;             if (last && has_next) S.a_ready(nxt);
;             if constexpr (SP2) {
;             PG8_LDB(B0, 0, 0); PG8_LDB(B1, 0, 1); PG8_SCHED; PG8_LDA(At, 0, 0); PG8_STAGE(PG8_SA(1, 1), a1 + hstep, voffA);
;             PG8_WAIT_V(8); PG8_WAIT_L(0); PG8_BAR; PG8_MMA(0, 0, At, B0); PG8_MMA(0, 1, At, B1); PG8_BAR; PG8_SCHED;
;             PG8_LDA(At, 0, 1); PG8_STAGE(PG8_SB(0, 0), b2, voffB); PG8_STAGE(PG8_SB(0, 1), b2 + hstep, voffB); PG8_STAGE(PG8_SA(0, 0), a2, voffA);
;             PG8_WAIT_V(8); PG8_WAIT_L(0); PG8_BAR; PG8_MMA(1, 0, At, B0); PG8_MMA(1, 1, At, B1); PG8_BAR; PG8_SCHED;
.LBB0_2046:
	s_add_u32 s20, s44, 0xfff80080
	s_addc_u32 s21, s45, -1
	s_add_i32 s30, 0, 0x10000
	s_cmp_eq_u32 s59, 28
	s_cselect_b32 s47, s12, s21
	s_cselect_b32 s46, s13, s20
	s_cselect_b32 s21, s23, s58
	s_cselect_b32 s20, s25, s33
	s_add_i32 s60, 0, 0x14000
	s_waitcnt vmcnt(0) lgkmcnt(0)
	v_add_u32_e32 v80, s30, v212
	v_add_u32_e32 v160, s60, v212
	ds_read_b128 v[60:63], v80
	ds_read_b128 v[64:67], v80 offset:1024
	ds_read_b128 v[76:79], v80 offset:2048
	ds_read_b128 v[80:83], v80 offset:3072
	ds_read_b128 v[148:151], v160
	ds_read_b128 v[152:155], v160 offset:1024
	ds_read_b128 v[156:159], v160 offset:2048
	ds_read_b128 v[160:163], v160 offset:3072
	s_add_i32 m0, s43, 0xc000
	ds_read_b128 v[164:167], v218
	ds_read_b128 v[168:171], v218 offset:1024
	ds_read_b128 v[172:175], v218 offset:2048
	ds_read_b128 v[176:179], v218 offset:3072
	ds_read_b128 v[190:193], v218 offset:4096
	ds_read_b128 v[194:197], v218 offset:5120
	ds_read_b128 v[198:201], v218 offset:6144
	ds_read_b128 v[202:205], v218 offset:7168
	global_load_lds_dwordx4 v188, s[44:45]
	s_add_i32 m0, s43, 0xe000
	s_nop 0
	global_load_lds_dwordx4 v186, s[44:45]
	s_waitcnt vmcnt(8)
	s_waitcnt lgkmcnt(0)
	s_barrier
	s_setprio 1
	s_waitcnt lgkmcnt(0)
	v_mfma_f32_16x16x32_bf16 v[144:147], v[60:63], v[164:167], v[144:147]
	v_mfma_f32_16x16x32_bf16 v[140:143], v[76:79], v[164:167], v[140:143]
	v_mfma_f32_16x16x32_bf16 v[136:139], v[60:63], v[172:175], v[136:139]
	v_mfma_f32_16x16x32_bf16 v[132:135], v[76:79], v[172:175], v[132:135]
	v_mfma_f32_16x16x32_bf16 v[112:115], v[60:63], v[190:193], v[112:115]
	v_mfma_f32_16x16x32_bf16 v[108:111], v[76:79], v[190:193], v[108:111]
	v_mfma_f32_16x16x32_bf16 v[104:107], v[60:63], v[198:201], v[104:107]
	v_mfma_f32_16x16x32_bf16 v[100:103], v[76:79], v[198:201], v[100:103]
	v_mfma_f32_16x16x32_bf16 v[144:147], v[64:67], v[168:171], v[144:147]
	v_mfma_f32_16x16x32_bf16 v[140:143], v[80:83], v[168:171], v[140:143]
	v_mfma_f32_16x16x32_bf16 v[136:139], v[64:67], v[176:179], v[136:139]
	v_mfma_f32_16x16x32_bf16 v[132:135], v[80:83], v[176:179], v[132:135]
	v_mfma_f32_16x16x32_bf16 v[112:115], v[64:67], v[194:197], v[112:115]
	v_mfma_f32_16x16x32_bf16 v[108:111], v[80:83], v[194:197], v[108:111]
	v_mfma_f32_16x16x32_bf16 v[104:107], v[64:67], v[202:205], v[104:107]
	v_mfma_f32_16x16x32_bf16 v[100:103], v[80:83], v[202:205], v[100:103]
	s_setprio 0
	s_setprio 1
	v_mfma_f32_16x16x32_bf16 v[128:131], v[148:151], v[164:167], v[128:131]
	v_mfma_f32_16x16x32_bf16 v[124:127], v[156:159], v[164:167], v[124:127]
	v_mfma_f32_16x16x32_bf16 v[120:123], v[148:151], v[172:175], v[120:123]
	v_mfma_f32_16x16x32_bf16 v[116:119], v[156:159], v[172:175], v[116:119]
	v_mfma_f32_16x16x32_bf16 v[96:99], v[148:151], v[190:193], v[96:99]
	v_mfma_f32_16x16x32_bf16 v[92:95], v[156:159], v[190:193], v[92:95]
	v_mfma_f32_16x16x32_bf16 v[88:91], v[148:151], v[198:201], v[88:91]
	v_mfma_f32_16x16x32_bf16 v[84:87], v[156:159], v[198:201], v[84:87]
	v_mfma_f32_16x16x32_bf16 v[128:131], v[152:155], v[168:171], v[128:131]
	v_mfma_f32_16x16x32_bf16 v[124:127], v[160:163], v[168:171], v[124:127]
	v_mfma_f32_16x16x32_bf16 v[120:123], v[152:155], v[176:179], v[120:123]
	v_mfma_f32_16x16x32_bf16 v[116:119], v[160:163], v[176:179], v[116:119]
	v_mfma_f32_16x16x32_bf16 v[96:99], v[152:155], v[194:197], v[96:99]
	v_mfma_f32_16x16x32_bf16 v[92:95], v[160:163], v[194:197], v[92:95]
	v_mfma_f32_16x16x32_bf16 v[88:91], v[152:155], v[202:205], v[88:91]
	v_mfma_f32_16x16x32_bf16 v[84:87], v[160:163], v[202:205], v[84:87]
	s_setprio 0
	s_barrier
	s_add_i32 s30, s30, s9
	v_lshl_add_u64 v[206:207], s[20:21], 0, v[2:3]
	s_mov_b32 m0, s30
	ds_read_b128 v[164:167], v218 offset:16384
	ds_read_b128 v[168:171], v218 offset:17408
	ds_read_b128 v[172:175], v218 offset:18432
	ds_read_b128 v[176:179], v218 offset:19456
	ds_read_b128 v[190:193], v218 offset:20480
	ds_read_b128 v[194:197], v218 offset:21504
	ds_read_b128 v[198:201], v218 offset:22528
	ds_read_b128 v[202:205], v218 offset:23552
	global_load_lds_dwordx4 v[206:207], off
	s_add_i32 m0, s30, 0x2000
	s_add_u32 s30, s20, 0x80000
	v_lshl_add_u64 v[208:209], s[20:21], 0, v[184:185]
	s_addc_u32 s31, s21, 0
	s_add_i32 s60, s60, s9
	global_load_lds_dwordx4 v[208:209], off
	s_mov_b32 m0, s60
	v_lshl_add_u64 v[214:215], s[46:47], 0, v[182:183]
	global_load_lds_dwordx4 v2, s[30:31]
	s_add_i32 m0, s60, 0x2000
	s_nop 0
	global_load_lds_dwordx4 v184, s[30:31]
	v_lshl_add_u64 v[210:211], s[46:47], 0, v[180:181]
	s_mov_b32 m0, s43
	s_nop 0
	global_load_lds_dwordx4 v[210:211], off
	s_mov_b32 m0, s50
	s_nop 0
	global_load_lds_dwordx4 v[214:215], off
	s_waitcnt vmcnt(8)
	s_waitcnt lgkmcnt(0)
	s_barrier
; #define PG8_STAGE(bufoff, gbase, voff) do { _Pragma("unroll") for (int _i = 0; _i < 2; ++_i) \
;         __builtin_amdgcn_global_load_lds((const unsigned*)((const char*)(gbase) + (voff)[_i]), (PG8_LAS unsigned*)(lds + (bufoff) + ldsw + _i * 8192), 16, 0, 0); } while (0)
; #define PG8_LDA(dst, b, h) do { _Pragma("unroll") for (int m = 0; m < 4; ++m) _Pragma("unroll") for (int k = 0; k < 2; ++k) dst[m][k] = *(const PG8_LAS bf16x8*)(lds + PG8_SA(b, h) + aoff + m * 2048 + k * 1024); } while (0)
; #define PG8_LDB(dst, b, h) do { _Pragma("unroll") for (int n = 0; n < 2; ++n) _Pragma("unroll") for (int k = 0; k < 2; ++k) dst[n][k] = *(const PG8_LAS bf16x8*)(lds + PG8_SB(b, h) + boff + n * 2048 + k * 1024); } while (0)
; #define PG8_MMA(ai, bj, At, Bt) do { __builtin_amdgcn_s_setprio(1); _Pragma("unroll") for (int m = 0; m < 4; ++m) _Pragma("unroll") for (int n = 0; n < 2; ++n) _Pragma("unroll") for (int k = 0; k < 2; ++k) \
;         acc[ai][bj][m][n] = __builtin_amdgcn_mfma_f32_16x16x32_bf16(Bt[n][k], At[m][k], acc[ai][bj][m][n], 0, 0, 0); __builtin_amdgcn_s_setprio(0); } while (0)
; #define PG8_WAIT_V(n) asm volatile("s_waitcnt vmcnt(" #n ")" ::: "memory")
; #define PG8_WAIT_L(n) asm volatile("s_waitcnt lgkmcnt(" #n ")" ::: "memory")
; #define PG8_BAR __builtin_amdgcn_s_barrier()
; #define PG8_SCHED __builtin_amdgcn_sched_barrier(0)
; template <class Epi, class Sched, bool ALIGN_EPI = false, bool SP2 = false>
; __device__ __forceinline__ void gemm_phase(PG8_LAS unsigned char* lds, const Gemm g, const Sched& S, const Epi& E) {
;     ...
;             PG8_WAIT_V(8); PG8_WAIT_L(0); PG8_BAR; PG8_MMA(1, 0, At, B0); PG8_MMA(1, 1, At, B1); PG8_BAR; PG8_SCHED;
;             PG8_LDB(B0, 1, 0); PG8_LDB(B1, 1, 1); PG8_SCHED; PG8_LDA(At, 1, 0); PG8_STAGE(PG8_SA(0, 1), a2 + hstep, voffA);
;             PG8_WAIT_V(8); PG8_WAIT_L(0); PG8_BAR; PG8_MMA(0, 0, At, B0); PG8_MMA(0, 1, At, B1); PG8_BAR; PG8_SCHED;
	s_setprio 1
	s_waitcnt lgkmcnt(0)
	v_mfma_f32_16x16x32_bf16 v[72:75], v[60:63], v[164:167], v[72:75]
	v_mfma_f32_16x16x32_bf16 v[68:71], v[76:79], v[164:167], v[68:71]
	v_mfma_f32_16x16x32_bf16 v[56:59], v[60:63], v[172:175], v[56:59]
	v_mfma_f32_16x16x32_bf16 v[52:55], v[76:79], v[172:175], v[52:55]
	v_mfma_f32_16x16x32_bf16 v[32:35], v[60:63], v[190:193], v[32:35]
	v_mfma_f32_16x16x32_bf16 v[28:31], v[76:79], v[190:193], v[28:31]
	v_mfma_f32_16x16x32_bf16 v[24:27], v[60:63], v[198:201], v[24:27]
	v_mfma_f32_16x16x32_bf16 v[20:23], v[76:79], v[198:201], v[20:23]
	v_mfma_f32_16x16x32_bf16 v[72:75], v[64:67], v[168:171], v[72:75]
	v_mfma_f32_16x16x32_bf16 v[68:71], v[80:83], v[168:171], v[68:71]
	v_mfma_f32_16x16x32_bf16 v[56:59], v[64:67], v[176:179], v[56:59]
	v_mfma_f32_16x16x32_bf16 v[52:55], v[80:83], v[176:179], v[52:55]
	v_mfma_f32_16x16x32_bf16 v[32:35], v[64:67], v[194:197], v[32:35]
	v_mfma_f32_16x16x32_bf16 v[28:31], v[80:83], v[194:197], v[28:31]
	v_mfma_f32_16x16x32_bf16 v[24:27], v[64:67], v[202:205], v[24:27]
	v_mfma_f32_16x16x32_bf16 v[20:23], v[80:83], v[202:205], v[20:23]
	s_setprio 0
	s_setprio 1
	v_mfma_f32_16x16x32_bf16 v[48:51], v[148:151], v[164:167], v[48:51]
	v_mfma_f32_16x16x32_bf16 v[44:47], v[156:159], v[164:167], v[44:47]
	v_mfma_f32_16x16x32_bf16 v[40:43], v[148:151], v[172:175], v[40:43]
	v_mfma_f32_16x16x32_bf16 v[36:39], v[156:159], v[172:175], v[36:39]
	v_mfma_f32_16x16x32_bf16 v[16:19], v[148:151], v[190:193], v[16:19]
	v_mfma_f32_16x16x32_bf16 v[12:15], v[156:159], v[190:193], v[12:15]
	v_mfma_f32_16x16x32_bf16 v[8:11], v[148:151], v[198:201], v[8:11]
	v_mfma_f32_16x16x32_bf16 v[4:7], v[156:159], v[198:201], v[4:7]
	v_mfma_f32_16x16x32_bf16 v[48:51], v[152:155], v[168:171], v[48:51]
	v_mfma_f32_16x16x32_bf16 v[44:47], v[160:163], v[168:171], v[44:47]
	v_mfma_f32_16x16x32_bf16 v[40:43], v[152:155], v[176:179], v[40:43]
	v_mfma_f32_16x16x32_bf16 v[36:39], v[160:163], v[176:179], v[36:39]
	v_mfma_f32_16x16x32_bf16 v[16:19], v[152:155], v[194:197], v[16:19]
	v_mfma_f32_16x16x32_bf16 v[12:15], v[160:163], v[194:197], v[12:15]
	v_mfma_f32_16x16x32_bf16 v[8:11], v[152:155], v[202:205], v[8:11]
	v_mfma_f32_16x16x32_bf16 v[4:7], v[160:163], v[202:205], v[4:7]
	s_setprio 0
	s_barrier
	s_add_i32 s60, 0, 0x18000
	s_add_i32 s61, 0, 0x1c000
	v_add_u32_e32 v80, s60, v212
	v_add_u32_e32 v160, s61, v212
	ds_read_b128 v[60:63], v80
	ds_read_b128 v[64:67], v80 offset:1024
	ds_read_b128 v[76:79], v80 offset:2048
	ds_read_b128 v[80:83], v80 offset:3072
	ds_read_b128 v[148:151], v160
	ds_read_b128 v[152:155], v160 offset:1024
	ds_read_b128 v[156:159], v160 offset:2048
	ds_read_b128 v[160:163], v160 offset:3072
	s_add_u32 s30, s46, 0x80000
	s_addc_u32 s31, s47, 0
	s_mov_b32 m0, s51
	ds_read_b128 v[164:167], v218 offset:32768
	ds_read_b128 v[168:171], v218 offset:33792
	ds_read_b128 v[172:175], v218 offset:34816
	ds_read_b128 v[176:179], v218 offset:35840
	ds_read_b128 v[190:193], v218 offset:36864
	ds_read_b128 v[194:197], v218 offset:37888
	ds_read_b128 v[198:201], v218 offset:38912
	ds_read_b128 v[202:205], v218 offset:39936
	global_load_lds_dwordx4 v180, s[30:31]
	s_mov_b32 m0, s52
	s_nop 0
	global_load_lds_dwordx4 v182, s[30:31]
	s_waitcnt vmcnt(8)
	s_waitcnt lgkmcnt(0)
	s_barrier
	s_setprio 1
	s_waitcnt lgkmcnt(0)
	v_mfma_f32_16x16x32_bf16 v[144:147], v[60:63], v[164:167], v[144:147]
	v_mfma_f32_16x16x32_bf16 v[140:143], v[76:79], v[164:167], v[140:143]
	v_mfma_f32_16x16x32_bf16 v[136:139], v[60:63], v[172:175], v[136:139]
	v_mfma_f32_16x16x32_bf16 v[132:135], v[76:79], v[172:175], v[132:135]
	v_mfma_f32_16x16x32_bf16 v[112:115], v[60:63], v[190:193], v[112:115]
	v_mfma_f32_16x16x32_bf16 v[108:111], v[76:79], v[190:193], v[108:111]
	v_mfma_f32_16x16x32_bf16 v[104:107], v[60:63], v[198:201], v[104:107]
	v_mfma_f32_16x16x32_bf16 v[100:103], v[76:79], v[198:201], v[100:103]
	v_mfma_f32_16x16x32_bf16 v[144:147], v[64:67], v[168:171], v[144:147]
	v_mfma_f32_16x16x32_bf16 v[140:143], v[80:83], v[168:171], v[140:143]
	v_mfma_f32_16x16x32_bf16 v[136:139], v[64:67], v[176:179], v[136:139]
	v_mfma_f32_16x16x32_bf16 v[132:135], v[80:83], v[176:179], v[132:135]
	v_mfma_f32_16x16x32_bf16 v[112:115], v[64:67], v[194:197], v[112:115]
	v_mfma_f32_16x16x32_bf16 v[108:111], v[80:83], v[194:197], v[108:111]
	v_mfma_f32_16x16x32_bf16 v[104:107], v[64:67], v[202:205], v[104:107]
	v_mfma_f32_16x16x32_bf16 v[100:103], v[80:83], v[202:205], v[100:103]
	s_setprio 0
	s_setprio 1
	v_mfma_f32_16x16x32_bf16 v[128:131], v[148:151], v[164:167], v[128:131]
	v_mfma_f32_16x16x32_bf16 v[124:127], v[156:159], v[164:167], v[124:127]
	v_mfma_f32_16x16x32_bf16 v[120:123], v[148:151], v[172:175], v[120:123]
	v_mfma_f32_16x16x32_bf16 v[116:119], v[156:159], v[172:175], v[116:119]
	v_mfma_f32_16x16x32_bf16 v[96:99], v[148:151], v[190:193], v[96:99]
	v_mfma_f32_16x16x32_bf16 v[92:95], v[156:159], v[190:193], v[92:95]
	v_mfma_f32_16x16x32_bf16 v[88:91], v[148:151], v[198:201], v[88:91]
	v_mfma_f32_16x16x32_bf16 v[84:87], v[156:159], v[198:201], v[84:87]
	v_mfma_f32_16x16x32_bf16 v[128:131], v[152:155], v[168:171], v[128:131]
	v_mfma_f32_16x16x32_bf16 v[124:127], v[160:163], v[168:171], v[124:127]
	v_mfma_f32_16x16x32_bf16 v[120:123], v[152:155], v[176:179], v[120:123]
	v_mfma_f32_16x16x32_bf16 v[116:119], v[160:163], v[176:179], v[116:119]
	v_mfma_f32_16x16x32_bf16 v[96:99], v[152:155], v[194:197], v[96:99]
	v_mfma_f32_16x16x32_bf16 v[92:95], v[160:163], v[194:197], v[92:95]
	v_mfma_f32_16x16x32_bf16 v[88:91], v[152:155], v[202:205], v[88:91]
	v_mfma_f32_16x16x32_bf16 v[84:87], v[160:163], v[202:205], v[84:87]
	s_setprio 0
	s_barrier
;     __device__ __forceinline__ void operator()(const f32x4 (&acc)[2][2][4][2], const Unit& u, int wr, int wc, int fr, int fq) const {
;         const int row0 = u.pm * BM + wr * 64 + fr; const int col0 = u.pn * BM + wc * 32 + 8 * fq;
;         const float* gp = gate + (size_t)((u.pm * BM) >> 12) * gstride + col0;
;         f32x4 gv[2][2];
; #pragma unroll
;         for (int bj = 0; bj < 2; ++bj)
; #pragma unroll
;             for (int n = 0; n < 2; ++n) gv[bj][n] = *(const f32x4*)(gp + bj * HALF + n * 4);
;         if (base_f32) { const float* bp = (const float*)base;
; #pragma unroll
;             for (int ai = 0; ai < 2; ++ai)
; #pragma unroll
;                 for (int m2 = 0; m2 < 2; ++m2) { f32x4 bs[2][2][2];
; #pragma unroll
;                     for (int mm = 0; mm < 2; ++mm) { const size_t off = (size_t)(row0 + ai * HALF + (2 * m2 + mm) * 16) * ldc + col0;
; #pragma unroll
;                         for (int bj = 0; bj < 2; ++bj)
; #pragma unroll
;                             for (int n = 0; n < 2; ++n) bs[mm][bj][n] = *(const f32x4*)(bp + off + bj * HALF + n * 4); }
; #pragma unroll
;                     for (int mm = 0; mm < 2; ++mm) { const size_t off = (size_t)(row0 + ai * HALF + (2 * m2 + mm) * 16) * ldc + col0;
; #pragma unroll
;                         for (int bj = 0; bj < 2; ++bj) { const f32x4 v0 = bs[mm][bj][0] + gv[bj][0] * acc[ai][bj][2 * m2 + mm][0], v1 = bs[mm][bj][1] + gv[bj][1] * acc[ai][bj][2 * m2 + mm][1];
;                             u32x4 w; w.x = cvt_pk_bf16(v0[0], v0[1]); w.y = cvt_pk_bf16(v0[2], v0[3]); w.z = cvt_pk_bf16(v1[0], v1[1]); w.w = cvt_pk_bf16(v1[2], v1[3]);
;                             *(u32x4*)(out + off + bj * HALF) = w; } }
;                     asm volatile("" ::: "memory"); }
;         } else { const bf16_t* bp = (const bf16_t*)base;
; #pragma unroll
;             for (int ai = 0; ai < 2; ++ai) { u32x4 bs[4][2];
; #pragma unroll
; template <class Epi, class Sched, bool ALIGN_EPI = false, bool SP2 = false>
; __device__ __forceinline__ void gemm_phase(PG8_LAS unsigned char* lds, const Gemm g, const Sched& S, const Epi& E) {
;     ...
;             PG8_LDA(At, 1, 1); PG8_STAGE(PG8_SB(1, 0), b3, voffB); PG8_STAGE(PG8_SB(1, 1), b3 + hstep, voffB); PG8_STAGE(PG8_SA(1, 0), a3, voffA);
;             PG8_WAIT_V(8); PG8_WAIT_L(0); PG8_BAR; PG8_MMA(1, 0, At, B0); PG8_MMA(1, 1, At, B1); PG8_BAR; PG8_SCHED;
	s_add_i32 s30, s60, s9
	v_lshl_add_u64 v[206:207], v[206:207], 0, s[28:29]
	s_mov_b32 m0, s30
	ds_read_b128 v[164:167], v218 offset:49152
	ds_read_b128 v[168:171], v218 offset:50176
	ds_read_b128 v[172:175], v218 offset:51200
	ds_read_b128 v[176:179], v218 offset:52224
	ds_read_b128 v[190:193], v218 offset:53248
	ds_read_b128 v[194:197], v218 offset:54272
	ds_read_b128 v[198:201], v218 offset:55296
	ds_read_b128 v[202:205], v218 offset:56320
	global_load_lds_dwordx4 v[206:207], off
	s_add_i32 m0, s30, 0x2000
	s_add_u32 s20, s20, 0x80080
	v_lshl_add_u64 v[206:207], v[208:209], 0, s[28:29]
	s_addc_u32 s21, s21, 0
	s_add_i32 s30, s61, s9
	global_load_lds_dwordx4 v[206:207], off
	s_mov_b32 m0, s30
	s_nop 0
	global_load_lds_dwordx4 v2, s[20:21]
	s_add_i32 m0, s30, 0x2000
	s_nop 0
	global_load_lds_dwordx4 v184, s[20:21]
	v_lshl_add_u64 v[206:207], v[210:211], 0, s[28:29]
	s_mov_b32 m0, s54
	s_nop 0
	global_load_lds_dwordx4 v[206:207], off
	v_lshl_add_u64 v[206:207], v[214:215], 0, s[28:29]
	s_mov_b32 m0, s55
	s_nop 0
	global_load_lds_dwordx4 v[206:207], off
	s_waitcnt vmcnt(8)
	s_waitcnt lgkmcnt(0)
	s_barrier
	s_setprio 1
	s_waitcnt lgkmcnt(0)
	v_mfma_f32_16x16x32_bf16 v[72:75], v[60:63], v[164:167], v[72:75]
	v_mfma_f32_16x16x32_bf16 v[68:71], v[76:79], v[164:167], v[68:71]
	v_mfma_f32_16x16x32_bf16 v[56:59], v[60:63], v[172:175], v[56:59]
	v_mfma_f32_16x16x32_bf16 v[52:55], v[76:79], v[172:175], v[52:55]
	v_mfma_f32_16x16x32_bf16 v[32:35], v[60:63], v[190:193], v[32:35]
	v_mfma_f32_16x16x32_bf16 v[28:31], v[76:79], v[190:193], v[28:31]
	v_mfma_f32_16x16x32_bf16 v[24:27], v[60:63], v[198:201], v[24:27]
	v_mfma_f32_16x16x32_bf16 v[20:23], v[76:79], v[198:201], v[20:23]
	v_mfma_f32_16x16x32_bf16 v[72:75], v[64:67], v[168:171], v[72:75]
	v_mfma_f32_16x16x32_bf16 v[68:71], v[80:83], v[168:171], v[68:71]
	v_mfma_f32_16x16x32_bf16 v[56:59], v[64:67], v[176:179], v[56:59]
	v_mfma_f32_16x16x32_bf16 v[52:55], v[80:83], v[176:179], v[52:55]
	v_mfma_f32_16x16x32_bf16 v[32:35], v[64:67], v[194:197], v[32:35]
	v_mfma_f32_16x16x32_bf16 v[28:31], v[80:83], v[194:197], v[28:31]
	v_mfma_f32_16x16x32_bf16 v[24:27], v[64:67], v[202:205], v[24:27]
	v_mfma_f32_16x16x32_bf16 v[20:23], v[80:83], v[202:205], v[20:23]
	s_setprio 0
	s_setprio 1
	v_mfma_f32_16x16x32_bf16 v[48:51], v[148:151], v[164:167], v[48:51]
	v_mfma_f32_16x16x32_bf16 v[44:47], v[156:159], v[164:167], v[44:47]
	v_mfma_f32_16x16x32_bf16 v[40:43], v[148:151], v[172:175], v[40:43]
	v_mfma_f32_16x16x32_bf16 v[36:39], v[156:159], v[172:175], v[36:39]
	v_mfma_f32_16x16x32_bf16 v[16:19], v[148:151], v[190:193], v[16:19]
	v_mfma_f32_16x16x32_bf16 v[12:15], v[156:159], v[190:193], v[12:15]
	v_mfma_f32_16x16x32_bf16 v[8:11], v[148:151], v[198:201], v[8:11]
	v_mfma_f32_16x16x32_bf16 v[4:7], v[156:159], v[198:201], v[4:7]
	v_mfma_f32_16x16x32_bf16 v[48:51], v[152:155], v[168:171], v[48:51]
	v_mfma_f32_16x16x32_bf16 v[44:47], v[160:163], v[168:171], v[44:47]
	v_mfma_f32_16x16x32_bf16 v[40:43], v[152:155], v[176:179], v[40:43]
	v_mfma_f32_16x16x32_bf16 v[36:39], v[160:163], v[176:179], v[36:39]
	v_mfma_f32_16x16x32_bf16 v[16:19], v[152:155], v[194:197], v[16:19]
	v_mfma_f32_16x16x32_bf16 v[12:15], v[160:163], v[194:197], v[12:15]
	v_mfma_f32_16x16x32_bf16 v[8:11], v[152:155], v[202:205], v[8:11]
	v_mfma_f32_16x16x32_bf16 v[4:7], v[160:163], v[202:205], v[4:7]
	s_setprio 0
	s_barrier
	s_add_i32 s59, s59, 2
	s_add_u32 s33, s33, 0x100
	s_addc_u32 s58, s58, 0
	s_add_u32 s44, s44, 0x100
	s_addc_u32 s45, s45, 0
	s_cmp_gt_u32 s59, 29
	s_cbranch_scc0 .LBB0_2046
	v_lshl_or_b32 v202, s4, 8, v213
	s_ashr_i32 s4, s42, 4
	s_mul_hi_i32 s13, s4, 0xc000
	s_mul_i32 s4, s4, 0xc000
	s_add_u32 s12, s18, s4
	s_addc_u32 s13, s53, s13
	v_ashrrev_i32_e32 v203, 31, v202
	v_lshl_add_u64 v[60:61], v[202:203], 2, s[12:13]
	flat_load_dwordx4 v[80:83], v[60:61]
	flat_load_dwordx4 v[76:79], v[60:61] offset:16
	flat_load_dwordx4 v[64:67], v[60:61] offset:512
	s_nop 0
	flat_load_dwordx4 v[60:63], v[60:61] offset:528
	v_lshl_add_u32 v192, s42, 8, v1
	v_ashrrev_i32_e32 v193, 31, v192
	v_or_b32_e32 v198, 16, v192
	v_or_b32_e32 v196, 32, v192
	v_or_b32_e32 v194, 48, v192
	v_lshlrev_b64 v[200:201], 11, v[192:193]
	s_and_b64 vcc, exec, s[16:17]
	v_lshlrev_b64 v[190:191], 1, v[202:203]
	v_ashrrev_i32_e32 v199, 31, v198
	v_ashrrev_i32_e32 v197, 31, v196
	v_ashrrev_i32_e32 v195, 31, v194
	s_cbranch_vccz .LBB0_2049
; __device__ __forceinline__ unsigned cvt_pk_bf16(float lo, float hi) { unsigned r; asm volatile("v_cvt_pk_bf16_f32 %0, %1, %2" : "=v"(r) : "v"(lo), "v"(hi)); return r; }
;     __device__ __forceinline__ void operator()(const f32x4 (&acc)[2][2][4][2], const Unit& u, int wr, int wc, int fr, int fq) const {
;     ...
;             for (int ai = 0; ai < 2; ++ai) { u32x4 bs[4][2];
; #pragma unroll
;                 for (int m = 0; m < 4; ++m) { const size_t off = (size_t)(row0 + ai * HALF + m * 16) * ldc + col0;
; #pragma unroll
;                     for (int bj = 0; bj < 2; ++bj) bs[m][bj] = *(const u32x4*)(bp + off + bj * HALF); }
; #pragma unroll
;                 for (int m = 0; m < 4; ++m) { const size_t off = (size_t)(row0 + ai * HALF + m * 16) * ldc + col0;
; #pragma unroll
;                     for (int bj = 0; bj < 2; ++bj) { const u32x4 r = bs[m][bj]; const f32x4 a0 = acc[ai][bj][m][0], a1 = acc[ai][bj][m][1];
;                         u32x4 w;
;                         w.x = cvt_pk_bf16(__builtin_bit_cast(float, r.x << 16) + gv[bj][0][0] * a0[0], __builtin_bit_cast(float, r.x & 0xffff0000u) + gv[bj][0][1] * a0[1]);
;                         w.y = cvt_pk_bf16(__builtin_bit_cast(float, r.y << 16) + gv[bj][0][2] * a0[2], __builtin_bit_cast(float, r.y & 0xffff0000u) + gv[bj][0][3] * a0[3]);
;                         w.z = cvt_pk_bf16(__builtin_bit_cast(float, r.z << 16) + gv[bj][1][0] * a1[0], __builtin_bit_cast(float, r.z & 0xffff0000u) + gv[bj][1][1] * a1[1]);
;                         w.w = cvt_pk_bf16(__builtin_bit_cast(float, r.w << 16) + gv[bj][1][2] * a1[2], __builtin_bit_cast(float, r.w & 0xffff0000u) + gv[bj][1][3] * a1[3]);
;                         *(u32x4*)(out + off + bj * HALF) = w; } }
	v_lshl_add_u64 v[204:205], s[26:27], 0, v[190:191]
	v_lshlrev_b64 v[156:157], 1, v[200:201]
	v_lshl_add_u64 v[148:149], v[204:205], 0, v[156:157]
	v_lshlrev_b64 v[152:153], 12, v[198:199]
	flat_load_dwordx4 v[172:175], v[148:149]
	flat_load_dwordx4 v[168:171], v[148:149] offset:256
	v_lshl_add_u64 v[148:149], v[204:205], 0, v[152:153]
	flat_load_dwordx4 v[164:167], v[148:149]
	s_nop 0
	flat_load_dwordx4 v[148:151], v[148:149] offset:256
	v_lshlrev_b64 v[208:209], 12, v[196:197]
	v_lshlrev_b64 v[206:207], 12, v[194:195]
	v_lshl_add_u64 v[154:155], v[204:205], 0, v[208:209]
	v_lshl_add_u64 v[210:211], v[204:205], 0, v[206:207]
	v_lshl_add_u64 v[214:215], s[14:15], 0, v[156:157]
	v_lshl_add_u64 v[216:217], s[14:15], 0, v[152:153]
	flat_load_dwordx4 v[176:179], v[154:155]
	flat_load_dwordx4 v[160:163], v[154:155] offset:256
	flat_load_dwordx4 v[156:159], v[210:211]
	s_nop 0
	flat_load_dwordx4 v[152:155], v[210:211] offset:256
	v_lshl_add_u64 v[210:211], v[216:217], 0, v[190:191]
	v_lshl_add_u64 v[214:215], v[214:215], 0, v[190:191]
	s_mov_b64 s[12:13], 0x80000
	s_waitcnt vmcnt(0) lgkmcnt(0)
	v_lshlrev_b32_e32 v216, 16, v172
	v_and_b32_e32 v172, 0xffff0000, v172
	v_lshlrev_b32_e32 v217, 16, v173
	v_and_b32_e32 v173, 0xffff0000, v173
	v_lshlrev_b32_e32 v219, 16, v174
	v_and_b32_e32 v174, 0xffff0000, v174
	v_lshlrev_b32_e32 v220, 16, v175
	v_and_b32_e32 v175, 0xffff0000, v175
	v_lshlrev_b32_e32 v221, 16, v168
	v_and_b32_e32 v168, 0xffff0000, v168
	v_lshlrev_b32_e32 v225, 16, v164
	v_and_b32_e32 v226, 0xffff0000, v164
	v_fmac_f32_e32 v216, v144, v80
	v_fmac_f32_e32 v172, v145, v81
	v_cvt_pk_bf16_f32 v164, v216, v172
	v_lshlrev_b32_e32 v222, 16, v169
	v_and_b32_e32 v169, 0xffff0000, v169
	v_lshlrev_b32_e32 v223, 16, v170
	v_and_b32_e32 v170, 0xffff0000, v170
	v_lshlrev_b32_e32 v224, 16, v171
	v_and_b32_e32 v171, 0xffff0000, v171
	v_lshlrev_b32_e32 v227, 16, v165
	v_and_b32_e32 v229, 0xffff0000, v165
	v_lshlrev_b32_e32 v232, 16, v166
	v_and_b32_e32 v233, 0xffff0000, v166
	v_lshlrev_b32_e32 v240, 16, v167
	v_and_b32_e32 v241, 0xffff0000, v167
	v_fmac_f32_e32 v217, v146, v82
	v_fmac_f32_e32 v173, v147, v83
	v_fmac_f32_e32 v219, v140, v76
	v_fmac_f32_e32 v174, v141, v77
	v_fmac_f32_e32 v220, v142, v78
	v_fmac_f32_e32 v175, v143, v79
	v_fmac_f32_e32 v221, v128, v64
	v_fmac_f32_e32 v168, v129, v65
	v_cvt_pk_bf16_f32 v165, v217, v173
	v_cvt_pk_bf16_f32 v166, v219, v174
	v_cvt_pk_bf16_f32 v167, v220, v175
	flat_store_dwordx4 v[214:215], v[164:167]
	v_fmac_f32_e32 v222, v130, v66
	v_fmac_f32_e32 v169, v131, v67
	v_cvt_pk_bf16_f32 v164, v221, v168
	v_fmac_f32_e32 v223, v124, v60
	v_fmac_f32_e32 v170, v125, v61
	v_fmac_f32_e32 v224, v126, v62
	v_fmac_f32_e32 v171, v127, v63
	v_fmac_f32_e32 v225, v136, v80
	v_fmac_f32_e32 v226, v137, v81
	v_cvt_pk_bf16_f32 v165, v222, v169
	v_cvt_pk_bf16_f32 v166, v223, v170
	v_cvt_pk_bf16_f32 v167, v224, v171
	flat_store_dwordx4 v[214:215], v[164:167] offset:256
	v_lshlrev_b32_e32 v242, 16, v148
	v_and_b32_e32 v148, 0xffff0000, v148
	v_cvt_pk_bf16_f32 v164, v225, v226
	v_fmac_f32_e32 v227, v138, v82
	v_fmac_f32_e32 v229, v139, v83
	v_fmac_f32_e32 v232, v132, v76
	v_fmac_f32_e32 v233, v133, v77
	v_fmac_f32_e32 v240, v134, v78
	v_fmac_f32_e32 v241, v135, v79
	v_cvt_pk_bf16_f32 v165, v227, v229
	v_cvt_pk_bf16_f32 v166, v232, v233
	v_cvt_pk_bf16_f32 v167, v240, v241
	flat_store_dwordx4 v[210:211], v[164:167]
	v_fmac_f32_e32 v148, v121, v65
	v_fmac_f32_e32 v242, v120, v64
	v_lshlrev_b32_e32 v164, 16, v149
	v_and_b32_e32 v149, 0xffff0000, v149
	v_fmac_f32_e32 v164, v122, v66
	v_fmac_f32_e32 v149, v123, v67
	v_cvt_pk_bf16_f32 v148, v242, v148
	v_cvt_pk_bf16_f32 v149, v164, v149
	v_lshlrev_b32_e32 v164, 16, v150
	v_and_b32_e32 v150, 0xffff0000, v150
	v_fmac_f32_e32 v164, v116, v60
	v_fmac_f32_e32 v150, v117, v61
	v_cvt_pk_bf16_f32 v150, v164, v150
	v_lshlrev_b32_e32 v164, 16, v151
	v_and_b32_e32 v151, 0xffff0000, v151
	v_fmac_f32_e32 v151, v119, v63
	v_fmac_f32_e32 v164, v118, v62
	v_cvt_pk_bf16_f32 v151, v164, v151
	flat_store_dwordx4 v[210:211], v[148:151] offset:256
	v_and_b32_e32 v164, 0xffff0000, v179
	v_fmac_f32_e32 v164, v111, v79
	v_lshlrev_b32_e32 v148, 16, v176
	v_and_b32_e32 v149, 0xffff0000, v176
	v_fmac_f32_e32 v148, v112, v80
	v_fmac_f32_e32 v149, v113, v81
	v_cvt_pk_bf16_f32 v148, v148, v149
	v_lshlrev_b32_e32 v149, 16, v177
	v_and_b32_e32 v150, 0xffff0000, v177
	v_fmac_f32_e32 v149, v114, v82
	v_fmac_f32_e32 v150, v115, v83
	v_cvt_pk_bf16_f32 v149, v149, v150
	v_lshlrev_b32_e32 v150, 16, v178
	v_and_b32_e32 v151, 0xffff0000, v178
	v_fmac_f32_e32 v150, v108, v76
	v_fmac_f32_e32 v151, v109, v77
	v_cvt_pk_bf16_f32 v150, v150, v151
	v_lshlrev_b32_e32 v151, 16, v179
	v_fmac_f32_e32 v151, v110, v78
	v_cvt_pk_bf16_f32 v151, v151, v164
	v_lshl_add_u64 v[164:165], s[14:15], 0, v[208:209]
	v_lshl_add_u64 v[164:165], v[164:165], 0, v[190:191]
	flat_store_dwordx4 v[164:165], v[148:151]
	s_nop 1
	v_lshlrev_b32_e32 v148, 16, v160
	v_and_b32_e32 v149, 0xffff0000, v160
	v_fmac_f32_e32 v148, v96, v64
	v_fmac_f32_e32 v149, v97, v65
	v_cvt_pk_bf16_f32 v148, v148, v149
	v_lshlrev_b32_e32 v149, 16, v161
	v_and_b32_e32 v150, 0xffff0000, v161
	v_fmac_f32_e32 v149, v98, v66
	v_fmac_f32_e32 v150, v99, v67
	v_cvt_pk_bf16_f32 v149, v149, v150
	v_lshlrev_b32_e32 v150, 16, v162
	v_and_b32_e32 v151, 0xffff0000, v162
	v_fmac_f32_e32 v150, v92, v60
	v_fmac_f32_e32 v151, v93, v61
	v_cvt_pk_bf16_f32 v150, v150, v151
	v_lshlrev_b32_e32 v151, 16, v163
	v_fmac_f32_e32 v151, v94, v62
	v_and_b32_e32 v160, 0xffff0000, v163
	v_fmac_f32_e32 v160, v95, v63
	v_cvt_pk_bf16_f32 v151, v151, v160
	flat_store_dwordx4 v[164:165], v[148:151] offset:256
	s_nop 1
; __device__ __forceinline__ unsigned cvt_pk_bf16(float lo, float hi) { unsigned r; asm volatile("v_cvt_pk_bf16_f32 %0, %1, %2" : "=v"(r) : "v"(lo), "v"(hi)); return r; }
;     __device__ __forceinline__ void operator()(const f32x4 (&acc)[2][2][4][2], const Unit& u, int wr, int wc, int fr, int fq) const {
;     ...
;             for (int ai = 0; ai < 2; ++ai) { u32x4 bs[4][2];
; #pragma unroll
;                 for (int m = 0; m < 4; ++m) { const size_t off = (size_t)(row0 + ai * HALF + m * 16) * ldc + col0;
; #pragma unroll
;                     for (int bj = 0; bj < 2; ++bj) bs[m][bj] = *(const u32x4*)(bp + off + bj * HALF); }
; #pragma unroll
;                 for (int m = 0; m < 4; ++m) { const size_t off = (size_t)(row0 + ai * HALF + m * 16) * ldc + col0;
; #pragma unroll
;                     for (int bj = 0; bj < 2; ++bj) { const u32x4 r = bs[m][bj]; const f32x4 a0 = acc[ai][bj][m][0], a1 = acc[ai][bj][m][1];
;                         u32x4 w;
;                         w.x = cvt_pk_bf16(__builtin_bit_cast(float, r.x << 16) + gv[bj][0][0] * a0[0], __builtin_bit_cast(float, r.x & 0xffff0000u) + gv[bj][0][1] * a0[1]);
;                         w.y = cvt_pk_bf16(__builtin_bit_cast(float, r.y << 16) + gv[bj][0][2] * a0[2], __builtin_bit_cast(float, r.y & 0xffff0000u) + gv[bj][0][3] * a0[3]);
;                         w.z = cvt_pk_bf16(__builtin_bit_cast(float, r.z << 16) + gv[bj][1][0] * a1[0], __builtin_bit_cast(float, r.z & 0xffff0000u) + gv[bj][1][1] * a1[1]);
;                         w.w = cvt_pk_bf16(__builtin_bit_cast(float, r.w << 16) + gv[bj][1][2] * a1[2], __builtin_bit_cast(float, r.w & 0xffff0000u) + gv[bj][1][3] * a1[3]);
;                         *(u32x4*)(out + off + bj * HALF) = w; } }
	v_lshlrev_b32_e32 v148, 16, v156
	v_and_b32_e32 v149, 0xffff0000, v156
	v_fmac_f32_e32 v148, v104, v80
	v_fmac_f32_e32 v149, v105, v81
	v_cvt_pk_bf16_f32 v148, v148, v149
	v_lshlrev_b32_e32 v149, 16, v157
	v_and_b32_e32 v150, 0xffff0000, v157
	v_fmac_f32_e32 v149, v106, v82
	v_fmac_f32_e32 v150, v107, v83
	v_cvt_pk_bf16_f32 v149, v149, v150
	v_lshlrev_b32_e32 v150, 16, v158
	v_and_b32_e32 v151, 0xffff0000, v158
	v_fmac_f32_e32 v150, v100, v76
	v_fmac_f32_e32 v151, v101, v77
	v_cvt_pk_bf16_f32 v150, v150, v151
	v_lshlrev_b32_e32 v151, 16, v159
	v_and_b32_e32 v156, 0xffff0000, v159
	v_fmac_f32_e32 v151, v102, v78
	v_fmac_f32_e32 v156, v103, v79
	v_cvt_pk_bf16_f32 v151, v151, v156
	v_lshl_add_u64 v[156:157], s[14:15], 0, v[206:207]
	v_lshl_add_u64 v[156:157], v[156:157], 0, v[190:191]
	flat_store_dwordx4 v[156:157], v[148:151]
	s_nop 1
	v_lshlrev_b32_e32 v148, 16, v152
	v_and_b32_e32 v149, 0xffff0000, v152
	v_fmac_f32_e32 v148, v88, v64
	v_fmac_f32_e32 v149, v89, v65
	v_cvt_pk_bf16_f32 v148, v148, v149
	v_lshlrev_b32_e32 v149, 16, v153
	v_and_b32_e32 v150, 0xffff0000, v153
	v_fmac_f32_e32 v149, v90, v66
	v_fmac_f32_e32 v150, v91, v67
	v_cvt_pk_bf16_f32 v149, v149, v150
	v_lshlrev_b32_e32 v150, 16, v154
	v_and_b32_e32 v151, 0xffff0000, v154
	v_fmac_f32_e32 v150, v84, v60
	v_fmac_f32_e32 v151, v85, v61
	v_cvt_pk_bf16_f32 v150, v150, v151
	v_lshlrev_b32_e32 v151, 16, v155
	v_fmac_f32_e32 v151, v86, v62
	v_and_b32_e32 v152, 0xffff0000, v155
	v_fmac_f32_e32 v152, v87, v63
	v_cvt_pk_bf16_f32 v151, v151, v152
	flat_store_dwordx4 v[156:157], v[148:151] offset:256
	s_nop 1
	v_lshlrev_b64 v[148:149], 12, v[192:193]
	v_lshl_add_u64 v[206:207], v[148:149], 0, s[12:13]
	v_lshl_add_u64 v[150:151], v[204:205], 0, v[206:207]
	flat_load_dwordx4 v[152:155], v[150:151]
	flat_load_dwordx4 v[156:159], v[150:151] offset:256
	s_mov_b64 s[12:13], 0x90000
	v_lshl_add_u64 v[208:209], v[148:149], 0, s[12:13]
	v_lshl_add_u64 v[150:151], v[204:205], 0, v[208:209]
	flat_load_dwordx4 v[160:163], v[150:151]
	flat_load_dwordx4 v[164:167], v[150:151] offset:256
	s_mov_b64 s[12:13], 0xa0000
	v_lshl_add_u64 v[210:211], v[148:149], 0, s[12:13]
	v_lshl_add_u64 v[150:151], v[204:205], 0, v[210:211]
	flat_load_dwordx4 v[168:171], v[150:151]
	flat_load_dwordx4 v[172:175], v[150:151] offset:256
	s_mov_b64 s[12:13], 0xb0000
	v_lshl_add_u64 v[214:215], v[148:149], 0, s[12:13]
	v_lshl_add_u64 v[148:149], v[204:205], 0, v[214:215]
	flat_load_dwordx4 v[176:179], v[148:149]
	s_nop 0
	flat_load_dwordx4 v[148:151], v[148:149] offset:256
	v_lshl_add_u64 v[204:205], s[14:15], 0, v[206:207]
	v_lshl_add_u64 v[204:205], v[204:205], 0, v[190:191]
	s_waitcnt vmcnt(0) lgkmcnt(0)
; __device__ __forceinline__ unsigned cvt_pk_bf16(float lo, float hi) { unsigned r; asm volatile("v_cvt_pk_bf16_f32 %0, %1, %2" : "=v"(r) : "v"(lo), "v"(hi)); return r; }
;     __device__ __forceinline__ void operator()(const f32x4 (&acc)[2][2][4][2], const Unit& u, int wr, int wc, int fr, int fq) const {
;     ...
;                 for (int m = 0; m < 4; ++m) { const size_t off = (size_t)(row0 + ai * HALF + m * 16) * ldc + col0;
; #pragma unroll
;                     for (int bj = 0; bj < 2; ++bj) { const u32x4 r = bs[m][bj]; const f32x4 a0 = acc[ai][bj][m][0], a1 = acc[ai][bj][m][1];
;                         u32x4 w;
;                         w.x = cvt_pk_bf16(__builtin_bit_cast(float, r.x << 16) + gv[bj][0][0] * a0[0], __builtin_bit_cast(float, r.x & 0xffff0000u) + gv[bj][0][1] * a0[1]);
;                         w.y = cvt_pk_bf16(__builtin_bit_cast(float, r.y << 16) + gv[bj][0][2] * a0[2], __builtin_bit_cast(float, r.y & 0xffff0000u) + gv[bj][0][3] * a0[3]);
;                         w.z = cvt_pk_bf16(__builtin_bit_cast(float, r.z << 16) + gv[bj][1][0] * a1[0], __builtin_bit_cast(float, r.z & 0xffff0000u) + gv[bj][1][1] * a1[1]);
;                         w.w = cvt_pk_bf16(__builtin_bit_cast(float, r.w << 16) + gv[bj][1][2] * a1[2], __builtin_bit_cast(float, r.w & 0xffff0000u) + gv[bj][1][3] * a1[3]);
;                         *(u32x4*)(out + off + bj * HALF) = w; } }
	v_lshlrev_b32_e32 v193, 16, v152
	v_and_b32_e32 v152, 0xffff0000, v152
	v_fmac_f32_e32 v193, v72, v80
	v_fmac_f32_e32 v152, v73, v81
	v_cvt_pk_bf16_f32 v152, v193, v152
	v_lshlrev_b32_e32 v193, 16, v153
	v_and_b32_e32 v153, 0xffff0000, v153
	v_fmac_f32_e32 v193, v74, v82
	v_fmac_f32_e32 v153, v75, v83
	v_cvt_pk_bf16_f32 v153, v193, v153
	v_lshlrev_b32_e32 v193, 16, v154
	v_and_b32_e32 v154, 0xffff0000, v154
	v_fmac_f32_e32 v193, v68, v76
	v_fmac_f32_e32 v154, v69, v77
	v_cvt_pk_bf16_f32 v154, v193, v154
	v_lshlrev_b32_e32 v193, 16, v155
	v_and_b32_e32 v155, 0xffff0000, v155
	v_fmac_f32_e32 v155, v71, v79
	v_fmac_f32_e32 v193, v70, v78
	v_cvt_pk_bf16_f32 v155, v193, v155
	flat_store_dwordx4 v[204:205], v[152:155]
	s_nop 1
	v_lshlrev_b32_e32 v152, 16, v156
	v_and_b32_e32 v153, 0xffff0000, v156
	v_fmac_f32_e32 v152, v48, v64
	v_fmac_f32_e32 v153, v49, v65
	v_cvt_pk_bf16_f32 v152, v152, v153
	v_lshlrev_b32_e32 v153, 16, v157
	v_and_b32_e32 v154, 0xffff0000, v157
	v_fmac_f32_e32 v153, v50, v66
	v_fmac_f32_e32 v154, v51, v67
	v_cvt_pk_bf16_f32 v153, v153, v154
	v_lshlrev_b32_e32 v154, 16, v158
	v_and_b32_e32 v155, 0xffff0000, v158
	v_fmac_f32_e32 v154, v44, v60
	v_fmac_f32_e32 v155, v45, v61
	v_cvt_pk_bf16_f32 v154, v154, v155
	v_lshlrev_b32_e32 v155, 16, v159
	v_fmac_f32_e32 v155, v46, v62
	v_and_b32_e32 v156, 0xffff0000, v159
	v_fmac_f32_e32 v156, v47, v63
	v_cvt_pk_bf16_f32 v155, v155, v156
	flat_store_dwordx4 v[204:205], v[152:155] offset:256
	v_and_b32_e32 v156, 0xffff0000, v163
	v_fmac_f32_e32 v156, v55, v79
	v_lshlrev_b32_e32 v152, 16, v160
	v_and_b32_e32 v153, 0xffff0000, v160
	v_fmac_f32_e32 v152, v56, v80
	v_fmac_f32_e32 v153, v57, v81
	v_cvt_pk_bf16_f32 v152, v152, v153
	v_lshlrev_b32_e32 v153, 16, v161
	v_and_b32_e32 v154, 0xffff0000, v161
	v_fmac_f32_e32 v153, v58, v82
	v_fmac_f32_e32 v154, v59, v83
	v_cvt_pk_bf16_f32 v153, v153, v154
	v_lshlrev_b32_e32 v154, 16, v162
	v_and_b32_e32 v155, 0xffff0000, v162
	v_fmac_f32_e32 v154, v52, v76
	v_fmac_f32_e32 v155, v53, v77
	v_cvt_pk_bf16_f32 v154, v154, v155
	v_lshlrev_b32_e32 v155, 16, v163
	v_fmac_f32_e32 v155, v54, v78
	v_cvt_pk_bf16_f32 v155, v155, v156
	v_lshl_add_u64 v[156:157], s[14:15], 0, v[208:209]
	v_lshl_add_u64 v[156:157], v[156:157], 0, v[190:191]
	flat_store_dwordx4 v[156:157], v[152:155]
	v_and_b32_e32 v158, 0xffff0000, v167
	v_fmac_f32_e32 v158, v39, v63
	v_lshlrev_b32_e32 v152, 16, v164
	v_and_b32_e32 v153, 0xffff0000, v164
	v_fmac_f32_e32 v152, v40, v64
	v_fmac_f32_e32 v153, v41, v65
	v_cvt_pk_bf16_f32 v152, v152, v153
	v_lshlrev_b32_e32 v153, 16, v165
	v_and_b32_e32 v154, 0xffff0000, v165
	v_fmac_f32_e32 v153, v42, v66
	v_fmac_f32_e32 v154, v43, v67
	v_cvt_pk_bf16_f32 v153, v153, v154
	v_lshlrev_b32_e32 v154, 16, v166
	v_and_b32_e32 v155, 0xffff0000, v166
	v_fmac_f32_e32 v154, v36, v60
	v_fmac_f32_e32 v155, v37, v61
	v_cvt_pk_bf16_f32 v154, v154, v155
	v_lshlrev_b32_e32 v155, 16, v167
	v_fmac_f32_e32 v155, v38, v62
	v_cvt_pk_bf16_f32 v155, v155, v158
	flat_store_dwordx4 v[156:157], v[152:155] offset:256
	v_and_b32_e32 v156, 0xffff0000, v171
	v_fmac_f32_e32 v156, v31, v79
	v_lshlrev_b32_e32 v152, 16, v168
	v_and_b32_e32 v153, 0xffff0000, v168
	v_fmac_f32_e32 v152, v32, v80
	v_fmac_f32_e32 v153, v33, v81
	v_cvt_pk_bf16_f32 v152, v152, v153
	v_lshlrev_b32_e32 v153, 16, v169
	v_and_b32_e32 v154, 0xffff0000, v169
	v_fmac_f32_e32 v153, v34, v82
	v_fmac_f32_e32 v154, v35, v83
	v_cvt_pk_bf16_f32 v153, v153, v154
	v_lshlrev_b32_e32 v154, 16, v170
	v_and_b32_e32 v155, 0xffff0000, v170
	v_fmac_f32_e32 v154, v28, v76
	v_fmac_f32_e32 v155, v29, v77
	v_cvt_pk_bf16_f32 v154, v154, v155
	v_lshlrev_b32_e32 v155, 16, v171
	v_fmac_f32_e32 v155, v30, v78
	v_cvt_pk_bf16_f32 v155, v155, v156
	v_lshl_add_u64 v[156:157], s[14:15], 0, v[210:211]
	v_lshl_add_u64 v[156:157], v[156:157], 0, v[190:191]
	flat_store_dwordx4 v[156:157], v[152:155]
	v_and_b32_e32 v158, 0xffff0000, v175
	v_fmac_f32_e32 v158, v15, v63
	v_lshlrev_b32_e32 v152, 16, v172
	v_and_b32_e32 v153, 0xffff0000, v172
	v_fmac_f32_e32 v152, v16, v64
	v_fmac_f32_e32 v153, v17, v65
	v_cvt_pk_bf16_f32 v152, v152, v153
	v_lshlrev_b32_e32 v153, 16, v173
	v_and_b32_e32 v154, 0xffff0000, v173
	v_fmac_f32_e32 v153, v18, v66
	v_fmac_f32_e32 v154, v19, v67
	v_cvt_pk_bf16_f32 v153, v153, v154
	v_lshlrev_b32_e32 v154, 16, v174
	v_and_b32_e32 v155, 0xffff0000, v174
	v_fmac_f32_e32 v154, v12, v60
	v_fmac_f32_e32 v155, v13, v61
	v_cvt_pk_bf16_f32 v154, v154, v155
	v_lshlrev_b32_e32 v155, 16, v175
	v_fmac_f32_e32 v155, v14, v62
	v_cvt_pk_bf16_f32 v155, v155, v158
	flat_store_dwordx4 v[156:157], v[152:155] offset:256
	v_and_b32_e32 v156, 0xffff0000, v179
	v_fmac_f32_e32 v156, v23, v79
	v_lshlrev_b32_e32 v152, 16, v176
	v_and_b32_e32 v153, 0xffff0000, v176
	v_fmac_f32_e32 v152, v24, v80
	v_fmac_f32_e32 v153, v25, v81
	v_cvt_pk_bf16_f32 v152, v152, v153
	v_lshlrev_b32_e32 v153, 16, v177
	v_and_b32_e32 v154, 0xffff0000, v177
	v_fmac_f32_e32 v153, v26, v82
	v_fmac_f32_e32 v154, v27, v83
	v_cvt_pk_bf16_f32 v153, v153, v154
	v_lshlrev_b32_e32 v154, 16, v178
	v_and_b32_e32 v155, 0xffff0000, v178
	v_fmac_f32_e32 v154, v20, v76
	v_fmac_f32_e32 v155, v21, v77
	v_cvt_pk_bf16_f32 v154, v154, v155
	v_lshlrev_b32_e32 v155, 16, v179
	v_fmac_f32_e32 v155, v22, v78
	v_cvt_pk_bf16_f32 v155, v155, v156
	v_lshl_add_u64 v[156:157], s[14:15], 0, v[214:215]
	v_lshl_add_u64 v[156:157], v[156:157], 0, v[190:191]
	flat_store_dwordx4 v[156:157], v[152:155]
	s_nop 1
	v_lshlrev_b32_e32 v152, 16, v148
	v_and_b32_e32 v148, 0xffff0000, v148
	v_fmac_f32_e32 v152, v8, v64
	v_fmac_f32_e32 v148, v9, v65
	v_cvt_pk_bf16_f32 v148, v152, v148
	v_lshlrev_b32_e32 v152, 16, v149
	v_and_b32_e32 v149, 0xffff0000, v149
	v_fmac_f32_e32 v152, v10, v66
	v_fmac_f32_e32 v149, v11, v67
	v_cvt_pk_bf16_f32 v149, v152, v149
	v_lshlrev_b32_e32 v152, 16, v150
	v_and_b32_e32 v150, 0xffff0000, v150
	v_fmac_f32_e32 v152, v4, v60
	v_fmac_f32_e32 v150, v5, v61
	v_cvt_pk_bf16_f32 v150, v152, v150
	v_lshlrev_b32_e32 v152, 16, v151
	v_and_b32_e32 v151, 0xffff0000, v151
	v_fmac_f32_e32 v151, v7, v63
	v_fmac_f32_e32 v152, v6, v62
	v_cvt_pk_bf16_f32 v151, v152, v151
	flat_store_dwordx4 v[156:157], v[148:151] offset:256
	s_cbranch_execnz .LBB0_2038
	s_branch .LBB0_2050

; #define PG8_STAGE(bufoff, gbase, voff) do { _Pragma("unroll") for (int _i = 0; _i < 2; ++_i) \
;         __builtin_amdgcn_global_load_lds((const unsigned*)((const char*)(gbase) + (voff)[_i]), (PG8_LAS unsigned*)(lds + (bufoff) + ldsw + _i * 8192), 16, 0, 0); } while (0)
; #define PG8_WAIT_V(n) asm volatile("s_waitcnt vmcnt(" #n ")" ::: "memory")
; #define PG8_BAR __builtin_amdgcn_s_barrier()
; template <class Epi, class Sched, bool ALIGN_EPI = false, bool SP2 = false>
; __device__ __forceinline__ void gemm_phase(PG8_LAS unsigned char* lds, const Gemm g, const Sched& S, const Epi& E) {
;     ...
;     for (int i = 0; i < 2; ++i) { int R, C; stage_rc(tid * 16 + i * 8192, R, C); const int Rb = Epi::PERM ? ((R & ~31) + perm32(R & 31)) : R;
;         voffA[i] = (unsigned)(R * K + C) * 2u; voffB[i] = (unsigned)(Rb * K + C) * 2u; }
;     const size_t kstep = (size_t)(BK * 2);
;     const size_t hstep = (size_t)HALF * K * 2;
;     const size_t tstep = 2 * hstep;
;     const unsigned ldsw = (unsigned)wid * 1024u;
;     const int aoff = lds_byte(wr * 64 + fr, fq * 8), boff = lds_byte(wc * 32 + fr, fq * 8);
;     ...
;     Unit cur, nxt; int ui = 0;
;     if (!S.next(0, cur)) return;
;     f32x4 acc[2][2][4][2];
; #pragma unroll
;     for (int a = 0; a < 2; ++a)
; #pragma unroll
;         for (int b = 0; b < 2; ++b)
; #pragma unroll
;             for (int m = 0; m < 4; ++m)
; #pragma unroll
;                 for (int n = 0; n < 2; ++n) acc[a][b][m][n] = (f32x4){0.f, 0.f, 0.f, 0.f};
;     bf16x8 At[4][2], B0[2][2], B1[2][2];
;     const char* cA = (const char*)g.A + (size_t)cur.pm * tstep; const char* cB = (const char*)g.Bt + (size_t)cur.pn * tstep;
;     S.a_ready(cur);
;     if constexpr (SP2) {
;         PG8_STAGE(PG8_SB(0, 0), cB, voffB); PG8_STAGE(PG8_SB(0, 1), cB + hstep, voffB); PG8_STAGE(PG8_SA(0, 0), cA, voffA); PG8_STAGE(PG8_SA(0, 1), cA + hstep, voffA);
;         if (wr == 1) PG8_BAR;
;         PG8_WAIT_V(2); PG8_BAR;
;         PG8_STAGE(PG8_SB(1, 0), cB + kstep, voffB); PG8_STAGE(PG8_SA(1, 0), cA + kstep, voffA); PG8_STAGE(PG8_SB(1, 1), cB + hstep + kstep, voffB);
;         PG8_WAIT_V(6); PG8_BAR;
.LBB0_2159:
	v_lshrrev_b32_e32 v20, 1, v18
	s_add_u32 s16, s16, 0xe800000
	v_and_b32_e32 v20, 24, v20
	s_addc_u32 s17, s17, 0
	v_and_b32_e32 v19, 15, v18
	v_lshlrev_b32_e32 v21, 1, v20
	v_lshlrev_b32_e32 v18, 2, v18
	s_lshl_b32 s13, s13, 5
	s_sext_i32_i16 s4, s18
	v_lshl_or_b32 v1, s22, 6, v19
	v_lshl_or_b32 v19, v19, 6, v21
	s_lshl_b32 s18, s22, 13
	v_and_b32_e32 v18, 32, v18
	s_and_b32 s13, s13, 0x60
	v_bitop3_b32 v21, v19, s18, v18 bitop3:0xde
	s_lshl_b32 s18, s13, 7
	s_add_i32 m0, s43, 0x18000
	v_lshl_add_u64 v[10:11], v[10:11], 0, s[28:29]
	v_bitop3_b32 v146, v19, s18, v18 bitop3:0xde
	s_waitcnt vmcnt(2)
	s_barrier
	global_load_lds_dwordx4 v[10:11], off
	v_lshl_add_u64 v[8:9], v[8:9], 0, s[28:29]
	s_add_i32 m0, s43, 0x1a000
	s_add_i32 s18, s43, 0x8000
	s_add_i32 s52, s43, 0xa000
	global_load_lds_dwordx4 v[8:9], off
	v_lshl_add_u64 v[4:5], v[4:5], 0, s[28:29]
	s_mov_b32 m0, s18
	s_add_u32 s22, s20, 0x80080
	global_load_lds_dwordx4 v[4:5], off
	v_lshl_add_u64 v[4:5], v[6:7], 0, s[28:29]
	s_mov_b32 m0, s52
	s_addc_u32 s23, s21, 0
	global_load_lds_dwordx4 v[4:5], off
	s_add_i32 m0, s43, 0x1c000
	s_nop 0
	global_load_lds_dwordx4 v2, s[22:23]
	v_lshl_add_u64 v[4:5], s[22:23], 0, v[132:133]
	s_add_i32 m0, s43, 0x1e000
	s_cmpk_lt_u32 s12, 0x100
	global_load_lds_dwordx4 v[4:5], off
	v_lshlrev_b32_e32 v4, 15, v12
	v_and_b32_e32 v4, 0xffff0000, v4
	v_lshl_add_u32 v4, v13, 12, v4
	v_and_b32_e32 v5, 1, v12
	v_lshl_or_b32 v4, v5, 6, v4
	v_lshl_add_u32 v138, v14, 1, v4
	v_lshlrev_b32_e32 v4, 15, v16
	v_and_b32_e32 v4, 0xffff0000, v4
	s_waitcnt vmcnt(6)
	v_lshl_add_u32 v4, v15, 12, v4
	v_and_b32_e32 v5, 1, v16
	v_lshl_or_b32 v4, v5, 6, v4
	s_cselect_b64 s[22:23], -1, 0
	s_ashr_i32 s53, s5, 31
	v_or_b32_e32 v147, s13, v20
	v_mov_b32_e32 v139, v3
	v_lshl_add_u32 v140, v17, 1, v4
	v_mov_b32_e32 v141, v3
	s_mov_b32 s54, 0
	v_add_u32_e32 v148, 0, v21
	s_barrier
	s_branch .LBB0_2162

; #define PG8_STAGE(bufoff, gbase, voff) do { _Pragma("unroll") for (int _i = 0; _i < 2; ++_i) \
;         __builtin_amdgcn_global_load_lds((const unsigned*)((const char*)(gbase) + (voff)[_i]), (PG8_LAS unsigned*)(lds + (bufoff) + ldsw + _i * 8192), 16, 0, 0); } while (0)
; #define PG8_LDA(dst, b, h) do { _Pragma("unroll") for (int m = 0; m < 4; ++m) _Pragma("unroll") for (int k = 0; k < 2; ++k) dst[m][k] = *(const PG8_LAS bf16x8*)(lds + PG8_SA(b, h) + aoff + m * 2048 + k * 1024); } while (0)
; #define PG8_LDB(dst, b, h) do { _Pragma("unroll") for (int n = 0; n < 2; ++n) _Pragma("unroll") for (int k = 0; k < 2; ++k) dst[n][k] = *(const PG8_LAS bf16x8*)(lds + PG8_SB(b, h) + boff + n * 2048 + k * 1024); } while (0)
; #define PG8_WAIT_V(n) asm volatile("s_waitcnt vmcnt(" #n ")" ::: "memory")
; #define PG8_WAIT_L(n) asm volatile("s_waitcnt lgkmcnt(" #n ")" ::: "memory")
; #define PG8_BAR __builtin_amdgcn_s_barrier()
; #define PG8_SCHED __builtin_amdgcn_sched_barrier(0)
; template <class Epi, class Sched, bool ALIGN_EPI = false, bool SP2 = false>
; __device__ __forceinline__ void gemm_phase(PG8_LAS unsigned char* lds, const Gemm g, const Sched& S, const Epi& E) {
;     ...
;         const char* nA = has_next ? (const char*)g.A + (size_t)nxt.pm * tstep : cA; const char* nB = has_next ? (const char*)g.Bt + (size_t)nxt.pn * tstep : cB;
;         for (int t = 0; t < nt; t += 2) {
;             const bool last = (t == nt - 2);
;             const char* a1 = cA + (size_t)(t + 1) * kstep;
;             const char* a2 = last ? nA : cA + (size_t)(t + 2) * kstep; const char* b2 = last ? nB : cB + (size_t)(t + 2) * kstep;
;             const char* a3 = a2 + kstep; const char* b3 = b2 + kstep;
;             if (last && has_next) S.a_ready(nxt);
;             if constexpr (SP2) {
;             PG8_LDB(B0, 0, 0); PG8_LDB(B1, 0, 1); PG8_SCHED; PG8_LDA(At, 0, 0); PG8_STAGE(PG8_SA(1, 1), a1 + hstep, voffA);
;             PG8_WAIT_V(8); PG8_WAIT_L(0); PG8_BAR; PG8_MMA(0, 0, At, B0); PG8_MMA(0, 1, At, B1); PG8_BAR; PG8_SCHED;
;             PG8_LDA(At, 0, 1); PG8_STAGE(PG8_SB(0, 0), b2, voffB); PG8_STAGE(PG8_SB(0, 1), b2 + hstep, voffB); PG8_STAGE(PG8_SA(0, 0), a2, voffA);
;             PG8_WAIT_V(8); PG8_WAIT_L(0); PG8_BAR; PG8_MMA(1, 0, At, B0); PG8_MMA(1, 1, At, B1); PG8_BAR; PG8_SCHED;
.LBB0_2165:
	s_add_u32 s20, s44, 0xfff80080
	s_addc_u32 s21, s45, -1
	s_add_i32 s30, 0, 0x10000
	s_cmp_eq_u32 s56, 28
	s_cselect_b32 s47, s12, s21
	s_cselect_b32 s46, s13, s20
	v_add_u32_e32 v149, s30, v146
	s_cselect_b32 s21, s25, s55
	s_cselect_b32 s20, s27, s33
	s_add_i32 s57, 0, 0x14000
	ds_read_b128 v[142:145], v149
	ds_read_b128 v[150:153], v149 offset:1024
	ds_read_b128 v[154:157], v149 offset:2048
	ds_read_b128 v[158:161], v149 offset:3072
	v_add_u32_e32 v149, s57, v146
	ds_read_b128 v[162:165], v149
	ds_read_b128 v[166:169], v149 offset:1024
	ds_read_b128 v[170:173], v149 offset:2048
	ds_read_b128 v[174:177], v149 offset:3072
	s_add_i32 m0, s43, 0xc000
	ds_read_b128 v[178:181], v148
	ds_read_b128 v[182:185], v148 offset:1024
	ds_read_b128 v[186:189], v148 offset:2048
	ds_read_b128 v[190:193], v148 offset:3072
	ds_read_b128 v[194:197], v148 offset:4096
	ds_read_b128 v[198:201], v148 offset:5120
	ds_read_b128 v[202:205], v148 offset:6144
	ds_read_b128 v[206:209], v148 offset:7168
	global_load_lds_dwordx4 v140, s[44:45]
	s_add_i32 m0, s43, 0xe000
	s_nop 0
	global_load_lds_dwordx4 v138, s[44:45]
	s_waitcnt vmcnt(8)
	s_waitcnt lgkmcnt(0)
	s_barrier
	s_setprio 1
	s_waitcnt lgkmcnt(0)
	v_mfma_f32_16x16x32_bf16 v[128:131], v[142:145], v[178:181], v[128:131]
	v_mfma_f32_16x16x32_bf16 v[120:123], v[154:157], v[178:181], v[120:123]
	v_mfma_f32_16x16x32_bf16 v[112:115], v[142:145], v[186:189], v[112:115]
	v_mfma_f32_16x16x32_bf16 v[104:107], v[154:157], v[186:189], v[104:107]
	v_mfma_f32_16x16x32_bf16 v[96:99], v[142:145], v[194:197], v[96:99]
	v_mfma_f32_16x16x32_bf16 v[88:91], v[154:157], v[194:197], v[88:91]
	v_mfma_f32_16x16x32_bf16 v[80:83], v[142:145], v[202:205], v[80:83]
	v_mfma_f32_16x16x32_bf16 v[72:75], v[154:157], v[202:205], v[72:75]
	v_mfma_f32_16x16x32_bf16 v[128:131], v[150:153], v[182:185], v[128:131]
	v_mfma_f32_16x16x32_bf16 v[120:123], v[158:161], v[182:185], v[120:123]
	v_mfma_f32_16x16x32_bf16 v[112:115], v[150:153], v[190:193], v[112:115]
	v_mfma_f32_16x16x32_bf16 v[104:107], v[158:161], v[190:193], v[104:107]
	v_mfma_f32_16x16x32_bf16 v[96:99], v[150:153], v[198:201], v[96:99]
	v_mfma_f32_16x16x32_bf16 v[88:91], v[158:161], v[198:201], v[88:91]
	v_mfma_f32_16x16x32_bf16 v[80:83], v[150:153], v[206:209], v[80:83]
	v_mfma_f32_16x16x32_bf16 v[72:75], v[158:161], v[206:209], v[72:75]
	s_setprio 0
	s_setprio 1
	v_mfma_f32_16x16x32_bf16 v[124:127], v[162:165], v[178:181], v[124:127]
	v_mfma_f32_16x16x32_bf16 v[116:119], v[170:173], v[178:181], v[116:119]
	v_mfma_f32_16x16x32_bf16 v[108:111], v[162:165], v[186:189], v[108:111]
	v_mfma_f32_16x16x32_bf16 v[100:103], v[170:173], v[186:189], v[100:103]
	v_mfma_f32_16x16x32_bf16 v[92:95], v[162:165], v[194:197], v[92:95]
	v_mfma_f32_16x16x32_bf16 v[84:87], v[170:173], v[194:197], v[84:87]
	v_mfma_f32_16x16x32_bf16 v[76:79], v[162:165], v[202:205], v[76:79]
	v_mfma_f32_16x16x32_bf16 v[68:71], v[170:173], v[202:205], v[68:71]
	v_mfma_f32_16x16x32_bf16 v[124:127], v[166:169], v[182:185], v[124:127]
	v_mfma_f32_16x16x32_bf16 v[116:119], v[174:177], v[182:185], v[116:119]
	v_mfma_f32_16x16x32_bf16 v[108:111], v[166:169], v[190:193], v[108:111]
	v_mfma_f32_16x16x32_bf16 v[100:103], v[174:177], v[190:193], v[100:103]
	v_mfma_f32_16x16x32_bf16 v[92:95], v[166:169], v[198:201], v[92:95]
	v_mfma_f32_16x16x32_bf16 v[84:87], v[174:177], v[198:201], v[84:87]
	v_mfma_f32_16x16x32_bf16 v[76:79], v[166:169], v[206:209], v[76:79]
	v_mfma_f32_16x16x32_bf16 v[68:71], v[174:177], v[206:209], v[68:71]
	s_setprio 0
	s_barrier
	s_add_i32 s30, s30, s11
	v_lshl_add_u64 v[210:211], s[20:21], 0, v[2:3]
	s_mov_b32 m0, s30
	ds_read_b128 v[178:181], v148 offset:16384
	ds_read_b128 v[182:185], v148 offset:17408
	ds_read_b128 v[186:189], v148 offset:18432
	ds_read_b128 v[190:193], v148 offset:19456
	ds_read_b128 v[194:197], v148 offset:20480
	ds_read_b128 v[198:201], v148 offset:21504
	ds_read_b128 v[202:205], v148 offset:22528
	ds_read_b128 v[206:209], v148 offset:23552
	global_load_lds_dwordx4 v[210:211], off
	s_add_i32 m0, s30, 0x2000
	s_add_u32 s30, s20, 0x80000
	v_lshl_add_u64 v[212:213], s[20:21], 0, v[132:133]
	s_addc_u32 s31, s21, 0
	s_add_i32 s57, s57, s11
	global_load_lds_dwordx4 v[212:213], off
	s_mov_b32 m0, s57
	v_lshl_add_u64 v[216:217], s[46:47], 0, v[134:135]
	global_load_lds_dwordx4 v2, s[30:31]
	s_add_i32 m0, s57, 0x2000
	s_nop 0
	global_load_lds_dwordx4 v132, s[30:31]
	v_lshl_add_u64 v[214:215], s[46:47], 0, v[136:137]
	s_mov_b32 m0, s43
	s_nop 0
	global_load_lds_dwordx4 v[214:215], off
	s_mov_b32 m0, s49
	s_nop 0
	global_load_lds_dwordx4 v[216:217], off
	s_waitcnt vmcnt(8)
	s_waitcnt lgkmcnt(0)
	s_barrier
; #define PG8_STAGE(bufoff, gbase, voff) do { _Pragma("unroll") for (int _i = 0; _i < 2; ++_i) \
;         __builtin_amdgcn_global_load_lds((const unsigned*)((const char*)(gbase) + (voff)[_i]), (PG8_LAS unsigned*)(lds + (bufoff) + ldsw + _i * 8192), 16, 0, 0); } while (0)
; #define PG8_LDA(dst, b, h) do { _Pragma("unroll") for (int m = 0; m < 4; ++m) _Pragma("unroll") for (int k = 0; k < 2; ++k) dst[m][k] = *(const PG8_LAS bf16x8*)(lds + PG8_SA(b, h) + aoff + m * 2048 + k * 1024); } while (0)
; #define PG8_LDB(dst, b, h) do { _Pragma("unroll") for (int n = 0; n < 2; ++n) _Pragma("unroll") for (int k = 0; k < 2; ++k) dst[n][k] = *(const PG8_LAS bf16x8*)(lds + PG8_SB(b, h) + boff + n * 2048 + k * 1024); } while (0)
; #define PG8_MMA(ai, bj, At, Bt) do { __builtin_amdgcn_s_setprio(1); _Pragma("unroll") for (int m = 0; m < 4; ++m) _Pragma("unroll") for (int n = 0; n < 2; ++n) _Pragma("unroll") for (int k = 0; k < 2; ++k) \
;         acc[ai][bj][m][n] = __builtin_amdgcn_mfma_f32_16x16x32_bf16(Bt[n][k], At[m][k], acc[ai][bj][m][n], 0, 0, 0); __builtin_amdgcn_s_setprio(0); } while (0)
; #define PG8_WAIT_V(n) asm volatile("s_waitcnt vmcnt(" #n ")" ::: "memory")
; #define PG8_WAIT_L(n) asm volatile("s_waitcnt lgkmcnt(" #n ")" ::: "memory")
; #define PG8_BAR __builtin_amdgcn_s_barrier()
; #define PG8_SCHED __builtin_amdgcn_sched_barrier(0)
; template <class Epi, class Sched, bool ALIGN_EPI = false, bool SP2 = false>
; __device__ __forceinline__ void gemm_phase(PG8_LAS unsigned char* lds, const Gemm g, const Sched& S, const Epi& E) {
;     ...
;             PG8_WAIT_V(8); PG8_WAIT_L(0); PG8_BAR; PG8_MMA(1, 0, At, B0); PG8_MMA(1, 1, At, B1); PG8_BAR; PG8_SCHED;
;             PG8_LDB(B0, 1, 0); PG8_LDB(B1, 1, 1); PG8_SCHED; PG8_LDA(At, 1, 0); PG8_STAGE(PG8_SA(0, 1), a2 + hstep, voffA);
;             PG8_WAIT_V(8); PG8_WAIT_L(0); PG8_BAR; PG8_MMA(0, 0, At, B0); PG8_MMA(0, 1, At, B1); PG8_BAR; PG8_SCHED;
	s_setprio 1
	s_waitcnt lgkmcnt(0)
	v_mfma_f32_16x16x32_bf16 v[64:67], v[142:145], v[178:181], v[64:67]
	v_mfma_f32_16x16x32_bf16 v[56:59], v[154:157], v[178:181], v[56:59]
	v_mfma_f32_16x16x32_bf16 v[48:51], v[142:145], v[186:189], v[48:51]
	v_mfma_f32_16x16x32_bf16 v[40:43], v[154:157], v[186:189], v[40:43]
	v_mfma_f32_16x16x32_bf16 v[32:35], v[142:145], v[194:197], v[32:35]
	v_mfma_f32_16x16x32_bf16 v[24:27], v[154:157], v[194:197], v[24:27]
	v_mfma_f32_16x16x32_bf16 v[16:19], v[142:145], v[202:205], v[16:19]
	v_mfma_f32_16x16x32_bf16 v[8:11], v[154:157], v[202:205], v[8:11]
	v_mfma_f32_16x16x32_bf16 v[64:67], v[150:153], v[182:185], v[64:67]
	v_mfma_f32_16x16x32_bf16 v[56:59], v[158:161], v[182:185], v[56:59]
	v_mfma_f32_16x16x32_bf16 v[48:51], v[150:153], v[190:193], v[48:51]
	v_mfma_f32_16x16x32_bf16 v[40:43], v[158:161], v[190:193], v[40:43]
	v_mfma_f32_16x16x32_bf16 v[32:35], v[150:153], v[198:201], v[32:35]
	v_mfma_f32_16x16x32_bf16 v[24:27], v[158:161], v[198:201], v[24:27]
	v_mfma_f32_16x16x32_bf16 v[16:19], v[150:153], v[206:209], v[16:19]
	v_mfma_f32_16x16x32_bf16 v[8:11], v[158:161], v[206:209], v[8:11]
	s_setprio 0
	s_setprio 1
	v_mfma_f32_16x16x32_bf16 v[60:63], v[162:165], v[178:181], v[60:63]
	v_mfma_f32_16x16x32_bf16 v[52:55], v[170:173], v[178:181], v[52:55]
	v_mfma_f32_16x16x32_bf16 v[44:47], v[162:165], v[186:189], v[44:47]
	v_mfma_f32_16x16x32_bf16 v[36:39], v[170:173], v[186:189], v[36:39]
	v_mfma_f32_16x16x32_bf16 v[28:31], v[162:165], v[194:197], v[28:31]
	v_mfma_f32_16x16x32_bf16 v[20:23], v[170:173], v[194:197], v[20:23]
	v_mfma_f32_16x16x32_bf16 v[12:15], v[162:165], v[202:205], v[12:15]
	v_mfma_f32_16x16x32_bf16 v[4:7], v[170:173], v[202:205], v[4:7]
	v_mfma_f32_16x16x32_bf16 v[60:63], v[166:169], v[182:185], v[60:63]
	v_mfma_f32_16x16x32_bf16 v[52:55], v[174:177], v[182:185], v[52:55]
	v_mfma_f32_16x16x32_bf16 v[44:47], v[166:169], v[190:193], v[44:47]
	v_mfma_f32_16x16x32_bf16 v[36:39], v[174:177], v[190:193], v[36:39]
	v_mfma_f32_16x16x32_bf16 v[28:31], v[166:169], v[198:201], v[28:31]
	v_mfma_f32_16x16x32_bf16 v[20:23], v[174:177], v[198:201], v[20:23]
	v_mfma_f32_16x16x32_bf16 v[12:15], v[166:169], v[206:209], v[12:15]
	v_mfma_f32_16x16x32_bf16 v[4:7], v[174:177], v[206:209], v[4:7]
	s_setprio 0
	s_barrier
	s_add_i32 s57, 0, 0x18000
	v_add_u32_e32 v149, s57, v146
	s_add_i32 s58, 0, 0x1c000
	ds_read_b128 v[142:145], v149
	ds_read_b128 v[150:153], v149 offset:1024
	ds_read_b128 v[154:157], v149 offset:2048
	ds_read_b128 v[158:161], v149 offset:3072
	v_add_u32_e32 v149, s58, v146
	ds_read_b128 v[162:165], v149
	ds_read_b128 v[166:169], v149 offset:1024
	ds_read_b128 v[170:173], v149 offset:2048
	ds_read_b128 v[174:177], v149 offset:3072
	s_add_u32 s30, s46, 0x80000
	s_addc_u32 s31, s47, 0
	s_mov_b32 m0, s50
	ds_read_b128 v[178:181], v148 offset:32768
	ds_read_b128 v[182:185], v148 offset:33792
	ds_read_b128 v[186:189], v148 offset:34816
	ds_read_b128 v[190:193], v148 offset:35840
	ds_read_b128 v[194:197], v148 offset:36864
	ds_read_b128 v[198:201], v148 offset:37888
	ds_read_b128 v[202:205], v148 offset:38912
	ds_read_b128 v[206:209], v148 offset:39936
	global_load_lds_dwordx4 v136, s[30:31]
	s_mov_b32 m0, s51
	s_nop 0
	global_load_lds_dwordx4 v134, s[30:31]
	s_waitcnt vmcnt(8)
	s_waitcnt lgkmcnt(0)
	s_barrier
	s_setprio 1
	s_waitcnt lgkmcnt(0)
	v_mfma_f32_16x16x32_bf16 v[128:131], v[142:145], v[178:181], v[128:131]
	v_mfma_f32_16x16x32_bf16 v[120:123], v[154:157], v[178:181], v[120:123]
	v_mfma_f32_16x16x32_bf16 v[112:115], v[142:145], v[186:189], v[112:115]
	v_mfma_f32_16x16x32_bf16 v[104:107], v[154:157], v[186:189], v[104:107]
	v_mfma_f32_16x16x32_bf16 v[96:99], v[142:145], v[194:197], v[96:99]
	v_mfma_f32_16x16x32_bf16 v[88:91], v[154:157], v[194:197], v[88:91]
	v_mfma_f32_16x16x32_bf16 v[80:83], v[142:145], v[202:205], v[80:83]
	v_mfma_f32_16x16x32_bf16 v[72:75], v[154:157], v[202:205], v[72:75]
	v_mfma_f32_16x16x32_bf16 v[128:131], v[150:153], v[182:185], v[128:131]
	v_mfma_f32_16x16x32_bf16 v[120:123], v[158:161], v[182:185], v[120:123]
	v_mfma_f32_16x16x32_bf16 v[112:115], v[150:153], v[190:193], v[112:115]
	v_mfma_f32_16x16x32_bf16 v[104:107], v[158:161], v[190:193], v[104:107]
	v_mfma_f32_16x16x32_bf16 v[96:99], v[150:153], v[198:201], v[96:99]
	v_mfma_f32_16x16x32_bf16 v[88:91], v[158:161], v[198:201], v[88:91]
	v_mfma_f32_16x16x32_bf16 v[80:83], v[150:153], v[206:209], v[80:83]
	v_mfma_f32_16x16x32_bf16 v[72:75], v[158:161], v[206:209], v[72:75]
	s_setprio 0
	s_setprio 1
	v_mfma_f32_16x16x32_bf16 v[124:127], v[162:165], v[178:181], v[124:127]
	v_mfma_f32_16x16x32_bf16 v[116:119], v[170:173], v[178:181], v[116:119]
	v_mfma_f32_16x16x32_bf16 v[108:111], v[162:165], v[186:189], v[108:111]
	v_mfma_f32_16x16x32_bf16 v[100:103], v[170:173], v[186:189], v[100:103]
	v_mfma_f32_16x16x32_bf16 v[92:95], v[162:165], v[194:197], v[92:95]
	v_mfma_f32_16x16x32_bf16 v[84:87], v[170:173], v[194:197], v[84:87]
	v_mfma_f32_16x16x32_bf16 v[76:79], v[162:165], v[202:205], v[76:79]
	v_mfma_f32_16x16x32_bf16 v[68:71], v[170:173], v[202:205], v[68:71]
	v_mfma_f32_16x16x32_bf16 v[124:127], v[166:169], v[182:185], v[124:127]
	v_mfma_f32_16x16x32_bf16 v[116:119], v[174:177], v[182:185], v[116:119]
	v_mfma_f32_16x16x32_bf16 v[108:111], v[166:169], v[190:193], v[108:111]
	v_mfma_f32_16x16x32_bf16 v[100:103], v[174:177], v[190:193], v[100:103]
	v_mfma_f32_16x16x32_bf16 v[92:95], v[166:169], v[198:201], v[92:95]
	v_mfma_f32_16x16x32_bf16 v[84:87], v[174:177], v[198:201], v[84:87]
	v_mfma_f32_16x16x32_bf16 v[76:79], v[166:169], v[206:209], v[76:79]
	v_mfma_f32_16x16x32_bf16 v[68:71], v[174:177], v[206:209], v[68:71]
	s_setprio 0
	s_barrier
; #define PG8_STAGE(bufoff, gbase, voff) do { _Pragma("unroll") for (int _i = 0; _i < 2; ++_i) \
;         __builtin_amdgcn_global_load_lds((const unsigned*)((const char*)(gbase) + (voff)[_i]), (PG8_LAS unsigned*)(lds + (bufoff) + ldsw + _i * 8192), 16, 0, 0); } while (0)
; #define PG8_LDA(dst, b, h) do { _Pragma("unroll") for (int m = 0; m < 4; ++m) _Pragma("unroll") for (int k = 0; k < 2; ++k) dst[m][k] = *(const PG8_LAS bf16x8*)(lds + PG8_SA(b, h) + aoff + m * 2048 + k * 1024); } while (0)
; #define PG8_MMA(ai, bj, At, Bt) do { __builtin_amdgcn_s_setprio(1); _Pragma("unroll") for (int m = 0; m < 4; ++m) _Pragma("unroll") for (int n = 0; n < 2; ++n) _Pragma("unroll") for (int k = 0; k < 2; ++k) \
;         acc[ai][bj][m][n] = __builtin_amdgcn_mfma_f32_16x16x32_bf16(Bt[n][k], At[m][k], acc[ai][bj][m][n], 0, 0, 0); __builtin_amdgcn_s_setprio(0); } while (0)
; #define PG8_WAIT_V(n) asm volatile("s_waitcnt vmcnt(" #n ")" ::: "memory")
; #define PG8_WAIT_L(n) asm volatile("s_waitcnt lgkmcnt(" #n ")" ::: "memory")
; #define PG8_BAR __builtin_amdgcn_s_barrier()
; #define PG8_SCHED __builtin_amdgcn_sched_barrier(0)
; template <class Epi, class Sched, bool ALIGN_EPI = false, bool SP2 = false>
; __device__ __forceinline__ void gemm_phase(PG8_LAS unsigned char* lds, const Gemm g, const Sched& S, const Epi& E) {
;     ...
;             PG8_LDA(At, 1, 1); PG8_STAGE(PG8_SB(1, 0), b3, voffB); PG8_STAGE(PG8_SB(1, 1), b3 + hstep, voffB); PG8_STAGE(PG8_SA(1, 0), a3, voffA);
;             PG8_WAIT_V(8); PG8_WAIT_L(0); PG8_BAR; PG8_MMA(1, 0, At, B0); PG8_MMA(1, 1, At, B1); PG8_BAR; PG8_SCHED;
;     ...
;         if constexpr (ALIGN_EPI) { if (wr == 0) PG8_BAR; }
	s_add_i32 s30, s57, s11
	v_lshl_add_u64 v[210:211], v[210:211], 0, s[28:29]
	s_mov_b32 m0, s30
	ds_read_b128 v[178:181], v148 offset:49152
	ds_read_b128 v[182:185], v148 offset:50176
	ds_read_b128 v[186:189], v148 offset:51200
	ds_read_b128 v[190:193], v148 offset:52224
	ds_read_b128 v[194:197], v148 offset:53248
	ds_read_b128 v[198:201], v148 offset:54272
	ds_read_b128 v[202:205], v148 offset:55296
	ds_read_b128 v[206:209], v148 offset:56320
	global_load_lds_dwordx4 v[210:211], off
	s_add_i32 m0, s30, 0x2000
	s_add_u32 s20, s20, 0x80080
	v_lshl_add_u64 v[210:211], v[212:213], 0, s[28:29]
	s_addc_u32 s21, s21, 0
	s_add_i32 s30, s58, s11
	global_load_lds_dwordx4 v[210:211], off
	s_mov_b32 m0, s30
	s_nop 0
	global_load_lds_dwordx4 v2, s[20:21]
	s_add_i32 m0, s30, 0x2000
	s_nop 0
	global_load_lds_dwordx4 v132, s[20:21]
	v_lshl_add_u64 v[210:211], v[214:215], 0, s[28:29]
	s_mov_b32 m0, s18
	s_nop 0
	global_load_lds_dwordx4 v[210:211], off
	v_lshl_add_u64 v[210:211], v[216:217], 0, s[28:29]
	s_mov_b32 m0, s52
	s_nop 0
	global_load_lds_dwordx4 v[210:211], off
	s_waitcnt vmcnt(8)
	s_waitcnt lgkmcnt(0)
	s_barrier
	s_setprio 1
	s_waitcnt lgkmcnt(0)
	v_mfma_f32_16x16x32_bf16 v[64:67], v[142:145], v[178:181], v[64:67]
	v_mfma_f32_16x16x32_bf16 v[56:59], v[154:157], v[178:181], v[56:59]
	v_mfma_f32_16x16x32_bf16 v[48:51], v[142:145], v[186:189], v[48:51]
	v_mfma_f32_16x16x32_bf16 v[40:43], v[154:157], v[186:189], v[40:43]
	v_mfma_f32_16x16x32_bf16 v[32:35], v[142:145], v[194:197], v[32:35]
	v_mfma_f32_16x16x32_bf16 v[24:27], v[154:157], v[194:197], v[24:27]
	v_mfma_f32_16x16x32_bf16 v[16:19], v[142:145], v[202:205], v[16:19]
	v_mfma_f32_16x16x32_bf16 v[8:11], v[154:157], v[202:205], v[8:11]
	v_mfma_f32_16x16x32_bf16 v[64:67], v[150:153], v[182:185], v[64:67]
	v_mfma_f32_16x16x32_bf16 v[56:59], v[158:161], v[182:185], v[56:59]
	v_mfma_f32_16x16x32_bf16 v[48:51], v[150:153], v[190:193], v[48:51]
	v_mfma_f32_16x16x32_bf16 v[40:43], v[158:161], v[190:193], v[40:43]
	v_mfma_f32_16x16x32_bf16 v[32:35], v[150:153], v[198:201], v[32:35]
	v_mfma_f32_16x16x32_bf16 v[24:27], v[158:161], v[198:201], v[24:27]
	v_mfma_f32_16x16x32_bf16 v[16:19], v[150:153], v[206:209], v[16:19]
	v_mfma_f32_16x16x32_bf16 v[8:11], v[158:161], v[206:209], v[8:11]
	s_setprio 0
	s_setprio 1
	v_mfma_f32_16x16x32_bf16 v[60:63], v[162:165], v[178:181], v[60:63]
	v_mfma_f32_16x16x32_bf16 v[52:55], v[170:173], v[178:181], v[52:55]
	v_mfma_f32_16x16x32_bf16 v[44:47], v[162:165], v[186:189], v[44:47]
	v_mfma_f32_16x16x32_bf16 v[36:39], v[170:173], v[186:189], v[36:39]
	v_mfma_f32_16x16x32_bf16 v[28:31], v[162:165], v[194:197], v[28:31]
	v_mfma_f32_16x16x32_bf16 v[20:23], v[170:173], v[194:197], v[20:23]
	v_mfma_f32_16x16x32_bf16 v[12:15], v[162:165], v[202:205], v[12:15]
	v_mfma_f32_16x16x32_bf16 v[4:7], v[170:173], v[202:205], v[4:7]
	v_mfma_f32_16x16x32_bf16 v[60:63], v[166:169], v[182:185], v[60:63]
	v_mfma_f32_16x16x32_bf16 v[52:55], v[174:177], v[182:185], v[52:55]
	v_mfma_f32_16x16x32_bf16 v[44:47], v[166:169], v[190:193], v[44:47]
	v_mfma_f32_16x16x32_bf16 v[36:39], v[174:177], v[190:193], v[36:39]
	v_mfma_f32_16x16x32_bf16 v[28:31], v[166:169], v[198:201], v[28:31]
	v_mfma_f32_16x16x32_bf16 v[20:23], v[174:177], v[198:201], v[20:23]
	v_mfma_f32_16x16x32_bf16 v[12:15], v[166:169], v[206:209], v[12:15]
	v_mfma_f32_16x16x32_bf16 v[4:7], v[174:177], v[206:209], v[4:7]
	s_setprio 0
	s_barrier
	s_add_i32 s56, s56, 2
	s_add_u32 s33, s33, 0x100
	s_addc_u32 s55, s55, 0
	s_add_u32 s44, s44, 0x100
	s_addc_u32 s45, s45, 0
	s_cmp_gt_u32 s56, 29
	s_cbranch_scc0 .LBB0_2165
	s_and_b64 vcc, exec, s[22:23]
	s_cbranch_vccz .LBB0_2168
	s_barrier

; #define PG8_STAGE(bufoff, gbase, voff) do { _Pragma("unroll") for (int _i = 0; _i < 2; ++_i) \
;         __builtin_amdgcn_global_load_lds((const unsigned*)((const char*)(gbase) + (voff)[_i]), (PG8_LAS unsigned*)(lds + (bufoff) + ldsw + _i * 8192), 16, 0, 0); } while (0)
; #define PG8_WAIT_V(n) asm volatile("s_waitcnt vmcnt(" #n ")" ::: "memory")
; #define PG8_BAR __builtin_amdgcn_s_barrier()
; template <class Epi, class Sched, bool ALIGN_EPI = false, bool SP2 = false>
; __device__ __forceinline__ void gemm_phase(PG8_LAS unsigned char* lds, const Gemm g, const Sched& S, const Epi& E) {
;     ...
;     for (int i = 0; i < 2; ++i) { int R, C; stage_rc(tid * 16 + i * 8192, R, C); const int Rb = Epi::PERM ? ((R & ~31) + perm32(R & 31)) : R;
;         voffA[i] = (unsigned)(R * K + C) * 2u; voffB[i] = (unsigned)(Rb * K + C) * 2u; }
;     const size_t kstep = (size_t)(BK * 2);
;     const size_t hstep = (size_t)HALF * K * 2;
;     const size_t tstep = 2 * hstep;
;     const unsigned ldsw = (unsigned)wid * 1024u;
;     const int aoff = lds_byte(wr * 64 + fr, fq * 8), boff = lds_byte(wc * 32 + fr, fq * 8);
;     ...
;     Unit cur, nxt; int ui = 0;
;     if (!S.next(0, cur)) return;
;     f32x4 acc[2][2][4][2];
; #pragma unroll
;     for (int a = 0; a < 2; ++a)
; #pragma unroll
;         for (int b = 0; b < 2; ++b)
; #pragma unroll
;             for (int m = 0; m < 4; ++m)
; #pragma unroll
;                 for (int n = 0; n < 2; ++n) acc[a][b][m][n] = (f32x4){0.f, 0.f, 0.f, 0.f};
;     bf16x8 At[4][2], B0[2][2], B1[2][2];
;     const char* cA = (const char*)g.A + (size_t)cur.pm * tstep; const char* cB = (const char*)g.Bt + (size_t)cur.pn * tstep;
;     S.a_ready(cur);
;     if constexpr (SP2) {
;         PG8_STAGE(PG8_SB(0, 0), cB, voffB); PG8_STAGE(PG8_SB(0, 1), cB + hstep, voffB); PG8_STAGE(PG8_SA(0, 0), cA, voffA); PG8_STAGE(PG8_SA(0, 1), cA + hstep, voffA);
;         if (wr == 1) PG8_BAR;
;         PG8_WAIT_V(2); PG8_BAR;
;         PG8_STAGE(PG8_SB(1, 0), cB + kstep, voffB); PG8_STAGE(PG8_SA(1, 0), cA + kstep, voffA); PG8_STAGE(PG8_SB(1, 1), cB + hstep + kstep, voffB);
;         PG8_WAIT_V(6); PG8_BAR;
.LBB0_2226:
	s_add_u32 s14, s14, 0x4800000
	s_addc_u32 s15, s15, 0
	v_lshrrev_b32_e32 v22, 1, v17
	s_add_u32 s47, s16, 0x10a000
	v_and_b32_e32 v22, 24, v22
	s_addc_u32 s48, s17, 0
	v_and_b32_e32 v21, 15, v17
	v_lshlrev_b32_e32 v23, 1, v22
	v_lshlrev_b32_e32 v17, 2, v17
	s_lshl_b32 s4, s4, 5
	v_lshl_or_b32 v1, s22, 6, v21
	v_lshl_or_b32 v21, v21, 6, v23
	s_lshl_b32 s16, s22, 13
	v_and_b32_e32 v17, 32, v17
	s_and_b32 s4, s4, 0x60
	s_add_i32 m0, s18, 0x18000
	v_lshl_add_u64 v[10:11], v[10:11], 0, s[28:29]
	v_bitop3_b32 v23, v21, s16, v17 bitop3:0xde
	s_lshl_b32 s16, s4, 7
	s_waitcnt vmcnt(2)
	s_barrier
	global_load_lds_dwordx4 v[10:11], off
	v_lshl_add_u64 v[8:9], v[8:9], 0, s[28:29]
	s_add_i32 m0, s18, 0x1a000
	s_add_i32 s49, s18, 0x8000
	s_add_i32 s50, s18, 0xa000
	v_bitop3_b32 v198, v21, s16, v17 bitop3:0xde
	global_load_lds_dwordx4 v[8:9], off
	v_lshl_add_u64 v[6:7], v[6:7], 0, s[28:29]
	s_mov_b32 m0, s49
	s_add_u32 s16, s24, 0x160080
	global_load_lds_dwordx4 v[6:7], off
	v_lshl_add_u64 v[4:5], v[4:5], 0, s[28:29]
	s_mov_b32 m0, s50
	s_addc_u32 s17, s25, 0
	global_load_lds_dwordx4 v[4:5], off
	s_add_i32 m0, s18, 0x1c000
	s_nop 0
	global_load_lds_dwordx4 v2, s[16:17]
	v_lshl_add_u64 v[4:5], s[16:17], 0, v[180:181]
	s_add_i32 m0, s18, 0x1e000
	s_movk_i32 s22, 0x1600
	global_load_lds_dwordx4 v[4:5], off
	v_or_b32_e32 v199, s4, v22
	v_lshrrev_b32_e32 v5, 1, v16
	v_mul_lo_u32 v4, v19, s22
	s_mov_b32 s4, 0x16000
	v_mad_u64_u32 v[4:5], s[16:17], v5, s4, v[4:5]
	v_or_b32_e32 v4, v4, v18
	v_add_lshl_u32 v4, v4, v20, 1
	v_mov_b32_e32 v5, v3
	s_mov_b64 s[26:27], 0x160080
	v_lshl_add_u64 v[182:183], v[4:5], 0, s[26:27]
	v_lshrrev_b32_e32 v5, 1, v12
	v_mul_lo_u32 v4, v14, s22
	v_mad_u64_u32 v[4:5], s[16:17], v5, s4, v[4:5]
	s_waitcnt vmcnt(6)
	v_or_b32_e32 v4, v4, v13
	v_add_lshl_u32 v4, v4, v15, 1
	v_mov_b32_e32 v5, v3
	s_sext_i32_i8 s54, s23
	s_ashr_i32 s51, s5, 31
	v_lshl_add_u64 v[184:185], v[4:5], 0, s[26:27]
	s_mov_b32 s4, 0
	v_add_u32_e32 v200, 0, v23
	s_barrier

; #define PG8_STAGE(bufoff, gbase, voff) do { _Pragma("unroll") for (int _i = 0; _i < 2; ++_i) \
;         __builtin_amdgcn_global_load_lds((const unsigned*)((const char*)(gbase) + (voff)[_i]), (PG8_LAS unsigned*)(lds + (bufoff) + ldsw + _i * 8192), 16, 0, 0); } while (0)
; #define PG8_LDA(dst, b, h) do { _Pragma("unroll") for (int m = 0; m < 4; ++m) _Pragma("unroll") for (int k = 0; k < 2; ++k) dst[m][k] = *(const PG8_LAS bf16x8*)(lds + PG8_SA(b, h) + aoff + m * 2048 + k * 1024); } while (0)
; #define PG8_LDB(dst, b, h) do { _Pragma("unroll") for (int n = 0; n < 2; ++n) _Pragma("unroll") for (int k = 0; k < 2; ++k) dst[n][k] = *(const PG8_LAS bf16x8*)(lds + PG8_SB(b, h) + boff + n * 2048 + k * 1024); } while (0)
; #define PG8_MMA(ai, bj, At, Bt) do { __builtin_amdgcn_s_setprio(1); _Pragma("unroll") for (int m = 0; m < 4; ++m) _Pragma("unroll") for (int n = 0; n < 2; ++n) _Pragma("unroll") for (int k = 0; k < 2; ++k) \
;         acc[ai][bj][m][n] = __builtin_amdgcn_mfma_f32_16x16x32_bf16(Bt[n][k], At[m][k], acc[ai][bj][m][n], 0, 0, 0); __builtin_amdgcn_s_setprio(0); } while (0)
; #define PG8_WAIT_V(n) asm volatile("s_waitcnt vmcnt(" #n ")" ::: "memory")
; #define PG8_WAIT_L(n) asm volatile("s_waitcnt lgkmcnt(" #n ")" ::: "memory")
; #define PG8_BAR __builtin_amdgcn_s_barrier()
; #define PG8_SCHED __builtin_amdgcn_sched_barrier(0)
; template <class Epi, class Sched, bool ALIGN_EPI = false, bool SP2 = false>
; __device__ __forceinline__ void gemm_phase(PG8_LAS unsigned char* lds, const Gemm g, const Sched& S, const Epi& E) {
;     ...
;             PG8_LDB(B0, 0, 0); PG8_LDB(B1, 0, 1); PG8_SCHED; PG8_LDA(At, 0, 0); PG8_STAGE(PG8_SA(1, 1), a1 + hstep, voffA);
;             PG8_WAIT_V(8); PG8_WAIT_L(0); PG8_BAR; PG8_MMA(0, 0, At, B0); PG8_MMA(0, 1, At, B1); PG8_BAR; PG8_SCHED;
;             PG8_LDA(At, 0, 1); PG8_STAGE(PG8_SB(0, 0), b2, voffB); PG8_STAGE(PG8_SB(0, 1), b2 + hstep, voffB); PG8_STAGE(PG8_SA(0, 0), a2, voffA);
.LBB0_2238:
	s_add_u32 s24, s20, 0x100
	s_addc_u32 s25, s21, 0
	s_add_i32 s30, 0, 0x10000
	s_cmpk_eq_i32 s42, 0x54
	s_cselect_b32 s37, s17, s25
	s_cselect_b32 s36, s16, s24
	s_cselect_b32 s27, s23, s41
	s_cselect_b32 s26, s22, s40
	s_add_i32 s31, 0, 0x14000
	v_add_u32_e32 v136, s30, v198
	v_add_u32_e32 v160, s31, v198
	ds_read_b128 v[124:127], v136
	ds_read_b128 v[128:131], v136 offset:1024
	ds_read_b128 v[132:135], v136 offset:2048
	ds_read_b128 v[136:139], v136 offset:3072
	ds_read_b128 v[148:151], v160
	ds_read_b128 v[152:155], v160 offset:1024
	ds_read_b128 v[156:159], v160 offset:2048
	ds_read_b128 v[160:163], v160 offset:3072
	v_lshl_add_u64 v[210:211], s[20:21], 0, v[184:185]
	s_add_i32 m0, s18, 0xc000
	ds_read_b128 v[164:167], v200
	ds_read_b128 v[168:171], v200 offset:1024
	ds_read_b128 v[172:175], v200 offset:2048
	ds_read_b128 v[186:189], v200 offset:3072
	ds_read_b128 v[190:193], v200 offset:4096
	ds_read_b128 v[194:197], v200 offset:5120
	ds_read_b128 v[202:205], v200 offset:6144
	ds_read_b128 v[206:209], v200 offset:7168
	global_load_lds_dwordx4 v[210:211], off
	v_lshl_add_u64 v[210:211], s[20:21], 0, v[182:183]
	s_add_i32 m0, s18, 0xe000
	s_nop 0
	global_load_lds_dwordx4 v[210:211], off
	s_waitcnt vmcnt(8)
	s_waitcnt lgkmcnt(0)
	s_barrier
	s_setprio 1
	s_waitcnt lgkmcnt(0)
	v_mfma_f32_16x16x32_bf16 v[144:147], v[124:127], v[164:167], v[144:147]
	v_mfma_f32_16x16x32_bf16 v[140:143], v[132:135], v[164:167], v[140:143]
	v_mfma_f32_16x16x32_bf16 v[112:115], v[124:127], v[172:175], v[112:115]
	v_mfma_f32_16x16x32_bf16 v[108:111], v[132:135], v[172:175], v[108:111]
	v_mfma_f32_16x16x32_bf16 v[100:103], v[124:127], v[190:193], v[100:103]
	v_mfma_f32_16x16x32_bf16 v[92:95], v[132:135], v[190:193], v[92:95]
	v_mfma_f32_16x16x32_bf16 v[84:87], v[124:127], v[202:205], v[84:87]
	v_mfma_f32_16x16x32_bf16 v[76:79], v[132:135], v[202:205], v[76:79]
	v_mfma_f32_16x16x32_bf16 v[144:147], v[128:131], v[168:171], v[144:147]
	v_mfma_f32_16x16x32_bf16 v[140:143], v[136:139], v[168:171], v[140:143]
	v_mfma_f32_16x16x32_bf16 v[112:115], v[128:131], v[186:189], v[112:115]
	v_mfma_f32_16x16x32_bf16 v[108:111], v[136:139], v[186:189], v[108:111]
	v_mfma_f32_16x16x32_bf16 v[100:103], v[128:131], v[194:197], v[100:103]
	v_mfma_f32_16x16x32_bf16 v[92:95], v[136:139], v[194:197], v[92:95]
	v_mfma_f32_16x16x32_bf16 v[84:87], v[128:131], v[206:209], v[84:87]
	v_mfma_f32_16x16x32_bf16 v[76:79], v[136:139], v[206:209], v[76:79]
	s_setprio 0
	s_setprio 1
	v_mfma_f32_16x16x32_bf16 v[120:123], v[148:151], v[164:167], v[120:123]
	v_mfma_f32_16x16x32_bf16 v[116:119], v[156:159], v[164:167], v[116:119]
	v_mfma_f32_16x16x32_bf16 v[104:107], v[148:151], v[172:175], v[104:107]
	v_mfma_f32_16x16x32_bf16 v[96:99], v[156:159], v[172:175], v[96:99]
	v_mfma_f32_16x16x32_bf16 v[88:91], v[148:151], v[190:193], v[88:91]
	v_mfma_f32_16x16x32_bf16 v[80:83], v[156:159], v[190:193], v[80:83]
	v_mfma_f32_16x16x32_bf16 v[72:75], v[148:151], v[202:205], v[72:75]
	v_mfma_f32_16x16x32_bf16 v[68:71], v[156:159], v[202:205], v[68:71]
	v_mfma_f32_16x16x32_bf16 v[120:123], v[152:155], v[168:171], v[120:123]
	v_mfma_f32_16x16x32_bf16 v[116:119], v[160:163], v[168:171], v[116:119]
	v_mfma_f32_16x16x32_bf16 v[104:107], v[152:155], v[186:189], v[104:107]
	v_mfma_f32_16x16x32_bf16 v[96:99], v[160:163], v[186:189], v[96:99]
	v_mfma_f32_16x16x32_bf16 v[88:91], v[152:155], v[194:197], v[88:91]
	v_mfma_f32_16x16x32_bf16 v[80:83], v[160:163], v[194:197], v[80:83]
	v_mfma_f32_16x16x32_bf16 v[72:75], v[152:155], v[206:209], v[72:75]
	v_mfma_f32_16x16x32_bf16 v[68:71], v[160:163], v[206:209], v[68:71]
	s_setprio 0
	s_barrier
	s_add_i32 s20, s30, s13
	v_lshl_add_u64 v[210:211], s[26:27], 0, v[2:3]
	s_mov_b32 m0, s20
	ds_read_b128 v[164:167], v200 offset:16384
	ds_read_b128 v[168:171], v200 offset:17408
	ds_read_b128 v[172:175], v200 offset:18432
	ds_read_b128 v[186:189], v200 offset:19456
	ds_read_b128 v[190:193], v200 offset:20480
	ds_read_b128 v[194:197], v200 offset:21504
	ds_read_b128 v[202:205], v200 offset:22528
	ds_read_b128 v[206:209], v200 offset:23552
	global_load_lds_dwordx4 v[210:211], off
	s_add_i32 m0, s20, 0x2000
	s_add_u32 s20, s26, 0x160000
	v_lshl_add_u64 v[212:213], s[26:27], 0, v[180:181]
	s_addc_u32 s21, s27, 0
	s_add_i32 s30, s31, s13
	global_load_lds_dwordx4 v[212:213], off
	s_mov_b32 m0, s30
	v_lshl_add_u64 v[216:217], s[36:37], 0, v[178:179]
	global_load_lds_dwordx4 v2, s[20:21]
	s_add_i32 m0, s30, 0x2000
	s_nop 0
	global_load_lds_dwordx4 v180, s[20:21]
	v_lshl_add_u64 v[214:215], s[36:37], 0, v[176:177]
	s_mov_b32 m0, s18
	s_nop 0
	global_load_lds_dwordx4 v[214:215], off
	s_mov_b32 m0, s44
	s_nop 0
	global_load_lds_dwordx4 v[216:217], off
	s_waitcnt vmcnt(8)
	s_waitcnt lgkmcnt(0)
	s_barrier
; #define PG8_STAGE(bufoff, gbase, voff) do { _Pragma("unroll") for (int _i = 0; _i < 2; ++_i) \
;         __builtin_amdgcn_global_load_lds((const unsigned*)((const char*)(gbase) + (voff)[_i]), (PG8_LAS unsigned*)(lds + (bufoff) + ldsw + _i * 8192), 16, 0, 0); } while (0)
; #define PG8_LDA(dst, b, h) do { _Pragma("unroll") for (int m = 0; m < 4; ++m) _Pragma("unroll") for (int k = 0; k < 2; ++k) dst[m][k] = *(const PG8_LAS bf16x8*)(lds + PG8_SA(b, h) + aoff + m * 2048 + k * 1024); } while (0)
; #define PG8_LDB(dst, b, h) do { _Pragma("unroll") for (int n = 0; n < 2; ++n) _Pragma("unroll") for (int k = 0; k < 2; ++k) dst[n][k] = *(const PG8_LAS bf16x8*)(lds + PG8_SB(b, h) + boff + n * 2048 + k * 1024); } while (0)
; #define PG8_MMA(ai, bj, At, Bt) do { __builtin_amdgcn_s_setprio(1); _Pragma("unroll") for (int m = 0; m < 4; ++m) _Pragma("unroll") for (int n = 0; n < 2; ++n) _Pragma("unroll") for (int k = 0; k < 2; ++k) \
;         acc[ai][bj][m][n] = __builtin_amdgcn_mfma_f32_16x16x32_bf16(Bt[n][k], At[m][k], acc[ai][bj][m][n], 0, 0, 0); __builtin_amdgcn_s_setprio(0); } while (0)
; #define PG8_WAIT_V(n) asm volatile("s_waitcnt vmcnt(" #n ")" ::: "memory")
; #define PG8_WAIT_L(n) asm volatile("s_waitcnt lgkmcnt(" #n ")" ::: "memory")
; #define PG8_BAR __builtin_amdgcn_s_barrier()
; #define PG8_SCHED __builtin_amdgcn_sched_barrier(0)
; template <class Epi, class Sched, bool ALIGN_EPI = false, bool SP2 = false>
; __device__ __forceinline__ void gemm_phase(PG8_LAS unsigned char* lds, const Gemm g, const Sched& S, const Epi& E) {
;     ...
;             PG8_WAIT_V(8); PG8_WAIT_L(0); PG8_BAR; PG8_MMA(1, 0, At, B0); PG8_MMA(1, 1, At, B1); PG8_BAR; PG8_SCHED;
;             PG8_LDB(B0, 1, 0); PG8_LDB(B1, 1, 1); PG8_SCHED; PG8_LDA(At, 1, 0); PG8_STAGE(PG8_SA(0, 1), a2 + hstep, voffA);
;             PG8_WAIT_V(8); PG8_WAIT_L(0); PG8_BAR; PG8_MMA(0, 0, At, B0); PG8_MMA(0, 1, At, B1); PG8_BAR; PG8_SCHED;
	s_setprio 1
	s_waitcnt lgkmcnt(0)
	v_mfma_f32_16x16x32_bf16 v[64:67], v[124:127], v[164:167], v[64:67]
	v_mfma_f32_16x16x32_bf16 v[60:63], v[132:135], v[164:167], v[60:63]
	v_mfma_f32_16x16x32_bf16 v[52:55], v[124:127], v[172:175], v[52:55]
	v_mfma_f32_16x16x32_bf16 v[44:47], v[132:135], v[172:175], v[44:47]
	v_mfma_f32_16x16x32_bf16 v[36:39], v[124:127], v[190:193], v[36:39]
	v_mfma_f32_16x16x32_bf16 v[28:31], v[132:135], v[190:193], v[28:31]
	v_mfma_f32_16x16x32_bf16 v[20:23], v[124:127], v[202:205], v[20:23]
	v_mfma_f32_16x16x32_bf16 v[12:15], v[132:135], v[202:205], v[12:15]
	v_mfma_f32_16x16x32_bf16 v[64:67], v[128:131], v[168:171], v[64:67]
	v_mfma_f32_16x16x32_bf16 v[60:63], v[136:139], v[168:171], v[60:63]
	v_mfma_f32_16x16x32_bf16 v[52:55], v[128:131], v[186:189], v[52:55]
	v_mfma_f32_16x16x32_bf16 v[44:47], v[136:139], v[186:189], v[44:47]
	v_mfma_f32_16x16x32_bf16 v[36:39], v[128:131], v[194:197], v[36:39]
	v_mfma_f32_16x16x32_bf16 v[28:31], v[136:139], v[194:197], v[28:31]
	v_mfma_f32_16x16x32_bf16 v[20:23], v[128:131], v[206:209], v[20:23]
	v_mfma_f32_16x16x32_bf16 v[12:15], v[136:139], v[206:209], v[12:15]
	s_setprio 0
	s_setprio 1
	v_mfma_f32_16x16x32_bf16 v[56:59], v[148:151], v[164:167], v[56:59]
	v_mfma_f32_16x16x32_bf16 v[48:51], v[156:159], v[164:167], v[48:51]
	v_mfma_f32_16x16x32_bf16 v[40:43], v[148:151], v[172:175], v[40:43]
	v_mfma_f32_16x16x32_bf16 v[32:35], v[156:159], v[172:175], v[32:35]
	v_mfma_f32_16x16x32_bf16 v[24:27], v[148:151], v[190:193], v[24:27]
	v_mfma_f32_16x16x32_bf16 v[16:19], v[156:159], v[190:193], v[16:19]
	v_mfma_f32_16x16x32_bf16 v[8:11], v[148:151], v[202:205], v[8:11]
	v_mfma_f32_16x16x32_bf16 v[4:7], v[156:159], v[202:205], v[4:7]
	v_mfma_f32_16x16x32_bf16 v[56:59], v[152:155], v[168:171], v[56:59]
	v_mfma_f32_16x16x32_bf16 v[48:51], v[160:163], v[168:171], v[48:51]
	v_mfma_f32_16x16x32_bf16 v[40:43], v[152:155], v[186:189], v[40:43]
	v_mfma_f32_16x16x32_bf16 v[32:35], v[160:163], v[186:189], v[32:35]
	v_mfma_f32_16x16x32_bf16 v[24:27], v[152:155], v[194:197], v[24:27]
	v_mfma_f32_16x16x32_bf16 v[16:19], v[160:163], v[194:197], v[16:19]
	v_mfma_f32_16x16x32_bf16 v[8:11], v[152:155], v[206:209], v[8:11]
	v_mfma_f32_16x16x32_bf16 v[4:7], v[160:163], v[206:209], v[4:7]
	s_setprio 0
	s_barrier
	s_add_i32 s30, 0, 0x18000
	s_add_i32 s31, 0, 0x1c000
	v_add_u32_e32 v136, s30, v198
	v_add_u32_e32 v160, s31, v198
	ds_read_b128 v[124:127], v136
	ds_read_b128 v[128:131], v136 offset:1024
	ds_read_b128 v[132:135], v136 offset:2048
	ds_read_b128 v[136:139], v136 offset:3072
	ds_read_b128 v[148:151], v160
	ds_read_b128 v[152:155], v160 offset:1024
	ds_read_b128 v[156:159], v160 offset:2048
	ds_read_b128 v[160:163], v160 offset:3072
	s_add_u32 s20, s36, 0x160000
	s_addc_u32 s21, s37, 0
	s_mov_b32 m0, s45
	ds_read_b128 v[164:167], v200 offset:32768
	ds_read_b128 v[168:171], v200 offset:33792
	ds_read_b128 v[172:175], v200 offset:34816
	ds_read_b128 v[186:189], v200 offset:35840
	ds_read_b128 v[190:193], v200 offset:36864
	ds_read_b128 v[194:197], v200 offset:37888
	ds_read_b128 v[202:205], v200 offset:38912
	ds_read_b128 v[206:209], v200 offset:39936
	global_load_lds_dwordx4 v176, s[20:21]
	s_mov_b32 m0, s46
	s_nop 0
	global_load_lds_dwordx4 v178, s[20:21]
	s_waitcnt vmcnt(8)
	s_waitcnt lgkmcnt(0)
	s_barrier
	s_setprio 1
	s_waitcnt lgkmcnt(0)
	v_mfma_f32_16x16x32_bf16 v[144:147], v[124:127], v[164:167], v[144:147]
	v_mfma_f32_16x16x32_bf16 v[140:143], v[132:135], v[164:167], v[140:143]
	v_mfma_f32_16x16x32_bf16 v[112:115], v[124:127], v[172:175], v[112:115]
	v_mfma_f32_16x16x32_bf16 v[108:111], v[132:135], v[172:175], v[108:111]
	v_mfma_f32_16x16x32_bf16 v[100:103], v[124:127], v[190:193], v[100:103]
	v_mfma_f32_16x16x32_bf16 v[92:95], v[132:135], v[190:193], v[92:95]
	v_mfma_f32_16x16x32_bf16 v[84:87], v[124:127], v[202:205], v[84:87]
	v_mfma_f32_16x16x32_bf16 v[76:79], v[132:135], v[202:205], v[76:79]
	v_mfma_f32_16x16x32_bf16 v[144:147], v[128:131], v[168:171], v[144:147]
	v_mfma_f32_16x16x32_bf16 v[140:143], v[136:139], v[168:171], v[140:143]
	v_mfma_f32_16x16x32_bf16 v[112:115], v[128:131], v[186:189], v[112:115]
	v_mfma_f32_16x16x32_bf16 v[108:111], v[136:139], v[186:189], v[108:111]
	v_mfma_f32_16x16x32_bf16 v[100:103], v[128:131], v[194:197], v[100:103]
	v_mfma_f32_16x16x32_bf16 v[92:95], v[136:139], v[194:197], v[92:95]
	v_mfma_f32_16x16x32_bf16 v[84:87], v[128:131], v[206:209], v[84:87]
	v_mfma_f32_16x16x32_bf16 v[76:79], v[136:139], v[206:209], v[76:79]
	s_setprio 0
	s_setprio 1
	v_mfma_f32_16x16x32_bf16 v[120:123], v[148:151], v[164:167], v[120:123]
	v_mfma_f32_16x16x32_bf16 v[116:119], v[156:159], v[164:167], v[116:119]
	v_mfma_f32_16x16x32_bf16 v[104:107], v[148:151], v[172:175], v[104:107]
	v_mfma_f32_16x16x32_bf16 v[96:99], v[156:159], v[172:175], v[96:99]
	v_mfma_f32_16x16x32_bf16 v[88:91], v[148:151], v[190:193], v[88:91]
	v_mfma_f32_16x16x32_bf16 v[80:83], v[156:159], v[190:193], v[80:83]
	v_mfma_f32_16x16x32_bf16 v[72:75], v[148:151], v[202:205], v[72:75]
	v_mfma_f32_16x16x32_bf16 v[68:71], v[156:159], v[202:205], v[68:71]
	v_mfma_f32_16x16x32_bf16 v[120:123], v[152:155], v[168:171], v[120:123]
	v_mfma_f32_16x16x32_bf16 v[116:119], v[160:163], v[168:171], v[116:119]
	v_mfma_f32_16x16x32_bf16 v[104:107], v[152:155], v[186:189], v[104:107]
	v_mfma_f32_16x16x32_bf16 v[96:99], v[160:163], v[186:189], v[96:99]
	v_mfma_f32_16x16x32_bf16 v[88:91], v[152:155], v[194:197], v[88:91]
	v_mfma_f32_16x16x32_bf16 v[80:83], v[160:163], v[194:197], v[80:83]
	v_mfma_f32_16x16x32_bf16 v[72:75], v[152:155], v[206:209], v[72:75]
	v_mfma_f32_16x16x32_bf16 v[68:71], v[160:163], v[206:209], v[68:71]
	s_setprio 0
	s_barrier
;     __device__ __forceinline__ void operator()(const f32x4 (&acc)[2][2][4][2], const Unit& u, int wr, int wc, int fr, int fq) const {
;         const int row0 = u.pm * BM + wr * 64 + fr; const int col0 = u.pn * BM + wc * 32 + 8 * fq;
;         const float* gp = gate + (size_t)((u.pm * BM) >> 12) * gstride + col0;
;         f32x4 gv[2][2];
; #pragma unroll
;         for (int bj = 0; bj < 2; ++bj)
; #pragma unroll
;             for (int n = 0; n < 2; ++n) gv[bj][n] = *(const f32x4*)(gp + bj * HALF + n * 4);
;         if (base_f32) { const float* bp = (const float*)base;
; #pragma unroll
;             for (int ai = 0; ai < 2; ++ai)
; #pragma unroll
;                 for (int m2 = 0; m2 < 2; ++m2) { f32x4 bs[2][2][2];
; #pragma unroll
;                     for (int mm = 0; mm < 2; ++mm) { const size_t off = (size_t)(row0 + ai * HALF + (2 * m2 + mm) * 16) * ldc + col0;
; #pragma unroll
;                         for (int bj = 0; bj < 2; ++bj)
; #pragma unroll
;                             for (int n = 0; n < 2; ++n) bs[mm][bj][n] = *(const f32x4*)(bp + off + bj * HALF + n * 4); }
; #pragma unroll
;                     for (int mm = 0; mm < 2; ++mm) { const size_t off = (size_t)(row0 + ai * HALF + (2 * m2 + mm) * 16) * ldc + col0;
; #pragma unroll
;                         for (int bj = 0; bj < 2; ++bj) { const f32x4 v0 = bs[mm][bj][0] + gv[bj][0] * acc[ai][bj][2 * m2 + mm][0], v1 = bs[mm][bj][1] + gv[bj][1] * acc[ai][bj][2 * m2 + mm][1];
;                             u32x4 w; w.x = cvt_pk_bf16(v0[0], v0[1]); w.y = cvt_pk_bf16(v0[2], v0[3]); w.z = cvt_pk_bf16(v1[0], v1[1]); w.w = cvt_pk_bf16(v1[2], v1[3]);
;                             *(u32x4*)(out + off + bj * HALF) = w; } }
;                     asm volatile("" ::: "memory"); }
;         } else { const bf16_t* bp = (const bf16_t*)base;
; #pragma unroll
;             for (int ai = 0; ai < 2; ++ai) { u32x4 bs[4][2];
; #pragma unroll
; template <class Epi, class Sched, bool ALIGN_EPI = false, bool SP2 = false>
; __device__ __forceinline__ void gemm_phase(PG8_LAS unsigned char* lds, const Gemm g, const Sched& S, const Epi& E) {
;     ...
;             PG8_LDA(At, 1, 1); PG8_STAGE(PG8_SB(1, 0), b3, voffB); PG8_STAGE(PG8_SB(1, 1), b3 + hstep, voffB); PG8_STAGE(PG8_SA(1, 0), a3, voffA);
;             PG8_WAIT_V(8); PG8_WAIT_L(0); PG8_BAR; PG8_MMA(1, 0, At, B0); PG8_MMA(1, 1, At, B1); PG8_BAR; PG8_SCHED;
	s_add_i32 s20, s30, s13
	v_lshl_add_u64 v[210:211], v[210:211], 0, s[28:29]
	s_mov_b32 m0, s20
	ds_read_b128 v[164:167], v200 offset:49152
	ds_read_b128 v[168:171], v200 offset:50176
	ds_read_b128 v[172:175], v200 offset:51200
	ds_read_b128 v[186:189], v200 offset:52224
	ds_read_b128 v[190:193], v200 offset:53248
	ds_read_b128 v[194:197], v200 offset:54272
	ds_read_b128 v[202:205], v200 offset:55296
	ds_read_b128 v[206:209], v200 offset:56320
	global_load_lds_dwordx4 v[210:211], off
	s_add_i32 m0, s20, 0x2000
	s_add_u32 s20, s26, 0x160080
	v_lshl_add_u64 v[210:211], v[212:213], 0, s[28:29]
	s_addc_u32 s21, s27, 0
	s_add_i32 s26, s31, s13
	global_load_lds_dwordx4 v[210:211], off
	s_mov_b32 m0, s26
	s_nop 0
	global_load_lds_dwordx4 v2, s[20:21]
	s_add_i32 m0, s26, 0x2000
	s_nop 0
	global_load_lds_dwordx4 v180, s[20:21]
	v_lshl_add_u64 v[210:211], v[214:215], 0, s[28:29]
	s_mov_b32 m0, s49
	s_nop 0
	global_load_lds_dwordx4 v[210:211], off
	v_lshl_add_u64 v[210:211], v[216:217], 0, s[28:29]
	s_mov_b32 m0, s50
	s_nop 0
	global_load_lds_dwordx4 v[210:211], off
	s_waitcnt vmcnt(8)
	s_waitcnt lgkmcnt(0)
	s_barrier
	s_setprio 1
	s_waitcnt lgkmcnt(0)
	v_mfma_f32_16x16x32_bf16 v[64:67], v[124:127], v[164:167], v[64:67]
	v_mfma_f32_16x16x32_bf16 v[60:63], v[132:135], v[164:167], v[60:63]
	v_mfma_f32_16x16x32_bf16 v[52:55], v[124:127], v[172:175], v[52:55]
	v_mfma_f32_16x16x32_bf16 v[44:47], v[132:135], v[172:175], v[44:47]
	v_mfma_f32_16x16x32_bf16 v[36:39], v[124:127], v[190:193], v[36:39]
	v_mfma_f32_16x16x32_bf16 v[28:31], v[132:135], v[190:193], v[28:31]
	v_mfma_f32_16x16x32_bf16 v[20:23], v[124:127], v[202:205], v[20:23]
	v_mfma_f32_16x16x32_bf16 v[12:15], v[132:135], v[202:205], v[12:15]
	v_mfma_f32_16x16x32_bf16 v[64:67], v[128:131], v[168:171], v[64:67]
	v_mfma_f32_16x16x32_bf16 v[60:63], v[136:139], v[168:171], v[60:63]
	v_mfma_f32_16x16x32_bf16 v[52:55], v[128:131], v[186:189], v[52:55]
	v_mfma_f32_16x16x32_bf16 v[44:47], v[136:139], v[186:189], v[44:47]
	v_mfma_f32_16x16x32_bf16 v[36:39], v[128:131], v[194:197], v[36:39]
	v_mfma_f32_16x16x32_bf16 v[28:31], v[136:139], v[194:197], v[28:31]
	v_mfma_f32_16x16x32_bf16 v[20:23], v[128:131], v[206:209], v[20:23]
	v_mfma_f32_16x16x32_bf16 v[12:15], v[136:139], v[206:209], v[12:15]
	s_setprio 0
	s_setprio 1
	v_mfma_f32_16x16x32_bf16 v[56:59], v[148:151], v[164:167], v[56:59]
	v_mfma_f32_16x16x32_bf16 v[48:51], v[156:159], v[164:167], v[48:51]
	v_mfma_f32_16x16x32_bf16 v[40:43], v[148:151], v[172:175], v[40:43]
	v_mfma_f32_16x16x32_bf16 v[32:35], v[156:159], v[172:175], v[32:35]
	v_mfma_f32_16x16x32_bf16 v[24:27], v[148:151], v[190:193], v[24:27]
	v_mfma_f32_16x16x32_bf16 v[16:19], v[156:159], v[190:193], v[16:19]
	v_mfma_f32_16x16x32_bf16 v[8:11], v[148:151], v[202:205], v[8:11]
	v_mfma_f32_16x16x32_bf16 v[4:7], v[156:159], v[202:205], v[4:7]
	v_mfma_f32_16x16x32_bf16 v[56:59], v[152:155], v[168:171], v[56:59]
	v_mfma_f32_16x16x32_bf16 v[48:51], v[160:163], v[168:171], v[48:51]
	v_mfma_f32_16x16x32_bf16 v[40:43], v[152:155], v[186:189], v[40:43]
	v_mfma_f32_16x16x32_bf16 v[32:35], v[160:163], v[186:189], v[32:35]
	v_mfma_f32_16x16x32_bf16 v[24:27], v[152:155], v[194:197], v[24:27]
	v_mfma_f32_16x16x32_bf16 v[16:19], v[160:163], v[194:197], v[16:19]
	v_mfma_f32_16x16x32_bf16 v[8:11], v[152:155], v[206:209], v[8:11]
	v_mfma_f32_16x16x32_bf16 v[4:7], v[160:163], v[206:209], v[4:7]
	s_setprio 0
	s_barrier
	s_add_i32 s42, s42, 2
	s_add_u32 s40, s40, 0x100
	s_addc_u32 s41, s41, 0
	s_cmpk_gt_u32 s42, 0x55
	s_mov_b64 s[20:21], s[24:25]
	s_cbranch_scc0 .LBB0_2238
	v_lshl_or_b32 v148, s54, 8, v199
	s_ashr_i32 s20, s33, 4
	s_mul_hi_i32 s21, s20, 0xc000
	s_mul_i32 s20, s20, 0xc000
	v_ashrrev_i32_e32 v149, 31, v148
	v_lshl_add_u32 v150, s33, 8, v1
	s_add_u32 s20, s47, s20
	v_ashrrev_i32_e32 v151, 31, v150
	v_lshlrev_b64 v[186:187], 1, v[148:149]
	s_addc_u32 s21, s48, s21
	v_lshl_add_u64 v[188:189], s[14:15], 0, v[186:187]
	v_lshlrev_b64 v[190:191], 12, v[150:151]
	v_lshl_add_u64 v[124:125], v[148:149], 2, s[20:21]
	v_lshl_add_u64 v[148:149], v[188:189], 0, v[190:191]
	flat_load_dwordx4 v[136:139], v[124:125]
	flat_load_dwordx4 v[132:135], v[124:125] offset:16
	flat_load_dwordx4 v[128:131], v[124:125] offset:512
	s_nop 0
	flat_load_dwordx4 v[124:127], v[124:125] offset:528
	s_nop 0
	flat_load_dwordx4 v[202:205], v[148:149]
	flat_load_dwordx4 v[172:175], v[148:149] offset:256
	v_or_b32_e32 v148, 16, v150
	v_ashrrev_i32_e32 v149, 31, v148
	v_lshlrev_b64 v[196:197], 12, v[148:149]
	v_lshl_add_u64 v[148:149], v[188:189], 0, v[196:197]
	flat_load_dwordx4 v[168:171], v[148:149]
	flat_load_dwordx4 v[164:167], v[148:149] offset:256
	v_or_b32_e32 v148, 32, v150
	v_ashrrev_i32_e32 v149, 31, v148
	v_lshlrev_b64 v[194:195], 12, v[148:149]
	v_lshl_add_u64 v[148:149], v[188:189], 0, v[194:195]
	flat_load_dwordx4 v[160:163], v[148:149]
	flat_load_dwordx4 v[152:155], v[148:149] offset:256
	v_or_b32_e32 v148, 48, v150
	v_ashrrev_i32_e32 v149, 31, v148
	v_lshlrev_b64 v[192:193], 12, v[148:149]
	v_lshl_add_u64 v[148:149], v[188:189], 0, v[192:193]
	flat_load_dwordx4 v[156:159], v[148:149]
	s_nop 0
	flat_load_dwordx4 v[148:151], v[148:149] offset:256
	s_mov_b64 s[20:21], 0x80000
	s_and_b64 vcc, exec, s[38:39]
	s_mov_b32 s54, s52
	s_mov_b32 s33, s53
	s_mov_b64 s[24:25], s[22:23]
	s_waitcnt vmcnt(0) lgkmcnt(0)
; __device__ __forceinline__ unsigned cvt_pk_bf16(float lo, float hi) { unsigned r; asm volatile("v_cvt_pk_bf16_f32 %0, %1, %2" : "=v"(r) : "v"(lo), "v"(hi)); return r; }
;     __device__ __forceinline__ void operator()(const f32x4 (&acc)[2][2][4][2], const Unit& u, int wr, int wc, int fr, int fq) const {
;     ...
;                 for (int m = 0; m < 4; ++m) { const size_t off = (size_t)(row0 + ai * HALF + m * 16) * ldc + col0;
; #pragma unroll
;                     for (int bj = 0; bj < 2; ++bj) { const u32x4 r = bs[m][bj]; const f32x4 a0 = acc[ai][bj][m][0], a1 = acc[ai][bj][m][1];
;                         u32x4 w;
;                         w.x = cvt_pk_bf16(__builtin_bit_cast(float, r.x << 16) + gv[bj][0][0] * a0[0], __builtin_bit_cast(float, r.x & 0xffff0000u) + gv[bj][0][1] * a0[1]);
;                         w.y = cvt_pk_bf16(__builtin_bit_cast(float, r.y << 16) + gv[bj][0][2] * a0[2], __builtin_bit_cast(float, r.y & 0xffff0000u) + gv[bj][0][3] * a0[3]);
;                         w.z = cvt_pk_bf16(__builtin_bit_cast(float, r.z << 16) + gv[bj][1][0] * a1[0], __builtin_bit_cast(float, r.z & 0xffff0000u) + gv[bj][1][1] * a1[1]);
;                         w.w = cvt_pk_bf16(__builtin_bit_cast(float, r.w << 16) + gv[bj][1][2] * a1[2], __builtin_bit_cast(float, r.w & 0xffff0000u) + gv[bj][1][3] * a1[3]);
;                         *(u32x4*)(out + off + bj * HALF) = w; } }
	v_lshlrev_b32_e32 v201, 16, v202
	v_fmac_f32_e32 v201, v144, v136
	v_and_b32_e32 v144, 0xffff0000, v202
	v_fmac_f32_e32 v144, v145, v137
	v_lshlrev_b32_e32 v145, 16, v203
	v_fmac_f32_e32 v145, v146, v138
	v_and_b32_e32 v146, 0xffff0000, v203
	v_fmac_f32_e32 v146, v147, v139
	v_cvt_pk_bf16_f32 v144, v201, v144
	v_cvt_pk_bf16_f32 v145, v145, v146
	v_lshlrev_b32_e32 v146, 16, v204
	v_fmac_f32_e32 v146, v140, v132
	v_and_b32_e32 v140, 0xffff0000, v204
	v_fmac_f32_e32 v140, v141, v133
	v_cvt_pk_bf16_f32 v146, v146, v140
	v_lshlrev_b32_e32 v140, 16, v205
	v_fmac_f32_e32 v140, v142, v134
	v_lshlrev_b32_e32 v142, 16, v172
	v_and_b32_e32 v141, 0xffff0000, v205
	v_fmac_f32_e32 v142, v120, v128
	v_and_b32_e32 v120, 0xffff0000, v172
	v_fmac_f32_e32 v141, v143, v135
	v_fmac_f32_e32 v120, v121, v129
	v_lshlrev_b32_e32 v121, 16, v173
	v_cvt_pk_bf16_f32 v147, v140, v141
	v_lshl_add_u64 v[140:141], s[14:15], 0, v[190:191]
	v_fmac_f32_e32 v121, v122, v130
	v_and_b32_e32 v122, 0xffff0000, v173
	v_lshl_add_u64 v[140:141], v[140:141], 0, v[186:187]
	v_fmac_f32_e32 v122, v123, v131
	flat_store_dwordx4 v[140:141], v[144:147]
	v_cvt_pk_bf16_f32 v120, v142, v120
	v_cvt_pk_bf16_f32 v121, v121, v122
	v_lshlrev_b32_e32 v122, 16, v174
	v_fmac_f32_e32 v122, v116, v124
	v_and_b32_e32 v116, 0xffff0000, v174
	v_fmac_f32_e32 v116, v117, v125
	v_cvt_pk_bf16_f32 v122, v122, v116
	v_lshlrev_b32_e32 v116, 16, v175
	v_fmac_f32_e32 v116, v118, v126
	v_and_b32_e32 v117, 0xffff0000, v175
	v_fmac_f32_e32 v117, v119, v127
	v_cvt_pk_bf16_f32 v123, v116, v117
	v_lshlrev_b32_e32 v116, 16, v168
	v_fmac_f32_e32 v116, v112, v136
	v_and_b32_e32 v112, 0xffff0000, v168
	v_fmac_f32_e32 v112, v113, v137
	v_lshlrev_b32_e32 v113, 16, v169
	v_fmac_f32_e32 v113, v114, v138
	v_and_b32_e32 v114, 0xffff0000, v169
	v_fmac_f32_e32 v114, v115, v139
	flat_store_dwordx4 v[140:141], v[120:123] offset:256
	v_cvt_pk_bf16_f32 v112, v116, v112
	v_cvt_pk_bf16_f32 v113, v113, v114
	v_lshlrev_b32_e32 v114, 16, v170
	v_fmac_f32_e32 v114, v108, v132
	v_and_b32_e32 v108, 0xffff0000, v170
	v_fmac_f32_e32 v108, v109, v133
	v_cvt_pk_bf16_f32 v114, v114, v108
	v_lshlrev_b32_e32 v108, 16, v171
	v_fmac_f32_e32 v108, v110, v134
	v_lshlrev_b32_e32 v110, 16, v164
	v_and_b32_e32 v109, 0xffff0000, v171
	v_fmac_f32_e32 v110, v104, v128
	v_and_b32_e32 v104, 0xffff0000, v164
	v_fmac_f32_e32 v109, v111, v135
	v_fmac_f32_e32 v104, v105, v129
	v_lshlrev_b32_e32 v105, 16, v165
	v_cvt_pk_bf16_f32 v115, v108, v109
	v_lshl_add_u64 v[108:109], s[14:15], 0, v[196:197]
	v_fmac_f32_e32 v105, v106, v130
	v_and_b32_e32 v106, 0xffff0000, v165
	v_lshl_add_u64 v[108:109], v[108:109], 0, v[186:187]
	v_fmac_f32_e32 v106, v107, v131
	flat_store_dwordx4 v[108:109], v[112:115]
	v_cvt_pk_bf16_f32 v104, v110, v104
	v_cvt_pk_bf16_f32 v105, v105, v106
	v_lshlrev_b32_e32 v106, 16, v166
	v_fmac_f32_e32 v106, v96, v124
	v_and_b32_e32 v96, 0xffff0000, v166
	v_fmac_f32_e32 v96, v97, v125
	v_cvt_pk_bf16_f32 v106, v106, v96
	v_lshlrev_b32_e32 v96, 16, v167
	v_and_b32_e32 v97, 0xffff0000, v167
	v_fmac_f32_e32 v96, v98, v126
	v_fmac_f32_e32 v97, v99, v127
	v_cvt_pk_bf16_f32 v107, v96, v97
	v_lshlrev_b32_e32 v96, 16, v160
	v_and_b32_e32 v97, 0xffff0000, v160
	v_fmac_f32_e32 v96, v100, v136
	v_fmac_f32_e32 v97, v101, v137
	flat_store_dwordx4 v[108:109], v[104:107] offset:256
	v_cvt_pk_bf16_f32 v96, v96, v97
	v_lshlrev_b32_e32 v97, 16, v161
	v_and_b32_e32 v98, 0xffff0000, v161
	v_fmac_f32_e32 v97, v102, v138
	v_fmac_f32_e32 v98, v103, v139
	v_cvt_pk_bf16_f32 v97, v97, v98
	v_lshlrev_b32_e32 v98, 16, v162
	v_fmac_f32_e32 v98, v92, v132
	v_and_b32_e32 v92, 0xffff0000, v162
	v_fmac_f32_e32 v92, v93, v133
	v_cvt_pk_bf16_f32 v98, v98, v92
	v_lshlrev_b32_e32 v92, 16, v163
	v_fmac_f32_e32 v92, v94, v134
	v_lshlrev_b32_e32 v94, 16, v152
	v_and_b32_e32 v93, 0xffff0000, v163
	v_fmac_f32_e32 v94, v88, v128
	v_and_b32_e32 v88, 0xffff0000, v152
	v_fmac_f32_e32 v93, v95, v135
	v_fmac_f32_e32 v88, v89, v129
	v_lshlrev_b32_e32 v89, 16, v153
	v_cvt_pk_bf16_f32 v99, v92, v93
	v_lshl_add_u64 v[92:93], s[14:15], 0, v[194:195]
	v_fmac_f32_e32 v89, v90, v130
	v_and_b32_e32 v90, 0xffff0000, v153
	v_lshl_add_u64 v[92:93], v[92:93], 0, v[186:187]
	v_fmac_f32_e32 v90, v91, v131
	flat_store_dwordx4 v[92:93], v[96:99]
	v_cvt_pk_bf16_f32 v88, v94, v88
	v_cvt_pk_bf16_f32 v89, v89, v90
	v_lshlrev_b32_e32 v90, 16, v154
	v_fmac_f32_e32 v90, v80, v124
	v_and_b32_e32 v80, 0xffff0000, v154
	v_fmac_f32_e32 v80, v81, v125
	v_cvt_pk_bf16_f32 v90, v90, v80
	v_lshlrev_b32_e32 v80, 16, v155
	v_and_b32_e32 v81, 0xffff0000, v155
	v_fmac_f32_e32 v80, v82, v126
	v_fmac_f32_e32 v81, v83, v127
	v_cvt_pk_bf16_f32 v91, v80, v81
	v_lshlrev_b32_e32 v80, 16, v156
	v_and_b32_e32 v81, 0xffff0000, v156
	v_fmac_f32_e32 v80, v84, v136
	v_fmac_f32_e32 v81, v85, v137
	flat_store_dwordx4 v[92:93], v[88:91] offset:256
	v_cvt_pk_bf16_f32 v80, v80, v81
	v_lshlrev_b32_e32 v81, 16, v157
	v_and_b32_e32 v82, 0xffff0000, v157
	v_fmac_f32_e32 v81, v86, v138
	v_fmac_f32_e32 v82, v87, v139
	v_cvt_pk_bf16_f32 v81, v81, v82
	v_lshlrev_b32_e32 v82, 16, v158
	v_fmac_f32_e32 v82, v76, v132
	v_and_b32_e32 v76, 0xffff0000, v158
	v_fmac_f32_e32 v76, v77, v133
	v_cvt_pk_bf16_f32 v82, v82, v76
	v_lshlrev_b32_e32 v76, 16, v159
	v_fmac_f32_e32 v76, v78, v134
	v_lshlrev_b32_e32 v78, 16, v148
	v_and_b32_e32 v77, 0xffff0000, v159
	v_fmac_f32_e32 v78, v72, v128
	v_and_b32_e32 v72, 0xffff0000, v148
	v_fmac_f32_e32 v77, v79, v135
	v_fmac_f32_e32 v72, v73, v129
	v_lshlrev_b32_e32 v73, 16, v149
	v_cvt_pk_bf16_f32 v83, v76, v77
	v_lshl_add_u64 v[76:77], s[14:15], 0, v[192:193]
	v_fmac_f32_e32 v73, v74, v130
	v_and_b32_e32 v74, 0xffff0000, v149
; __device__ __forceinline__ unsigned cvt_pk_bf16(float lo, float hi) { unsigned r; asm volatile("v_cvt_pk_bf16_f32 %0, %1, %2" : "=v"(r) : "v"(lo), "v"(hi)); return r; }
;     __device__ __forceinline__ void operator()(const f32x4 (&acc)[2][2][4][2], const Unit& u, int wr, int wc, int fr, int fq) const {
;     ...
;             for (int ai = 0; ai < 2; ++ai) { u32x4 bs[4][2];
; #pragma unroll
;                 for (int m = 0; m < 4; ++m) { const size_t off = (size_t)(row0 + ai * HALF + m * 16) * ldc + col0;
; #pragma unroll
;                     for (int bj = 0; bj < 2; ++bj) bs[m][bj] = *(const u32x4*)(bp + off + bj * HALF); }
; #pragma unroll
;                 for (int m = 0; m < 4; ++m) { const size_t off = (size_t)(row0 + ai * HALF + m * 16) * ldc + col0;
; #pragma unroll
;                     for (int bj = 0; bj < 2; ++bj) { const u32x4 r = bs[m][bj]; const f32x4 a0 = acc[ai][bj][m][0], a1 = acc[ai][bj][m][1];
;                         u32x4 w;
;                         w.x = cvt_pk_bf16(__builtin_bit_cast(float, r.x << 16) + gv[bj][0][0] * a0[0], __builtin_bit_cast(float, r.x & 0xffff0000u) + gv[bj][0][1] * a0[1]);
;                         w.y = cvt_pk_bf16(__builtin_bit_cast(float, r.y << 16) + gv[bj][0][2] * a0[2], __builtin_bit_cast(float, r.y & 0xffff0000u) + gv[bj][0][3] * a0[3]);
;                         w.z = cvt_pk_bf16(__builtin_bit_cast(float, r.z << 16) + gv[bj][1][0] * a1[0], __builtin_bit_cast(float, r.z & 0xffff0000u) + gv[bj][1][1] * a1[1]);
;                         w.w = cvt_pk_bf16(__builtin_bit_cast(float, r.w << 16) + gv[bj][1][2] * a1[2], __builtin_bit_cast(float, r.w & 0xffff0000u) + gv[bj][1][3] * a1[3]);
;                         *(u32x4*)(out + off + bj * HALF) = w; } }
	v_lshl_add_u64 v[76:77], v[76:77], 0, v[186:187]
	v_fmac_f32_e32 v74, v75, v131
	flat_store_dwordx4 v[76:77], v[80:83]
	v_cvt_pk_bf16_f32 v72, v78, v72
	v_cvt_pk_bf16_f32 v73, v73, v74
	v_lshlrev_b32_e32 v74, 16, v150
	v_fmac_f32_e32 v74, v68, v124
	v_and_b32_e32 v68, 0xffff0000, v150
	v_fmac_f32_e32 v68, v69, v125
	v_cvt_pk_bf16_f32 v74, v74, v68
	v_lshlrev_b32_e32 v68, 16, v151
	v_and_b32_e32 v69, 0xffff0000, v151
	v_fmac_f32_e32 v68, v70, v126
	v_fmac_f32_e32 v69, v71, v127
	v_cvt_pk_bf16_f32 v75, v68, v69
	flat_store_dwordx4 v[76:77], v[72:75] offset:256
	v_lshl_add_u64 v[100:101], v[190:191], 0, s[20:21]
	v_lshl_add_u64 v[68:69], v[188:189], 0, v[100:101]
	flat_load_dwordx4 v[72:75], v[68:69]
	flat_load_dwordx4 v[76:79], v[68:69] offset:256
	s_mov_b64 s[20:21], 0x90000
	v_lshl_add_u64 v[102:103], v[190:191], 0, s[20:21]
	v_lshl_add_u64 v[68:69], v[188:189], 0, v[102:103]
	flat_load_dwordx4 v[80:83], v[68:69]
	flat_load_dwordx4 v[84:87], v[68:69] offset:256
	s_mov_b64 s[20:21], 0xa0000
	v_lshl_add_u64 v[104:105], v[190:191], 0, s[20:21]
	v_lshl_add_u64 v[68:69], v[188:189], 0, v[104:105]
	flat_load_dwordx4 v[88:91], v[68:69]
	flat_load_dwordx4 v[92:95], v[68:69] offset:256
	s_mov_b64 s[20:21], 0xb0000
	v_lshl_add_u64 v[106:107], v[190:191], 0, s[20:21]
	v_lshl_add_u64 v[68:69], v[188:189], 0, v[106:107]
	flat_load_dwordx4 v[96:99], v[68:69]
	s_nop 0
	flat_load_dwordx4 v[68:71], v[68:69] offset:256
	s_mov_b64 s[20:21], s[16:17]
	s_waitcnt vmcnt(0) lgkmcnt(0)
; __device__ __forceinline__ unsigned cvt_pk_bf16(float lo, float hi) { unsigned r; asm volatile("v_cvt_pk_bf16_f32 %0, %1, %2" : "=v"(r) : "v"(lo), "v"(hi)); return r; }
; #define PG8_WAIT_V(n) asm volatile("s_waitcnt vmcnt(" #n ")" ::: "memory")
; #define PG8_BAR __builtin_amdgcn_s_barrier()
;     __device__ __forceinline__ void operator()(const f32x4 (&acc)[2][2][4][2], const Unit& u, int wr, int wc, int fr, int fq) const {
;     ...
;                 for (int m = 0; m < 4; ++m) { const size_t off = (size_t)(row0 + ai * HALF + m * 16) * ldc + col0;
; #pragma unroll
;                     for (int bj = 0; bj < 2; ++bj) { const u32x4 r = bs[m][bj]; const f32x4 a0 = acc[ai][bj][m][0], a1 = acc[ai][bj][m][1];
;                         u32x4 w;
;                         w.x = cvt_pk_bf16(__builtin_bit_cast(float, r.x << 16) + gv[bj][0][0] * a0[0], __builtin_bit_cast(float, r.x & 0xffff0000u) + gv[bj][0][1] * a0[1]);
;                         w.y = cvt_pk_bf16(__builtin_bit_cast(float, r.y << 16) + gv[bj][0][2] * a0[2], __builtin_bit_cast(float, r.y & 0xffff0000u) + gv[bj][0][3] * a0[3]);
;                         w.z = cvt_pk_bf16(__builtin_bit_cast(float, r.z << 16) + gv[bj][1][0] * a1[0], __builtin_bit_cast(float, r.z & 0xffff0000u) + gv[bj][1][1] * a1[1]);
;                         w.w = cvt_pk_bf16(__builtin_bit_cast(float, r.w << 16) + gv[bj][1][2] * a1[2], __builtin_bit_cast(float, r.w & 0xffff0000u) + gv[bj][1][3] * a1[3]);
;                         *(u32x4*)(out + off + bj * HALF) = w; } }
; template <class Epi, class Sched, bool ALIGN_EPI = false, bool SP2 = false>
; __device__ __forceinline__ void gemm_phase(PG8_LAS unsigned char* lds, const Gemm g, const Sched& S, const Epi& E) {
;     ...
;         if (!has_next) break;
; #pragma unroll
;         for (int a = 0; a < 2; ++a)
; #pragma unroll
;             for (int b = 0; b < 2; ++b)
; #pragma unroll
;                 for (int m = 0; m < 4; ++m)
; #pragma unroll
;                     for (int n = 0; n < 2; ++n) acc[a][b][m][n] = (f32x4){0.f, 0.f, 0.f, 0.f};
;         cur = nxt; cA = nA; cB = nB; ++ui;
;         if constexpr (ALIGN_EPI) { if (wr == 1) PG8_BAR; }
;     }
;     PG8_WAIT_V(0);
;     if constexpr (!ALIGN_EPI) { if (wr == 0) PG8_BAR; }
	v_lshlrev_b32_e32 v108, 16, v72
	v_fmac_f32_e32 v108, v64, v136
	v_and_b32_e32 v64, 0xffff0000, v72
	v_fmac_f32_e32 v64, v65, v137
	v_lshlrev_b32_e32 v65, 16, v73
	v_fmac_f32_e32 v65, v66, v138
	v_and_b32_e32 v66, 0xffff0000, v73
	v_fmac_f32_e32 v66, v67, v139
	v_cvt_pk_bf16_f32 v64, v108, v64
	v_cvt_pk_bf16_f32 v65, v65, v66
	v_lshlrev_b32_e32 v66, 16, v74
	v_fmac_f32_e32 v66, v60, v132
	v_and_b32_e32 v60, 0xffff0000, v74
	v_fmac_f32_e32 v60, v61, v133
	v_cvt_pk_bf16_f32 v66, v66, v60
	v_lshlrev_b32_e32 v60, 16, v75
	v_fmac_f32_e32 v60, v62, v134
	v_lshlrev_b32_e32 v62, 16, v76
	v_and_b32_e32 v61, 0xffff0000, v75
	v_fmac_f32_e32 v62, v56, v128
	v_and_b32_e32 v56, 0xffff0000, v76
	v_fmac_f32_e32 v61, v63, v135
	v_fmac_f32_e32 v56, v57, v129
	v_lshlrev_b32_e32 v57, 16, v77
	v_cvt_pk_bf16_f32 v67, v60, v61
	v_lshl_add_u64 v[60:61], s[14:15], 0, v[100:101]
	v_fmac_f32_e32 v57, v58, v130
	v_and_b32_e32 v58, 0xffff0000, v77
	v_lshl_add_u64 v[60:61], v[60:61], 0, v[186:187]
	v_fmac_f32_e32 v58, v59, v131
	flat_store_dwordx4 v[60:61], v[64:67]
	v_cvt_pk_bf16_f32 v56, v62, v56
	v_cvt_pk_bf16_f32 v57, v57, v58
	v_lshlrev_b32_e32 v58, 16, v78
	v_fmac_f32_e32 v58, v48, v124
	v_and_b32_e32 v48, 0xffff0000, v78
	v_fmac_f32_e32 v48, v49, v125
	v_cvt_pk_bf16_f32 v58, v58, v48
	v_lshlrev_b32_e32 v48, 16, v79
	v_and_b32_e32 v49, 0xffff0000, v79
	v_fmac_f32_e32 v48, v50, v126
	v_fmac_f32_e32 v49, v51, v127
	v_cvt_pk_bf16_f32 v59, v48, v49
	v_lshlrev_b32_e32 v48, 16, v80
	v_and_b32_e32 v49, 0xffff0000, v80
	v_fmac_f32_e32 v48, v52, v136
	v_fmac_f32_e32 v49, v53, v137
	flat_store_dwordx4 v[60:61], v[56:59] offset:256
	v_cvt_pk_bf16_f32 v48, v48, v49
	v_lshlrev_b32_e32 v49, 16, v81
	v_and_b32_e32 v50, 0xffff0000, v81
	v_fmac_f32_e32 v49, v54, v138
	v_fmac_f32_e32 v50, v55, v139
	v_cvt_pk_bf16_f32 v49, v49, v50
	v_lshlrev_b32_e32 v50, 16, v82
	v_fmac_f32_e32 v50, v44, v132
	v_and_b32_e32 v44, 0xffff0000, v82
	v_fmac_f32_e32 v44, v45, v133
	v_cvt_pk_bf16_f32 v50, v50, v44
	v_lshlrev_b32_e32 v44, 16, v83
	v_fmac_f32_e32 v44, v46, v134
	v_lshlrev_b32_e32 v46, 16, v84
	v_and_b32_e32 v45, 0xffff0000, v83
	v_fmac_f32_e32 v46, v40, v128
	v_and_b32_e32 v40, 0xffff0000, v84
	v_fmac_f32_e32 v45, v47, v135
	v_fmac_f32_e32 v40, v41, v129
	v_lshlrev_b32_e32 v41, 16, v85
	v_cvt_pk_bf16_f32 v51, v44, v45
	v_lshl_add_u64 v[44:45], s[14:15], 0, v[102:103]
	v_fmac_f32_e32 v41, v42, v130
	v_and_b32_e32 v42, 0xffff0000, v85
	v_lshl_add_u64 v[44:45], v[44:45], 0, v[186:187]
	v_fmac_f32_e32 v42, v43, v131
	flat_store_dwordx4 v[44:45], v[48:51]
	v_cvt_pk_bf16_f32 v40, v46, v40
	v_cvt_pk_bf16_f32 v41, v41, v42
	v_lshlrev_b32_e32 v42, 16, v86
	v_fmac_f32_e32 v42, v32, v124
	v_and_b32_e32 v32, 0xffff0000, v86
	v_fmac_f32_e32 v32, v33, v125
	v_cvt_pk_bf16_f32 v42, v42, v32
	v_lshlrev_b32_e32 v32, 16, v87
	v_and_b32_e32 v33, 0xffff0000, v87
	v_fmac_f32_e32 v32, v34, v126
	v_fmac_f32_e32 v33, v35, v127
	v_cvt_pk_bf16_f32 v43, v32, v33
	v_lshlrev_b32_e32 v32, 16, v88
	v_and_b32_e32 v33, 0xffff0000, v88
	v_fmac_f32_e32 v32, v36, v136
	v_fmac_f32_e32 v33, v37, v137
	flat_store_dwordx4 v[44:45], v[40:43] offset:256
	v_cvt_pk_bf16_f32 v32, v32, v33
	v_lshlrev_b32_e32 v33, 16, v89
	v_and_b32_e32 v34, 0xffff0000, v89
	v_fmac_f32_e32 v33, v38, v138
	v_fmac_f32_e32 v34, v39, v139
	v_cvt_pk_bf16_f32 v33, v33, v34
	v_lshlrev_b32_e32 v34, 16, v90
	v_fmac_f32_e32 v34, v28, v132
	v_and_b32_e32 v28, 0xffff0000, v90
	v_fmac_f32_e32 v28, v29, v133
	v_cvt_pk_bf16_f32 v34, v34, v28
	v_lshlrev_b32_e32 v28, 16, v91
	v_fmac_f32_e32 v28, v30, v134
	v_lshlrev_b32_e32 v30, 16, v92
	v_and_b32_e32 v29, 0xffff0000, v91
	v_fmac_f32_e32 v30, v24, v128
	v_and_b32_e32 v24, 0xffff0000, v92
	v_fmac_f32_e32 v29, v31, v135
	v_fmac_f32_e32 v24, v25, v129
	v_lshlrev_b32_e32 v25, 16, v93
	v_cvt_pk_bf16_f32 v35, v28, v29
	v_lshl_add_u64 v[28:29], s[14:15], 0, v[104:105]
	v_fmac_f32_e32 v25, v26, v130
	v_and_b32_e32 v26, 0xffff0000, v93
	v_lshl_add_u64 v[28:29], v[28:29], 0, v[186:187]
	v_fmac_f32_e32 v26, v27, v131
	flat_store_dwordx4 v[28:29], v[32:35]
	v_cvt_pk_bf16_f32 v24, v30, v24
	v_cvt_pk_bf16_f32 v25, v25, v26
	v_lshlrev_b32_e32 v26, 16, v94
	v_fmac_f32_e32 v26, v16, v124
	v_and_b32_e32 v16, 0xffff0000, v94
	v_fmac_f32_e32 v16, v17, v125
	v_cvt_pk_bf16_f32 v26, v26, v16
	v_lshlrev_b32_e32 v16, 16, v95
	v_and_b32_e32 v17, 0xffff0000, v95
	v_fmac_f32_e32 v16, v18, v126
	v_fmac_f32_e32 v17, v19, v127
	v_cvt_pk_bf16_f32 v27, v16, v17
	v_lshlrev_b32_e32 v16, 16, v96
	v_and_b32_e32 v17, 0xffff0000, v96
	v_fmac_f32_e32 v16, v20, v136
	v_fmac_f32_e32 v17, v21, v137
	flat_store_dwordx4 v[28:29], v[24:27] offset:256
	v_cvt_pk_bf16_f32 v16, v16, v17
	v_lshlrev_b32_e32 v17, 16, v97
	v_and_b32_e32 v18, 0xffff0000, v97
	v_fmac_f32_e32 v17, v22, v138
	v_fmac_f32_e32 v18, v23, v139
	v_cvt_pk_bf16_f32 v17, v17, v18
	v_lshlrev_b32_e32 v18, 16, v98
	v_fmac_f32_e32 v18, v12, v132
	v_and_b32_e32 v12, 0xffff0000, v98
	v_fmac_f32_e32 v12, v13, v133
	v_cvt_pk_bf16_f32 v18, v18, v12
	v_lshlrev_b32_e32 v12, 16, v99
	v_fmac_f32_e32 v12, v14, v134
	v_lshlrev_b32_e32 v14, 16, v68
	v_and_b32_e32 v13, 0xffff0000, v99
	v_fmac_f32_e32 v14, v8, v128
	v_and_b32_e32 v8, 0xffff0000, v68
	v_fmac_f32_e32 v13, v15, v135
	v_fmac_f32_e32 v8, v9, v129
	v_lshlrev_b32_e32 v9, 16, v69
	v_cvt_pk_bf16_f32 v19, v12, v13
	v_lshl_add_u64 v[12:13], s[14:15], 0, v[106:107]
	v_fmac_f32_e32 v9, v10, v130
	v_and_b32_e32 v10, 0xffff0000, v69
	v_lshl_add_u64 v[12:13], v[12:13], 0, v[186:187]
	v_fmac_f32_e32 v10, v11, v131
	flat_store_dwordx4 v[12:13], v[16:19]
	v_cvt_pk_bf16_f32 v8, v14, v8
	v_cvt_pk_bf16_f32 v9, v9, v10
	v_lshlrev_b32_e32 v10, 16, v70
	v_fmac_f32_e32 v10, v4, v124
	v_and_b32_e32 v4, 0xffff0000, v70
	v_fmac_f32_e32 v4, v5, v125
	v_cvt_pk_bf16_f32 v10, v10, v4
	v_lshlrev_b32_e32 v4, 16, v71
	v_and_b32_e32 v5, 0xffff0000, v71
	v_fmac_f32_e32 v4, v6, v126
	v_fmac_f32_e32 v5, v7, v127
	v_cvt_pk_bf16_f32 v11, v4, v5
	flat_store_dwordx4 v[12:13], v[8:11] offset:256
	s_cbranch_vccz .LBB0_2227
	s_waitcnt vmcnt(0)
	s_cmpk_gt_u32 s7, 0xff
	s_cbranch_scc1 .LBB0_2242
	s_barrier
